# v20 + first K-iteration of every GEMM tile peeled: first MFMA per accumulator takes C=0, the 128 zeroing v_mov per tile removed
# baseline (speedup 1.0000x reference)
; #define PG8_STAGE(bufoff, gbase, voff) do { _Pragma("unroll") for (int _i = 0; _i < 2; ++_i) \
;         __builtin_amdgcn_global_load_lds((const unsigned*)((const char*)(gbase) + (voff)[_i]), (PG8_LAS unsigned*)(lds + (bufoff) + ldsw + _i * 8192), 16, 0, 0); } while (0)
; #define PG8_LDA(dst, b, h) do { _Pragma("unroll") for (int m = 0; m < 4; ++m) _Pragma("unroll") for (int k = 0; k < 2; ++k) dst[m][k] = *(const PG8_LAS bf16x8*)(lds + PG8_SA(b, h) + aoff + m * 2048 + k * 1024); } while (0)
; #define PG8_LDB(dst, b, h) do { _Pragma("unroll") for (int n = 0; n < 2; ++n) _Pragma("unroll") for (int k = 0; k < 2; ++k) dst[n][k] = *(const PG8_LAS bf16x8*)(lds + PG8_SB(b, h) + boff + n * 2048 + k * 1024); } while (0)
; #define PG8_MMA(ai, bj, At, Bt) do { __builtin_amdgcn_s_setprio(1); _Pragma("unroll") for (int m = 0; m < 4; ++m) _Pragma("unroll") for (int n = 0; n < 2; ++n) _Pragma("unroll") for (int k = 0; k < 2; ++k) \
;         acc[ai][bj][m][n] = mma16(Bt[n][k], At[m][k], acc[ai][bj][m][n]); __builtin_amdgcn_s_setprio(0); } while (0)
; template <class Epi, class Sched, bool ALIGN_EPI = false, bool SP2 = false>
; __device__ __forceinline__ void gemm_phase(PG8_LAS unsigned char* lds, const Gemm g, const Sched& S, const Epi& E) {
;     ...
;         const bool has_next = S.next(ui + 1, nxt);
;         const char* nA = has_next ? PG8_ABASE(nxt) : cA; const char* nB = has_next ? PG8_BBASE(nxt) : cB;
; #pragma unroll 1
;         for (int t = 0; t < nt; t += 2) {
;             const bool last = (t == nt - 2);
;             const char* a1 = cA + (size_t)(t + 1) * kstep;
;             const char* a2 = last ? nA : cA + (size_t)(t + 2) * kstep; const char* b2 = last ? nB : cB + (size_t)(t + 2) * kstep;
;             const char* a3 = a2 + kstep; const char* b3 = b2 + kstep;
;             if (last && has_next) S.a_ready(nxt);
;             if constexpr (SP2) {
;             PG8_LDB(B0, 0, 0); PG8_LDB(B1, 0, 1); PG8_SCHED; PG8_LDA(At, 0, 0); PG8_STAGE(PG8_SA(1, 1), a1 + hstepA, voffA);
;             PG8_WAIT_V(8); PG8_WAIT_L(0); PG8_BAR; PG8_MMA(0, 0, At, B0); PG8_MMA(0, 1, At, B1); PG8_BAR; PG8_SCHED;
;             PG8_LDA(At, 0, 1); PG8_STAGE(PG8_SB(0, 0), b2, voffB); PG8_STAGE(PG8_SB(0, 1), b2 + hstepB, voffB); PG8_STAGE(PG8_SA(0, 0), a2, voffA);
;             PG8_WAIT_V(8); PG8_WAIT_L(0); PG8_BAR; PG8_MMA(1, 0, At, B0); PG8_MMA(1, 1, At, B1); PG8_BAR; PG8_SCHED;
.LBB0_230:
	s_ashr_i32 s45, s44, 31
	s_lshl_b64 s[36:37], s[44:45], 21
	s_add_u32 s58, s8, s36
	s_addc_u32 s59, s11, s37
	s_and_b64 s[0:1], s[0:1], exec
	s_cselect_b32 s29, s59, s65
	s_cselect_b32 s33, s58, s64
	s_add_u32 s0, s66, 0x100080
	s_addc_u32 s1, s67, 0
	s_add_u32 s35, s64, 0x100
	s_addc_u32 s36, s65, 0
	s_mov_b32 s37, -2
	ds_read_b128 v[146:149], v158
	ds_read_b128 v[162:165], v158 offset:1024
	ds_read_b128 v[182:185], v158 offset:2048
	ds_read_b128 v[186:189], v158 offset:3072
	ds_read_b128 v[190:193], v159
	ds_read_b128 v[194:197], v159 offset:1024
	ds_read_b128 v[198:201], v159 offset:2048
	ds_read_b128 v[202:205], v159 offset:3072
	s_add_u32 s45, s0, 0xfff00080
	s_addc_u32 s46, s1, -1
	s_cmp_eq_u32 s37, 60
	s_cselect_b32 s67, s55, s46
	s_cselect_b32 s66, s54, s45
	s_cselect_b32 s65, s29, s36
	s_cselect_b32 s64, s33, s35
	v_lshl_add_u64 v[166:167], s[0:1], 0, v[138:139]
	s_add_i32 m0, s13, 0xc000
	ds_read_b128 v[206:209], v160
	ds_read_b128 v[212:215], v160 offset:1024
	ds_read_b128 v[216:219], v160 offset:2048
	ds_read_b128 v[220:223], v160 offset:3072
	ds_read_b128 v[224:227], v160 offset:4096
	ds_read_b128 v[228:231], v160 offset:5120
	ds_read_b128 v[232:235], v160 offset:6144
	ds_read_b128 v[236:239], v160 offset:7168
	global_load_lds_dwordx4 v[166:167], off
	v_lshl_add_u64 v[166:167], s[0:1], 0, v[140:141]
	s_add_i32 m0, s13, 0xe000
	s_nop 0
	global_load_lds_dwordx4 v[166:167], off
	s_waitcnt vmcnt(8)
	s_waitcnt lgkmcnt(0)
	s_barrier
	s_setprio 1
	s_waitcnt lgkmcnt(0)
	v_mfma_f32_16x16x32_bf16 v[126:129], v[146:149], v[206:209], 0
	v_mfma_f32_16x16x32_bf16 v[126:129], v[162:165], v[212:215], v[126:129]
	v_mfma_f32_16x16x32_bf16 v[122:125], v[186:189], v[212:215], 0
	v_mfma_f32_16x16x32_bf16 v[122:125], v[182:185], v[206:209], v[122:125]
	v_mfma_f32_16x16x32_bf16 v[110:113], v[182:185], v[216:219], 0
	v_mfma_f32_16x16x32_bf16 v[110:113], v[186:189], v[220:223], v[110:113]
	v_mfma_f32_16x16x32_bf16 v[118:121], v[162:165], v[220:223], 0
	v_mfma_f32_16x16x32_bf16 v[118:121], v[146:149], v[216:219], v[118:121]
	v_mfma_f32_16x16x32_bf16 v[102:105], v[146:149], v[224:227], 0
	v_mfma_f32_16x16x32_bf16 v[102:105], v[162:165], v[228:231], v[102:105]
	v_mfma_f32_16x16x32_bf16 v[94:97], v[186:189], v[228:231], 0
	v_mfma_f32_16x16x32_bf16 v[94:97], v[182:185], v[224:227], v[94:97]
	v_mfma_f32_16x16x32_bf16 v[78:81], v[182:185], v[232:235], 0
	v_mfma_f32_16x16x32_bf16 v[78:81], v[186:189], v[236:239], v[78:81]
	v_mfma_f32_16x16x32_bf16 v[86:89], v[162:165], v[236:239], 0
	v_mfma_f32_16x16x32_bf16 v[86:89], v[146:149], v[232:235], v[86:89]
	s_setprio 0
	s_setprio 1
	v_mfma_f32_16x16x32_bf16 v[114:117], v[190:193], v[206:209], 0
	v_mfma_f32_16x16x32_bf16 v[114:117], v[194:197], v[212:215], v[114:117]
	v_mfma_f32_16x16x32_bf16 v[106:109], v[202:205], v[212:215], 0
	v_mfma_f32_16x16x32_bf16 v[106:109], v[198:201], v[206:209], v[106:109]
	v_mfma_f32_16x16x32_bf16 v[90:93], v[198:201], v[216:219], 0
	v_mfma_f32_16x16x32_bf16 v[90:93], v[202:205], v[220:223], v[90:93]
	v_mfma_f32_16x16x32_bf16 v[98:101], v[194:197], v[220:223], 0
	v_mfma_f32_16x16x32_bf16 v[98:101], v[190:193], v[216:219], v[98:101]
	v_mfma_f32_16x16x32_bf16 v[82:85], v[190:193], v[224:227], 0
	v_mfma_f32_16x16x32_bf16 v[82:85], v[194:197], v[228:231], v[82:85]
	v_mfma_f32_16x16x32_bf16 v[74:77], v[202:205], v[228:231], 0
	v_mfma_f32_16x16x32_bf16 v[74:77], v[198:201], v[224:227], v[74:77]
	v_mfma_f32_16x16x32_bf16 v[66:69], v[198:201], v[232:235], 0
	v_mfma_f32_16x16x32_bf16 v[66:69], v[202:205], v[236:239], v[66:69]
	v_mfma_f32_16x16x32_bf16 v[70:73], v[194:197], v[236:239], 0
	v_mfma_f32_16x16x32_bf16 v[70:73], v[190:193], v[232:235], v[70:73]
	s_setprio 0
	s_barrier
	s_add_i32 s45, s26, s12
	v_lshl_add_u64 v[166:167], s[64:65], 0, v[132:133]
	s_mov_b32 m0, s45
	ds_read_b128 v[206:209], v160 offset:16384
	ds_read_b128 v[212:215], v160 offset:17408
	ds_read_b128 v[216:219], v160 offset:18432
	ds_read_b128 v[220:223], v160 offset:19456
	ds_read_b128 v[224:227], v160 offset:20480
	ds_read_b128 v[228:231], v160 offset:21504
	ds_read_b128 v[232:235], v160 offset:22528
	ds_read_b128 v[236:239], v160 offset:23552
	global_load_lds_dwordx4 v[166:167], off
	s_add_i32 m0, s45, 0x2000
	s_add_u32 s46, s64, 0x100000
	v_lshl_add_u64 v[176:177], s[64:65], 0, v[136:137]
	s_addc_u32 s47, s65, 0
	s_add_i32 s45, s27, s12
	global_load_lds_dwordx4 v[176:177], off
	v_lshl_add_u64 v[240:241], s[46:47], 0, v[132:133]
	s_mov_b32 m0, s45
	v_lshl_add_u64 v[242:243], s[66:67], 0, v[134:135]
	global_load_lds_dwordx4 v[240:241], off
	v_lshl_add_u64 v[240:241], s[46:47], 0, v[136:137]
	s_add_i32 m0, s45, 0x2000
	s_nop 0
	global_load_lds_dwordx4 v[240:241], off
	v_lshl_add_u64 v[240:241], s[66:67], 0, v[130:131]
	s_mov_b32 m0, s13
	s_nop 0
	global_load_lds_dwordx4 v[240:241], off
	s_mov_b32 m0, s18
	s_nop 0
	global_load_lds_dwordx4 v[242:243], off
	s_waitcnt vmcnt(8)
	s_waitcnt lgkmcnt(0)
	s_barrier
; #define PG8_STAGE(bufoff, gbase, voff) do { _Pragma("unroll") for (int _i = 0; _i < 2; ++_i) \
;         __builtin_amdgcn_global_load_lds((const unsigned*)((const char*)(gbase) + (voff)[_i]), (PG8_LAS unsigned*)(lds + (bufoff) + ldsw + _i * 8192), 16, 0, 0); } while (0)
; #define PG8_LDA(dst, b, h) do { _Pragma("unroll") for (int m = 0; m < 4; ++m) _Pragma("unroll") for (int k = 0; k < 2; ++k) dst[m][k] = *(const PG8_LAS bf16x8*)(lds + PG8_SA(b, h) + aoff + m * 2048 + k * 1024); } while (0)
; #define PG8_LDB(dst, b, h) do { _Pragma("unroll") for (int n = 0; n < 2; ++n) _Pragma("unroll") for (int k = 0; k < 2; ++k) dst[n][k] = *(const PG8_LAS bf16x8*)(lds + PG8_SB(b, h) + boff + n * 2048 + k * 1024); } while (0)
; #define PG8_MMA(ai, bj, At, Bt) do { __builtin_amdgcn_s_setprio(1); _Pragma("unroll") for (int m = 0; m < 4; ++m) _Pragma("unroll") for (int n = 0; n < 2; ++n) _Pragma("unroll") for (int k = 0; k < 2; ++k) \
;         acc[ai][bj][m][n] = mma16(Bt[n][k], At[m][k], acc[ai][bj][m][n]); __builtin_amdgcn_s_setprio(0); } while (0)
; #define PG8_WAIT_V(n) asm volatile("s_waitcnt vmcnt(" #n ")" ::: "memory")
; #define PG8_WAIT_L(n) asm volatile("s_waitcnt lgkmcnt(" #n ")" ::: "memory")
; #define PG8_BAR __builtin_amdgcn_s_barrier()
; #define PG8_SCHED __builtin_amdgcn_sched_barrier(0)
; template <class Epi, class Sched, bool ALIGN_EPI = false, bool SP2 = false>
; __device__ __forceinline__ void gemm_phase(PG8_LAS unsigned char* lds, const Gemm g, const Sched& S, const Epi& E) {
;     ...
;             PG8_WAIT_V(8); PG8_WAIT_L(0); PG8_BAR; PG8_MMA(1, 0, At, B0); PG8_MMA(1, 1, At, B1); PG8_BAR; PG8_SCHED;
;             PG8_LDB(B0, 1, 0); PG8_LDB(B1, 1, 1); PG8_SCHED; PG8_LDA(At, 1, 0); PG8_STAGE(PG8_SA(0, 1), a2 + hstepA, voffA);
;             PG8_WAIT_V(8); PG8_WAIT_L(0); PG8_BAR; PG8_MMA(0, 0, At, B0); PG8_MMA(0, 1, At, B1); PG8_BAR; PG8_SCHED;
	s_setprio 1
	s_waitcnt lgkmcnt(0)
	v_mfma_f32_16x16x32_bf16 v[62:65], v[146:149], v[206:209], 0
	v_mfma_f32_16x16x32_bf16 v[62:65], v[162:165], v[212:215], v[62:65]
	v_mfma_f32_16x16x32_bf16 v[58:61], v[186:189], v[212:215], 0
	v_mfma_f32_16x16x32_bf16 v[58:61], v[182:185], v[206:209], v[58:61]
	v_mfma_f32_16x16x32_bf16 v[46:49], v[182:185], v[216:219], 0
	v_mfma_f32_16x16x32_bf16 v[46:49], v[186:189], v[220:223], v[46:49]
	v_mfma_f32_16x16x32_bf16 v[54:57], v[162:165], v[220:223], 0
	v_mfma_f32_16x16x32_bf16 v[54:57], v[146:149], v[216:219], v[54:57]
	v_mfma_f32_16x16x32_bf16 v[38:41], v[146:149], v[224:227], 0
	v_mfma_f32_16x16x32_bf16 v[38:41], v[162:165], v[228:231], v[38:41]
	v_mfma_f32_16x16x32_bf16 v[30:33], v[186:189], v[228:231], 0
	v_mfma_f32_16x16x32_bf16 v[30:33], v[182:185], v[224:227], v[30:33]
	v_mfma_f32_16x16x32_bf16 v[14:17], v[182:185], v[232:235], 0
	v_mfma_f32_16x16x32_bf16 v[14:17], v[186:189], v[236:239], v[14:17]
	v_mfma_f32_16x16x32_bf16 v[22:25], v[162:165], v[236:239], 0
	v_mfma_f32_16x16x32_bf16 v[22:25], v[146:149], v[232:235], v[22:25]
	s_setprio 0
	s_setprio 1
	v_mfma_f32_16x16x32_bf16 v[50:53], v[190:193], v[206:209], 0
	v_mfma_f32_16x16x32_bf16 v[50:53], v[194:197], v[212:215], v[50:53]
	v_mfma_f32_16x16x32_bf16 v[42:45], v[202:205], v[212:215], 0
	v_mfma_f32_16x16x32_bf16 v[42:45], v[198:201], v[206:209], v[42:45]
	v_mfma_f32_16x16x32_bf16 v[26:29], v[198:201], v[216:219], 0
	v_mfma_f32_16x16x32_bf16 v[26:29], v[202:205], v[220:223], v[26:29]
	v_mfma_f32_16x16x32_bf16 v[34:37], v[194:197], v[220:223], 0
	v_mfma_f32_16x16x32_bf16 v[34:37], v[190:193], v[216:219], v[34:37]
	v_mfma_f32_16x16x32_bf16 v[18:21], v[190:193], v[224:227], 0
	v_mfma_f32_16x16x32_bf16 v[18:21], v[194:197], v[228:231], v[18:21]
	v_mfma_f32_16x16x32_bf16 v[10:13], v[202:205], v[228:231], 0
	v_mfma_f32_16x16x32_bf16 v[10:13], v[198:201], v[224:227], v[10:13]
	v_mfma_f32_16x16x32_bf16 v[2:5], v[198:201], v[232:235], 0
	v_mfma_f32_16x16x32_bf16 v[2:5], v[202:205], v[236:239], v[2:5]
	v_mfma_f32_16x16x32_bf16 v[6:9], v[194:197], v[236:239], 0
	v_mfma_f32_16x16x32_bf16 v[6:9], v[190:193], v[232:235], v[6:9]
	s_setprio 0
	s_barrier
	s_add_i32 s45, 0, 0x18000
	v_add_u32_e32 v161, s45, v156
	s_add_i32 s49, 0, 0x1c000
	ds_read_b128 v[146:149], v161
	ds_read_b128 v[162:165], v161 offset:1024
	ds_read_b128 v[182:185], v161 offset:2048
	ds_read_b128 v[186:189], v161 offset:3072
	v_add_u32_e32 v161, s49, v156
	ds_read_b128 v[190:193], v161
	ds_read_b128 v[194:197], v161 offset:1024
	ds_read_b128 v[198:201], v161 offset:2048
	ds_read_b128 v[202:205], v161 offset:3072
	s_add_u32 s46, s66, 0x100000
	s_addc_u32 s47, s67, 0
	s_mov_b32 m0, s19
	v_lshl_add_u64 v[244:245], s[46:47], 0, v[130:131]
	ds_read_b128 v[206:209], v160 offset:32768
	ds_read_b128 v[212:215], v160 offset:33792
	ds_read_b128 v[216:219], v160 offset:34816
	ds_read_b128 v[220:223], v160 offset:35840
	ds_read_b128 v[224:227], v160 offset:36864
	ds_read_b128 v[228:231], v160 offset:37888
	ds_read_b128 v[232:235], v160 offset:38912
	ds_read_b128 v[236:239], v160 offset:39936
	global_load_lds_dwordx4 v[244:245], off
	v_lshl_add_u64 v[244:245], s[46:47], 0, v[134:135]
	s_mov_b32 m0, s20
	s_nop 0
	global_load_lds_dwordx4 v[244:245], off
	s_waitcnt vmcnt(8)
	s_waitcnt lgkmcnt(0)
	s_barrier
	s_setprio 1
	s_waitcnt lgkmcnt(0)
	v_mfma_f32_16x16x32_bf16 v[126:129], v[146:149], v[206:209], v[126:129]
	v_mfma_f32_16x16x32_bf16 v[126:129], v[162:165], v[212:215], v[126:129]
	v_mfma_f32_16x16x32_bf16 v[122:125], v[186:189], v[212:215], v[122:125]
	v_mfma_f32_16x16x32_bf16 v[122:125], v[182:185], v[206:209], v[122:125]
	v_mfma_f32_16x16x32_bf16 v[110:113], v[182:185], v[216:219], v[110:113]
	v_mfma_f32_16x16x32_bf16 v[110:113], v[186:189], v[220:223], v[110:113]
	v_mfma_f32_16x16x32_bf16 v[118:121], v[162:165], v[220:223], v[118:121]
	v_mfma_f32_16x16x32_bf16 v[118:121], v[146:149], v[216:219], v[118:121]
	v_mfma_f32_16x16x32_bf16 v[102:105], v[146:149], v[224:227], v[102:105]
	v_mfma_f32_16x16x32_bf16 v[102:105], v[162:165], v[228:231], v[102:105]
	v_mfma_f32_16x16x32_bf16 v[94:97], v[186:189], v[228:231], v[94:97]
	v_mfma_f32_16x16x32_bf16 v[94:97], v[182:185], v[224:227], v[94:97]
	v_mfma_f32_16x16x32_bf16 v[78:81], v[182:185], v[232:235], v[78:81]
	v_mfma_f32_16x16x32_bf16 v[78:81], v[186:189], v[236:239], v[78:81]
	v_mfma_f32_16x16x32_bf16 v[86:89], v[162:165], v[236:239], v[86:89]
	v_mfma_f32_16x16x32_bf16 v[86:89], v[146:149], v[232:235], v[86:89]
	s_setprio 0
	s_setprio 1
	v_mfma_f32_16x16x32_bf16 v[114:117], v[190:193], v[206:209], v[114:117]
	v_mfma_f32_16x16x32_bf16 v[114:117], v[194:197], v[212:215], v[114:117]
	v_mfma_f32_16x16x32_bf16 v[106:109], v[202:205], v[212:215], v[106:109]
	v_mfma_f32_16x16x32_bf16 v[106:109], v[198:201], v[206:209], v[106:109]
	v_mfma_f32_16x16x32_bf16 v[90:93], v[198:201], v[216:219], v[90:93]
	v_mfma_f32_16x16x32_bf16 v[90:93], v[202:205], v[220:223], v[90:93]
	v_mfma_f32_16x16x32_bf16 v[98:101], v[194:197], v[220:223], v[98:101]
	v_mfma_f32_16x16x32_bf16 v[98:101], v[190:193], v[216:219], v[98:101]
	v_mfma_f32_16x16x32_bf16 v[82:85], v[190:193], v[224:227], v[82:85]
	v_mfma_f32_16x16x32_bf16 v[82:85], v[194:197], v[228:231], v[82:85]
	v_mfma_f32_16x16x32_bf16 v[74:77], v[202:205], v[228:231], v[74:77]
	v_mfma_f32_16x16x32_bf16 v[74:77], v[198:201], v[224:227], v[74:77]
	v_mfma_f32_16x16x32_bf16 v[66:69], v[198:201], v[232:235], v[66:69]
	v_mfma_f32_16x16x32_bf16 v[66:69], v[202:205], v[236:239], v[66:69]
	v_mfma_f32_16x16x32_bf16 v[70:73], v[194:197], v[236:239], v[70:73]
	v_mfma_f32_16x16x32_bf16 v[70:73], v[190:193], v[232:235], v[70:73]
	s_setprio 0
	s_barrier
; #define PG8_STAGE(bufoff, gbase, voff) do { _Pragma("unroll") for (int _i = 0; _i < 2; ++_i) \
;         __builtin_amdgcn_global_load_lds((const unsigned*)((const char*)(gbase) + (voff)[_i]), (PG8_LAS unsigned*)(lds + (bufoff) + ldsw + _i * 8192), 16, 0, 0); } while (0)
; #define PG8_LDA(dst, b, h) do { _Pragma("unroll") for (int m = 0; m < 4; ++m) _Pragma("unroll") for (int k = 0; k < 2; ++k) dst[m][k] = *(const PG8_LAS bf16x8*)(lds + PG8_SA(b, h) + aoff + m * 2048 + k * 1024); } while (0)
; #define PG8_MMA(ai, bj, At, Bt) do { __builtin_amdgcn_s_setprio(1); _Pragma("unroll") for (int m = 0; m < 4; ++m) _Pragma("unroll") for (int n = 0; n < 2; ++n) _Pragma("unroll") for (int k = 0; k < 2; ++k) \
;         acc[ai][bj][m][n] = mma16(Bt[n][k], At[m][k], acc[ai][bj][m][n]); __builtin_amdgcn_s_setprio(0); } while (0)
; #define PG8_WAIT_V(n) asm volatile("s_waitcnt vmcnt(" #n ")" ::: "memory")
; #define PG8_WAIT_L(n) asm volatile("s_waitcnt lgkmcnt(" #n ")" ::: "memory")
; #define PG8_BAR __builtin_amdgcn_s_barrier()
; #define PG8_SCHED __builtin_amdgcn_sched_barrier(0)
; template <class Epi, class Sched, bool ALIGN_EPI = false, bool SP2 = false>
; __device__ __forceinline__ void gemm_phase(PG8_LAS unsigned char* lds, const Gemm g, const Sched& S, const Epi& E) {
;     ...
;             PG8_LDA(At, 1, 1); PG8_STAGE(PG8_SB(1, 0), b3, voffB); PG8_STAGE(PG8_SB(1, 1), b3 + hstepB, voffB); PG8_STAGE(PG8_SA(1, 0), a3, voffA);
;             PG8_WAIT_V(8); PG8_WAIT_L(0); PG8_BAR; PG8_MMA(1, 0, At, B0); PG8_MMA(1, 1, At, B1); PG8_BAR; PG8_SCHED;
	s_add_i32 s45, s45, s12
	v_lshl_add_u64 v[166:167], v[166:167], 0, s[40:41]
	s_mov_b32 m0, s45
	ds_read_b128 v[206:209], v160 offset:49152
	ds_read_b128 v[212:215], v160 offset:50176
	ds_read_b128 v[216:219], v160 offset:51200
	ds_read_b128 v[220:223], v160 offset:52224
	ds_read_b128 v[224:227], v160 offset:53248
	ds_read_b128 v[228:231], v160 offset:54272
	ds_read_b128 v[232:235], v160 offset:55296
	ds_read_b128 v[236:239], v160 offset:56320
	global_load_lds_dwordx4 v[166:167], off
	s_add_i32 m0, s45, 0x2000
	s_add_u32 s46, s64, 0x100080
	v_lshl_add_u64 v[166:167], v[176:177], 0, s[40:41]
	s_addc_u32 s47, s65, 0
	s_add_i32 s45, s49, s12
	global_load_lds_dwordx4 v[166:167], off
	v_lshl_add_u64 v[166:167], s[46:47], 0, v[132:133]
	s_mov_b32 m0, s45
	s_nop 0
	global_load_lds_dwordx4 v[166:167], off
	v_lshl_add_u64 v[166:167], s[46:47], 0, v[136:137]
	s_add_i32 m0, s45, 0x2000
	s_nop 0
	global_load_lds_dwordx4 v[166:167], off
	v_lshl_add_u64 v[166:167], v[240:241], 0, s[40:41]
	s_mov_b32 m0, s22
	s_nop 0
	global_load_lds_dwordx4 v[166:167], off
	v_lshl_add_u64 v[166:167], v[242:243], 0, s[40:41]
	s_mov_b32 m0, s23
	s_nop 0
	global_load_lds_dwordx4 v[166:167], off
	s_waitcnt vmcnt(8)
	s_waitcnt lgkmcnt(0)
	s_barrier
	s_setprio 1
	s_waitcnt lgkmcnt(0)
	v_mfma_f32_16x16x32_bf16 v[62:65], v[146:149], v[206:209], v[62:65]
	v_mfma_f32_16x16x32_bf16 v[62:65], v[162:165], v[212:215], v[62:65]
	v_mfma_f32_16x16x32_bf16 v[58:61], v[186:189], v[212:215], v[58:61]
	v_mfma_f32_16x16x32_bf16 v[58:61], v[182:185], v[206:209], v[58:61]
	v_mfma_f32_16x16x32_bf16 v[46:49], v[182:185], v[216:219], v[46:49]
	v_mfma_f32_16x16x32_bf16 v[46:49], v[186:189], v[220:223], v[46:49]
	v_mfma_f32_16x16x32_bf16 v[54:57], v[162:165], v[220:223], v[54:57]
	v_mfma_f32_16x16x32_bf16 v[54:57], v[146:149], v[216:219], v[54:57]
	v_mfma_f32_16x16x32_bf16 v[38:41], v[146:149], v[224:227], v[38:41]
	v_mfma_f32_16x16x32_bf16 v[38:41], v[162:165], v[228:231], v[38:41]
	v_mfma_f32_16x16x32_bf16 v[30:33], v[186:189], v[228:231], v[30:33]
	v_mfma_f32_16x16x32_bf16 v[30:33], v[182:185], v[224:227], v[30:33]
	v_mfma_f32_16x16x32_bf16 v[14:17], v[182:185], v[232:235], v[14:17]
	v_mfma_f32_16x16x32_bf16 v[14:17], v[186:189], v[236:239], v[14:17]
	v_mfma_f32_16x16x32_bf16 v[22:25], v[162:165], v[236:239], v[22:25]
	v_mfma_f32_16x16x32_bf16 v[22:25], v[146:149], v[232:235], v[22:25]
	s_setprio 0
	s_setprio 1
	v_mfma_f32_16x16x32_bf16 v[50:53], v[190:193], v[206:209], v[50:53]
	v_mfma_f32_16x16x32_bf16 v[50:53], v[194:197], v[212:215], v[50:53]
	v_mfma_f32_16x16x32_bf16 v[42:45], v[202:205], v[212:215], v[42:45]
	v_mfma_f32_16x16x32_bf16 v[42:45], v[198:201], v[206:209], v[42:45]
	v_mfma_f32_16x16x32_bf16 v[26:29], v[198:201], v[216:219], v[26:29]
	v_mfma_f32_16x16x32_bf16 v[26:29], v[202:205], v[220:223], v[26:29]
	v_mfma_f32_16x16x32_bf16 v[34:37], v[194:197], v[220:223], v[34:37]
	v_mfma_f32_16x16x32_bf16 v[34:37], v[190:193], v[216:219], v[34:37]
	v_mfma_f32_16x16x32_bf16 v[18:21], v[190:193], v[224:227], v[18:21]
	v_mfma_f32_16x16x32_bf16 v[18:21], v[194:197], v[228:231], v[18:21]
	v_mfma_f32_16x16x32_bf16 v[10:13], v[202:205], v[228:231], v[10:13]
	v_mfma_f32_16x16x32_bf16 v[10:13], v[198:201], v[224:227], v[10:13]
	v_mfma_f32_16x16x32_bf16 v[2:5], v[198:201], v[232:235], v[2:5]
	v_mfma_f32_16x16x32_bf16 v[2:5], v[202:205], v[236:239], v[2:5]
	v_mfma_f32_16x16x32_bf16 v[6:9], v[194:197], v[236:239], v[6:9]
	v_mfma_f32_16x16x32_bf16 v[6:9], v[190:193], v[232:235], v[6:9]
	s_setprio 0
	s_barrier
	s_add_i32 s37, s37, 2
	s_add_u32 s0, s0, 0x100
	s_addc_u32 s1, s1, 0
	s_add_u32 s35, s35, 0x100
	s_addc_u32 s36, s36, 0

; #define PG8_STAGE(bufoff, gbase, voff) do { _Pragma("unroll") for (int _i = 0; _i < 2; ++_i) \
;         __builtin_amdgcn_global_load_lds((const unsigned*)((const char*)(gbase) + (voff)[_i]), (PG8_LAS unsigned*)(lds + (bufoff) + ldsw + _i * 8192), 16, 0, 0); } while (0)
; #define PG8_LDA(dst, b, h) do { _Pragma("unroll") for (int m = 0; m < 4; ++m) _Pragma("unroll") for (int k = 0; k < 2; ++k) dst[m][k] = *(const PG8_LAS bf16x8*)(lds + PG8_SA(b, h) + aoff + m * 2048 + k * 1024); } while (0)
; #define PG8_LDB(dst, b, h) do { _Pragma("unroll") for (int n = 0; n < 2; ++n) _Pragma("unroll") for (int k = 0; k < 2; ++k) dst[n][k] = *(const PG8_LAS bf16x8*)(lds + PG8_SB(b, h) + boff + n * 2048 + k * 1024); } while (0)
; #define PG8_MMA(ai, bj, At, Bt) do { __builtin_amdgcn_s_setprio(1); _Pragma("unroll") for (int m = 0; m < 4; ++m) _Pragma("unroll") for (int n = 0; n < 2; ++n) _Pragma("unroll") for (int k = 0; k < 2; ++k) \
;         acc[ai][bj][m][n] = mma16(Bt[n][k], At[m][k], acc[ai][bj][m][n]); __builtin_amdgcn_s_setprio(0); } while (0)
; template <class Epi, class Sched, bool ALIGN_EPI = false, bool SP2 = false>
; __device__ __forceinline__ void gemm_phase(PG8_LAS unsigned char* lds, const Gemm g, const Sched& S, const Epi& E) {
;     ...
;         const bool has_next = S.next(ui + 1, nxt);
;         const char* nA = has_next ? PG8_ABASE(nxt) : cA; const char* nB = has_next ? PG8_BBASE(nxt) : cB;
; #pragma unroll 1
;         for (int t = 0; t < nt; t += 2) {
;             const bool last = (t == nt - 2);
;             const char* a1 = cA + (size_t)(t + 1) * kstep;
;             const char* a2 = last ? nA : cA + (size_t)(t + 2) * kstep; const char* b2 = last ? nB : cB + (size_t)(t + 2) * kstep;
;             const char* a3 = a2 + kstep; const char* b3 = b2 + kstep;
;             if (last && has_next) S.a_ready(nxt);
;             if constexpr (SP2) {
;             PG8_LDB(B0, 0, 0); PG8_LDB(B1, 0, 1); PG8_SCHED; PG8_LDA(At, 0, 0); PG8_STAGE(PG8_SA(1, 1), a1 + hstepA, voffA);
;             PG8_WAIT_V(8); PG8_WAIT_L(0); PG8_BAR; PG8_MMA(0, 0, At, B0); PG8_MMA(0, 1, At, B1); PG8_BAR; PG8_SCHED;
;             PG8_LDA(At, 0, 1); PG8_STAGE(PG8_SB(0, 0), b2, voffB); PG8_STAGE(PG8_SB(0, 1), b2 + hstepB, voffB); PG8_STAGE(PG8_SA(0, 0), a2, voffA);
;             PG8_WAIT_V(8); PG8_WAIT_L(0); PG8_BAR; PG8_MMA(1, 0, At, B0); PG8_MMA(1, 1, At, B1); PG8_BAR; PG8_SCHED;
.LBB0_248:
	s_ashr_i32 s59, s58, 31
	s_lshl_b64 s[36:37], s[58:59], 20
	s_add_u32 s66, s74, s36
	s_addc_u32 s67, s75, s37
	s_and_b64 s[0:1], s[0:1], exec
	s_cselect_b32 s36, s67, s95
	s_cselect_b32 s37, s66, s94
	s_add_u32 s0, s96, 0x80080
	s_addc_u32 s1, s97, 0
	s_add_u32 s46, s94, 0x100
	s_addc_u32 s47, s95, 0
	s_mov_b32 s50, -2
	ds_read_b128 v[122:125], v181
	ds_read_b128 v[126:129], v181 offset:1024
	ds_read_b128 v[134:137], v181 offset:2048
	ds_read_b128 v[142:145], v181 offset:3072
	ds_read_b128 v[184:187], v182
	ds_read_b128 v[188:191], v182 offset:1024
	ds_read_b128 v[192:195], v182 offset:2048
	ds_read_b128 v[196:199], v182 offset:3072
	s_add_u32 s51, s0, 0xfff80080
	s_addc_u32 s63, s1, -1
	s_cmp_eq_u32 s50, 28
	s_cselect_b32 s95, s65, s63
	s_cselect_b32 s94, s64, s51
	s_cselect_b32 s91, s36, s47
	s_cselect_b32 s90, s37, s46
	v_lshl_add_u64 v[166:167], s[0:1], 0, v[158:159]
	s_add_i32 m0, s13, 0xc000
	ds_read_b128 v[200:203], v183
	ds_read_b128 v[204:207], v183 offset:1024
	ds_read_b128 v[212:215], v183 offset:2048
	ds_read_b128 v[216:219], v183 offset:3072
	ds_read_b128 v[220:223], v183 offset:4096
	ds_read_b128 v[224:227], v183 offset:5120
	ds_read_b128 v[228:231], v183 offset:6144
	ds_read_b128 v[232:235], v183 offset:7168
	global_load_lds_dwordx4 v[166:167], off
	v_lshl_add_u64 v[166:167], s[0:1], 0, v[160:161]
	s_add_i32 m0, s13, 0xe000
	s_nop 0
	global_load_lds_dwordx4 v[166:167], off
	s_waitcnt vmcnt(8)
	s_waitcnt lgkmcnt(0)
	s_barrier
	s_setprio 1
	s_waitcnt lgkmcnt(0)
	v_mfma_i32_16x16x64_i8 v[138:141], v[122:125], v[200:203], 0
	v_mfma_i32_16x16x64_i8 v[138:141], v[126:129], v[204:207], v[138:141]
	v_mfma_i32_16x16x64_i8 v[130:133], v[142:145], v[204:207], 0
	v_mfma_i32_16x16x64_i8 v[130:133], v[134:137], v[200:203], v[130:133]
	v_mfma_i32_16x16x64_i8 v[106:109], v[134:137], v[212:215], 0
	v_mfma_i32_16x16x64_i8 v[106:109], v[142:145], v[216:219], v[106:109]
	v_mfma_i32_16x16x64_i8 v[110:113], v[126:129], v[216:219], 0
	v_mfma_i32_16x16x64_i8 v[110:113], v[122:125], v[212:215], v[110:113]
	v_mfma_i32_16x16x64_i8 v[94:97], v[122:125], v[220:223], 0
	v_mfma_i32_16x16x64_i8 v[94:97], v[126:129], v[224:227], v[94:97]
	v_mfma_i32_16x16x64_i8 v[90:93], v[142:145], v[224:227], 0
	v_mfma_i32_16x16x64_i8 v[90:93], v[134:137], v[220:223], v[90:93]
	v_mfma_i32_16x16x64_i8 v[74:77], v[134:137], v[228:231], 0
	v_mfma_i32_16x16x64_i8 v[74:77], v[142:145], v[232:235], v[74:77]
	v_mfma_i32_16x16x64_i8 v[78:81], v[126:129], v[232:235], 0
	v_mfma_i32_16x16x64_i8 v[78:81], v[122:125], v[228:231], v[78:81]
	s_setprio 0
	s_setprio 1
	v_mfma_i32_16x16x64_i8 v[118:121], v[184:187], v[200:203], 0
	v_mfma_i32_16x16x64_i8 v[118:121], v[188:191], v[204:207], v[118:121]
	v_mfma_i32_16x16x64_i8 v[114:117], v[196:199], v[204:207], 0
	v_mfma_i32_16x16x64_i8 v[114:117], v[192:195], v[200:203], v[114:117]
	v_mfma_i32_16x16x64_i8 v[98:101], v[192:195], v[212:215], 0
	v_mfma_i32_16x16x64_i8 v[98:101], v[196:199], v[216:219], v[98:101]
	v_mfma_i32_16x16x64_i8 v[102:105], v[188:191], v[216:219], 0
	v_mfma_i32_16x16x64_i8 v[102:105], v[184:187], v[212:215], v[102:105]
	v_mfma_i32_16x16x64_i8 v[86:89], v[184:187], v[220:223], 0
	v_mfma_i32_16x16x64_i8 v[86:89], v[188:191], v[224:227], v[86:89]
	v_mfma_i32_16x16x64_i8 v[82:85], v[196:199], v[224:227], 0
	v_mfma_i32_16x16x64_i8 v[82:85], v[192:195], v[220:223], v[82:85]
	v_mfma_i32_16x16x64_i8 v[66:69], v[192:195], v[228:231], 0
	v_mfma_i32_16x16x64_i8 v[66:69], v[196:199], v[232:235], v[66:69]
	v_mfma_i32_16x16x64_i8 v[70:73], v[188:191], v[232:235], 0
	v_mfma_i32_16x16x64_i8 v[70:73], v[184:187], v[228:231], v[70:73]
	s_setprio 0
	s_barrier
	s_add_i32 s51, s27, s7
	v_lshl_add_u64 v[166:167], s[90:91], 0, v[148:149]
	s_mov_b32 m0, s51
	ds_read_b128 v[200:203], v183 offset:16384
	ds_read_b128 v[204:207], v183 offset:17408
	ds_read_b128 v[212:215], v183 offset:18432
	ds_read_b128 v[216:219], v183 offset:19456
	ds_read_b128 v[220:223], v183 offset:20480
	ds_read_b128 v[224:227], v183 offset:21504
	ds_read_b128 v[228:231], v183 offset:22528
	ds_read_b128 v[232:235], v183 offset:23552
	global_load_lds_dwordx4 v[166:167], off
	s_add_i32 m0, s51, 0x2000
	s_add_u32 s68, s90, 0x80000
	v_lshl_add_u64 v[208:209], s[90:91], 0, v[152:153]
	s_addc_u32 s69, s91, 0
	s_add_i32 s51, s28, s7
	global_load_lds_dwordx4 v[208:209], off
	v_lshl_add_u64 v[236:237], s[68:69], 0, v[148:149]
	s_mov_b32 m0, s51
	v_lshl_add_u64 v[238:239], s[94:95], 0, v[150:151]
	global_load_lds_dwordx4 v[236:237], off
	v_lshl_add_u64 v[236:237], s[68:69], 0, v[152:153]
	s_add_i32 m0, s51, 0x2000
	s_nop 0
	global_load_lds_dwordx4 v[236:237], off
	v_lshl_add_u64 v[236:237], s[94:95], 0, v[146:147]
	s_mov_b32 m0, s13
	s_nop 0
	global_load_lds_dwordx4 v[236:237], off
	s_mov_b32 m0, s18
	s_nop 0
	global_load_lds_dwordx4 v[238:239], off
	s_waitcnt vmcnt(8)
	s_waitcnt lgkmcnt(0)
	s_barrier
; #define PG8_STAGE(bufoff, gbase, voff) do { _Pragma("unroll") for (int _i = 0; _i < 2; ++_i) \
;         __builtin_amdgcn_global_load_lds((const unsigned*)((const char*)(gbase) + (voff)[_i]), (PG8_LAS unsigned*)(lds + (bufoff) + ldsw + _i * 8192), 16, 0, 0); } while (0)
; #define PG8_LDA(dst, b, h) do { _Pragma("unroll") for (int m = 0; m < 4; ++m) _Pragma("unroll") for (int k = 0; k < 2; ++k) dst[m][k] = *(const PG8_LAS bf16x8*)(lds + PG8_SA(b, h) + aoff + m * 2048 + k * 1024); } while (0)
; #define PG8_LDB(dst, b, h) do { _Pragma("unroll") for (int n = 0; n < 2; ++n) _Pragma("unroll") for (int k = 0; k < 2; ++k) dst[n][k] = *(const PG8_LAS bf16x8*)(lds + PG8_SB(b, h) + boff + n * 2048 + k * 1024); } while (0)
; #define PG8_MMA(ai, bj, At, Bt) do { __builtin_amdgcn_s_setprio(1); _Pragma("unroll") for (int m = 0; m < 4; ++m) _Pragma("unroll") for (int n = 0; n < 2; ++n) _Pragma("unroll") for (int k = 0; k < 2; ++k) \
;         acc[ai][bj][m][n] = mma16(Bt[n][k], At[m][k], acc[ai][bj][m][n]); __builtin_amdgcn_s_setprio(0); } while (0)
; #define PG8_WAIT_V(n) asm volatile("s_waitcnt vmcnt(" #n ")" ::: "memory")
; #define PG8_WAIT_L(n) asm volatile("s_waitcnt lgkmcnt(" #n ")" ::: "memory")
; #define PG8_BAR __builtin_amdgcn_s_barrier()
; #define PG8_SCHED __builtin_amdgcn_sched_barrier(0)
; template <class Epi, class Sched, bool ALIGN_EPI = false, bool SP2 = false>
; __device__ __forceinline__ void gemm_phase(PG8_LAS unsigned char* lds, const Gemm g, const Sched& S, const Epi& E) {
;     ...
;             PG8_WAIT_V(8); PG8_WAIT_L(0); PG8_BAR; PG8_MMA(1, 0, At, B0); PG8_MMA(1, 1, At, B1); PG8_BAR; PG8_SCHED;
;             PG8_LDB(B0, 1, 0); PG8_LDB(B1, 1, 1); PG8_SCHED; PG8_LDA(At, 1, 0); PG8_STAGE(PG8_SA(0, 1), a2 + hstepA, voffA);
;             PG8_WAIT_V(8); PG8_WAIT_L(0); PG8_BAR; PG8_MMA(0, 0, At, B0); PG8_MMA(0, 1, At, B1); PG8_BAR; PG8_SCHED;
	s_setprio 1
	s_waitcnt lgkmcnt(0)
	v_mfma_i32_16x16x64_i8 v[62:65], v[122:125], v[200:203], 0
	v_mfma_i32_16x16x64_i8 v[62:65], v[126:129], v[204:207], v[62:65]
	v_mfma_i32_16x16x64_i8 v[58:61], v[142:145], v[204:207], 0
	v_mfma_i32_16x16x64_i8 v[58:61], v[134:137], v[200:203], v[58:61]
	v_mfma_i32_16x16x64_i8 v[42:45], v[134:137], v[212:215], 0
	v_mfma_i32_16x16x64_i8 v[42:45], v[142:145], v[216:219], v[42:45]
	v_mfma_i32_16x16x64_i8 v[46:49], v[126:129], v[216:219], 0
	v_mfma_i32_16x16x64_i8 v[46:49], v[122:125], v[212:215], v[46:49]
	v_mfma_i32_16x16x64_i8 v[30:33], v[122:125], v[220:223], 0
	v_mfma_i32_16x16x64_i8 v[30:33], v[126:129], v[224:227], v[30:33]
	v_mfma_i32_16x16x64_i8 v[26:29], v[142:145], v[224:227], 0
	v_mfma_i32_16x16x64_i8 v[26:29], v[134:137], v[220:223], v[26:29]
	v_mfma_i32_16x16x64_i8 v[10:13], v[134:137], v[228:231], 0
	v_mfma_i32_16x16x64_i8 v[10:13], v[142:145], v[232:235], v[10:13]
	v_mfma_i32_16x16x64_i8 v[14:17], v[126:129], v[232:235], 0
	v_mfma_i32_16x16x64_i8 v[14:17], v[122:125], v[228:231], v[14:17]
	s_setprio 0
	s_setprio 1
	v_mfma_i32_16x16x64_i8 v[54:57], v[184:187], v[200:203], 0
	v_mfma_i32_16x16x64_i8 v[54:57], v[188:191], v[204:207], v[54:57]
	v_mfma_i32_16x16x64_i8 v[50:53], v[196:199], v[204:207], 0
	v_mfma_i32_16x16x64_i8 v[50:53], v[192:195], v[200:203], v[50:53]
	v_mfma_i32_16x16x64_i8 v[34:37], v[192:195], v[212:215], 0
	v_mfma_i32_16x16x64_i8 v[34:37], v[196:199], v[216:219], v[34:37]
	v_mfma_i32_16x16x64_i8 v[38:41], v[188:191], v[216:219], 0
	v_mfma_i32_16x16x64_i8 v[38:41], v[184:187], v[212:215], v[38:41]
	v_mfma_i32_16x16x64_i8 v[22:25], v[184:187], v[220:223], 0
	v_mfma_i32_16x16x64_i8 v[22:25], v[188:191], v[224:227], v[22:25]
	v_mfma_i32_16x16x64_i8 v[18:21], v[196:199], v[224:227], 0
	v_mfma_i32_16x16x64_i8 v[18:21], v[192:195], v[220:223], v[18:21]
	v_mfma_i32_16x16x64_i8 v[2:5], v[192:195], v[228:231], 0
	v_mfma_i32_16x16x64_i8 v[2:5], v[196:199], v[232:235], v[2:5]
	v_mfma_i32_16x16x64_i8 v[6:9], v[188:191], v[232:235], 0
	v_mfma_i32_16x16x64_i8 v[6:9], v[184:187], v[228:231], v[6:9]
	s_setprio 0
	s_barrier
	s_add_i32 s51, 0, 0x18000
	s_add_i32 s63, 0, 0x1c000
	v_add_u32_e32 v142, s51, v176
	v_add_u32_e32 v196, s63, v176
	ds_read_b128 v[122:125], v142
	ds_read_b128 v[126:129], v142 offset:1024
	ds_read_b128 v[134:137], v142 offset:2048
	ds_read_b128 v[142:145], v142 offset:3072
	ds_read_b128 v[184:187], v196
	ds_read_b128 v[188:191], v196 offset:1024
	ds_read_b128 v[192:195], v196 offset:2048
	ds_read_b128 v[196:199], v196 offset:3072
	s_add_u32 s68, s94, 0x80000
	s_addc_u32 s69, s95, 0
	s_mov_b32 m0, s19
	v_lshl_add_u64 v[240:241], s[68:69], 0, v[146:147]
	ds_read_b128 v[200:203], v183 offset:32768
	ds_read_b128 v[204:207], v183 offset:33792
	ds_read_b128 v[212:215], v183 offset:34816
	ds_read_b128 v[216:219], v183 offset:35840
	ds_read_b128 v[220:223], v183 offset:36864
	ds_read_b128 v[224:227], v183 offset:37888
	ds_read_b128 v[228:231], v183 offset:38912
	ds_read_b128 v[232:235], v183 offset:39936
	global_load_lds_dwordx4 v[240:241], off
	v_lshl_add_u64 v[240:241], s[68:69], 0, v[150:151]
	s_mov_b32 m0, s20
	s_nop 0
	global_load_lds_dwordx4 v[240:241], off
	s_waitcnt vmcnt(8)
	s_waitcnt lgkmcnt(0)
	s_barrier
	s_setprio 1
	s_waitcnt lgkmcnt(0)
	v_mfma_i32_16x16x64_i8 v[138:141], v[122:125], v[200:203], v[138:141]
	v_mfma_i32_16x16x64_i8 v[138:141], v[126:129], v[204:207], v[138:141]
	v_mfma_i32_16x16x64_i8 v[130:133], v[142:145], v[204:207], v[130:133]
	v_mfma_i32_16x16x64_i8 v[130:133], v[134:137], v[200:203], v[130:133]
	v_mfma_i32_16x16x64_i8 v[106:109], v[134:137], v[212:215], v[106:109]
	v_mfma_i32_16x16x64_i8 v[106:109], v[142:145], v[216:219], v[106:109]
	v_mfma_i32_16x16x64_i8 v[110:113], v[126:129], v[216:219], v[110:113]
	v_mfma_i32_16x16x64_i8 v[110:113], v[122:125], v[212:215], v[110:113]
	v_mfma_i32_16x16x64_i8 v[94:97], v[122:125], v[220:223], v[94:97]
	v_mfma_i32_16x16x64_i8 v[94:97], v[126:129], v[224:227], v[94:97]
	v_mfma_i32_16x16x64_i8 v[90:93], v[142:145], v[224:227], v[90:93]
	v_mfma_i32_16x16x64_i8 v[90:93], v[134:137], v[220:223], v[90:93]
	v_mfma_i32_16x16x64_i8 v[74:77], v[134:137], v[228:231], v[74:77]
	v_mfma_i32_16x16x64_i8 v[74:77], v[142:145], v[232:235], v[74:77]
	v_mfma_i32_16x16x64_i8 v[78:81], v[126:129], v[232:235], v[78:81]
	v_mfma_i32_16x16x64_i8 v[78:81], v[122:125], v[228:231], v[78:81]
	s_setprio 0
	s_setprio 1
	v_mfma_i32_16x16x64_i8 v[118:121], v[184:187], v[200:203], v[118:121]
	v_mfma_i32_16x16x64_i8 v[118:121], v[188:191], v[204:207], v[118:121]
	v_mfma_i32_16x16x64_i8 v[114:117], v[196:199], v[204:207], v[114:117]
	v_mfma_i32_16x16x64_i8 v[114:117], v[192:195], v[200:203], v[114:117]
	v_mfma_i32_16x16x64_i8 v[98:101], v[192:195], v[212:215], v[98:101]
	v_mfma_i32_16x16x64_i8 v[98:101], v[196:199], v[216:219], v[98:101]
	v_mfma_i32_16x16x64_i8 v[102:105], v[188:191], v[216:219], v[102:105]
	v_mfma_i32_16x16x64_i8 v[102:105], v[184:187], v[212:215], v[102:105]
	v_mfma_i32_16x16x64_i8 v[86:89], v[184:187], v[220:223], v[86:89]
	v_mfma_i32_16x16x64_i8 v[86:89], v[188:191], v[224:227], v[86:89]
	v_mfma_i32_16x16x64_i8 v[82:85], v[196:199], v[224:227], v[82:85]
	v_mfma_i32_16x16x64_i8 v[82:85], v[192:195], v[220:223], v[82:85]
	v_mfma_i32_16x16x64_i8 v[66:69], v[192:195], v[228:231], v[66:69]
	v_mfma_i32_16x16x64_i8 v[66:69], v[196:199], v[232:235], v[66:69]
	v_mfma_i32_16x16x64_i8 v[70:73], v[188:191], v[232:235], v[70:73]
	v_mfma_i32_16x16x64_i8 v[70:73], v[184:187], v[228:231], v[70:73]
	s_setprio 0
	s_barrier
; #define PG8_STAGE(bufoff, gbase, voff) do { _Pragma("unroll") for (int _i = 0; _i < 2; ++_i) \
;         __builtin_amdgcn_global_load_lds((const unsigned*)((const char*)(gbase) + (voff)[_i]), (PG8_LAS unsigned*)(lds + (bufoff) + ldsw + _i * 8192), 16, 0, 0); } while (0)
; #define PG8_LDA(dst, b, h) do { _Pragma("unroll") for (int m = 0; m < 4; ++m) _Pragma("unroll") for (int k = 0; k < 2; ++k) dst[m][k] = *(const PG8_LAS bf16x8*)(lds + PG8_SA(b, h) + aoff + m * 2048 + k * 1024); } while (0)
; #define PG8_MMA(ai, bj, At, Bt) do { __builtin_amdgcn_s_setprio(1); _Pragma("unroll") for (int m = 0; m < 4; ++m) _Pragma("unroll") for (int n = 0; n < 2; ++n) _Pragma("unroll") for (int k = 0; k < 2; ++k) \
;         acc[ai][bj][m][n] = mma16(Bt[n][k], At[m][k], acc[ai][bj][m][n]); __builtin_amdgcn_s_setprio(0); } while (0)
; #define PG8_WAIT_V(n) asm volatile("s_waitcnt vmcnt(" #n ")" ::: "memory")
; #define PG8_WAIT_L(n) asm volatile("s_waitcnt lgkmcnt(" #n ")" ::: "memory")
; #define PG8_BAR __builtin_amdgcn_s_barrier()
; #define PG8_SCHED __builtin_amdgcn_sched_barrier(0)
; template <class Epi, class Sched, bool ALIGN_EPI = false, bool SP2 = false>
; __device__ __forceinline__ void gemm_phase(PG8_LAS unsigned char* lds, const Gemm g, const Sched& S, const Epi& E) {
;     ...
;             PG8_LDA(At, 1, 1); PG8_STAGE(PG8_SB(1, 0), b3, voffB); PG8_STAGE(PG8_SB(1, 1), b3 + hstepB, voffB); PG8_STAGE(PG8_SA(1, 0), a3, voffA);
;             PG8_WAIT_V(8); PG8_WAIT_L(0); PG8_BAR; PG8_MMA(1, 0, At, B0); PG8_MMA(1, 1, At, B1); PG8_BAR; PG8_SCHED;
	s_add_i32 s51, s51, s7
	v_lshl_add_u64 v[166:167], v[166:167], 0, s[48:49]
	s_mov_b32 m0, s51
	ds_read_b128 v[200:203], v183 offset:49152
	ds_read_b128 v[204:207], v183 offset:50176
	ds_read_b128 v[212:215], v183 offset:51200
	ds_read_b128 v[216:219], v183 offset:52224
	ds_read_b128 v[220:223], v183 offset:53248
	ds_read_b128 v[224:227], v183 offset:54272
	ds_read_b128 v[228:231], v183 offset:55296
	ds_read_b128 v[232:235], v183 offset:56320
	global_load_lds_dwordx4 v[166:167], off
	s_add_i32 m0, s51, 0x2000
	s_add_u32 s68, s90, 0x80080
	v_lshl_add_u64 v[166:167], v[208:209], 0, s[48:49]
	s_addc_u32 s69, s91, 0
	s_add_i32 s51, s63, s7
	global_load_lds_dwordx4 v[166:167], off
	v_lshl_add_u64 v[166:167], s[68:69], 0, v[148:149]
	s_mov_b32 m0, s51
	s_nop 0
	global_load_lds_dwordx4 v[166:167], off
	v_lshl_add_u64 v[166:167], s[68:69], 0, v[152:153]
	s_add_i32 m0, s51, 0x2000
	s_nop 0
	global_load_lds_dwordx4 v[166:167], off
	v_lshl_add_u64 v[166:167], v[236:237], 0, s[48:49]
	s_mov_b32 m0, s23
	s_nop 0
	global_load_lds_dwordx4 v[166:167], off
	v_lshl_add_u64 v[166:167], v[238:239], 0, s[48:49]
	s_mov_b32 m0, s24
	s_nop 0
	global_load_lds_dwordx4 v[166:167], off
	s_waitcnt vmcnt(8)
	s_waitcnt lgkmcnt(0)
	s_barrier
	s_setprio 1
	s_waitcnt lgkmcnt(0)
	v_mfma_i32_16x16x64_i8 v[62:65], v[122:125], v[200:203], v[62:65]
	v_mfma_i32_16x16x64_i8 v[62:65], v[126:129], v[204:207], v[62:65]
	v_mfma_i32_16x16x64_i8 v[58:61], v[142:145], v[204:207], v[58:61]
	v_mfma_i32_16x16x64_i8 v[58:61], v[134:137], v[200:203], v[58:61]
	v_mfma_i32_16x16x64_i8 v[42:45], v[134:137], v[212:215], v[42:45]
	v_mfma_i32_16x16x64_i8 v[42:45], v[142:145], v[216:219], v[42:45]
	v_mfma_i32_16x16x64_i8 v[46:49], v[126:129], v[216:219], v[46:49]
	v_mfma_i32_16x16x64_i8 v[46:49], v[122:125], v[212:215], v[46:49]
	v_mfma_i32_16x16x64_i8 v[30:33], v[122:125], v[220:223], v[30:33]
	v_mfma_i32_16x16x64_i8 v[30:33], v[126:129], v[224:227], v[30:33]
	v_mfma_i32_16x16x64_i8 v[26:29], v[142:145], v[224:227], v[26:29]
	v_mfma_i32_16x16x64_i8 v[26:29], v[134:137], v[220:223], v[26:29]
	v_mfma_i32_16x16x64_i8 v[10:13], v[134:137], v[228:231], v[10:13]
	v_mfma_i32_16x16x64_i8 v[10:13], v[142:145], v[232:235], v[10:13]
	v_mfma_i32_16x16x64_i8 v[14:17], v[126:129], v[232:235], v[14:17]
	v_mfma_i32_16x16x64_i8 v[14:17], v[122:125], v[228:231], v[14:17]
	s_setprio 0
	s_setprio 1
	v_mfma_i32_16x16x64_i8 v[54:57], v[184:187], v[200:203], v[54:57]
	v_mfma_i32_16x16x64_i8 v[54:57], v[188:191], v[204:207], v[54:57]
	v_mfma_i32_16x16x64_i8 v[50:53], v[196:199], v[204:207], v[50:53]
	v_mfma_i32_16x16x64_i8 v[50:53], v[192:195], v[200:203], v[50:53]
	v_mfma_i32_16x16x64_i8 v[34:37], v[192:195], v[212:215], v[34:37]
	v_mfma_i32_16x16x64_i8 v[34:37], v[196:199], v[216:219], v[34:37]
	v_mfma_i32_16x16x64_i8 v[38:41], v[188:191], v[216:219], v[38:41]
	v_mfma_i32_16x16x64_i8 v[38:41], v[184:187], v[212:215], v[38:41]
	v_mfma_i32_16x16x64_i8 v[22:25], v[184:187], v[220:223], v[22:25]
	v_mfma_i32_16x16x64_i8 v[22:25], v[188:191], v[224:227], v[22:25]
	v_mfma_i32_16x16x64_i8 v[18:21], v[196:199], v[224:227], v[18:21]
	v_mfma_i32_16x16x64_i8 v[18:21], v[192:195], v[220:223], v[18:21]
	v_mfma_i32_16x16x64_i8 v[2:5], v[192:195], v[228:231], v[2:5]
	v_mfma_i32_16x16x64_i8 v[2:5], v[196:199], v[232:235], v[2:5]
	v_mfma_i32_16x16x64_i8 v[6:9], v[188:191], v[232:235], v[6:9]
	v_mfma_i32_16x16x64_i8 v[6:9], v[184:187], v[228:231], v[6:9]
	s_setprio 0
	s_barrier
	s_add_i32 s50, s50, 2
	s_add_u32 s0, s0, 0x100
	s_addc_u32 s1, s1, 0
	s_add_u32 s46, s46, 0x100
	s_addc_u32 s47, s47, 0

; #define PG8_STAGE(bufoff, gbase, voff) do { _Pragma("unroll") for (int _i = 0; _i < 2; ++_i) \
;         __builtin_amdgcn_global_load_lds((const unsigned*)((const char*)(gbase) + (voff)[_i]), (PG8_LAS unsigned*)(lds + (bufoff) + ldsw + _i * 8192), 16, 0, 0); } while (0)
; #define PG8_LDA(dst, b, h) do { _Pragma("unroll") for (int m = 0; m < 4; ++m) _Pragma("unroll") for (int k = 0; k < 2; ++k) dst[m][k] = *(const PG8_LAS bf16x8*)(lds + PG8_SA(b, h) + aoff + m * 2048 + k * 1024); } while (0)
; #define PG8_LDB(dst, b, h) do { _Pragma("unroll") for (int n = 0; n < 2; ++n) _Pragma("unroll") for (int k = 0; k < 2; ++k) dst[n][k] = *(const PG8_LAS bf16x8*)(lds + PG8_SB(b, h) + boff + n * 2048 + k * 1024); } while (0)
; #define PG8_MMA(ai, bj, At, Bt) do { __builtin_amdgcn_s_setprio(1); _Pragma("unroll") for (int m = 0; m < 4; ++m) _Pragma("unroll") for (int n = 0; n < 2; ++n) _Pragma("unroll") for (int k = 0; k < 2; ++k) \
;         acc[ai][bj][m][n] = mma16(Bt[n][k], At[m][k], acc[ai][bj][m][n]); __builtin_amdgcn_s_setprio(0); } while (0)
; template <class Epi, class Sched, bool ALIGN_EPI = false, bool SP2 = false>
; __device__ __forceinline__ void gemm_phase(PG8_LAS unsigned char* lds, const Gemm g, const Sched& S, const Epi& E) {
;     ...
;         const bool has_next = S.next(ui + 1, nxt);
;         const char* nA = has_next ? PG8_ABASE(nxt) : cA; const char* nB = has_next ? PG8_BBASE(nxt) : cB;
; #pragma unroll 1
;         for (int t = 0; t < nt; t += 2) {
;             const bool last = (t == nt - 2);
;             const char* a1 = cA + (size_t)(t + 1) * kstep;
;             const char* a2 = last ? nA : cA + (size_t)(t + 2) * kstep; const char* b2 = last ? nB : cB + (size_t)(t + 2) * kstep;
;             const char* a3 = a2 + kstep; const char* b3 = b2 + kstep;
;             if (last && has_next) S.a_ready(nxt);
;             if constexpr (SP2) {
;             PG8_LDB(B0, 0, 0); PG8_LDB(B1, 0, 1); PG8_SCHED; PG8_LDA(At, 0, 0); PG8_STAGE(PG8_SA(1, 1), a1 + hstepA, voffA);
;             PG8_WAIT_V(8); PG8_WAIT_L(0); PG8_BAR; PG8_MMA(0, 0, At, B0); PG8_MMA(0, 1, At, B1); PG8_BAR; PG8_SCHED;
;             PG8_LDA(At, 0, 1); PG8_STAGE(PG8_SB(0, 0), b2, voffB); PG8_STAGE(PG8_SB(0, 1), b2 + hstepB, voffB); PG8_STAGE(PG8_SA(0, 0), a2, voffA);
;             PG8_WAIT_V(8); PG8_WAIT_L(0); PG8_BAR; PG8_MMA(1, 0, At, B0); PG8_MMA(1, 1, At, B1); PG8_BAR; PG8_SCHED;
.LBB0_274:
	s_ashr_i32 s39, s38, 31
	s_lshl_b64 s[46:47], s[38:39], 20
	s_add_u32 s58, s8, s46
	s_addc_u32 s59, s11, s47
	s_and_b64 s[0:1], s[0:1], exec
	s_cselect_b32 s37, s59, s65
	s_cselect_b32 s46, s58, s64
	s_add_u32 s0, s66, 0x80080
	s_addc_u32 s1, s67, 0
	s_add_u32 s47, s64, 0x100
	s_addc_u32 s49, s65, 0
	s_mov_b32 s50, -2
	ds_read_b128 v[122:125], v169
	ds_read_b128 v[126:129], v169 offset:1024
	ds_read_b128 v[134:137], v169 offset:2048
	ds_read_b128 v[142:145], v169 offset:3072
	ds_read_b128 v[182:185], v170
	ds_read_b128 v[186:189], v170 offset:1024
	ds_read_b128 v[190:193], v170 offset:2048
	ds_read_b128 v[194:197], v170 offset:3072
	s_add_u32 s51, s0, 0xfff80080
	s_addc_u32 s63, s1, -1
	s_cmp_eq_u32 s50, 28
	s_cselect_b32 s67, s55, s63
	s_cselect_b32 s66, s54, s51
	s_cselect_b32 s65, s37, s49
	s_cselect_b32 s64, s46, s47
	v_lshl_add_u64 v[166:167], s[0:1], 0, v[158:159]
	s_add_i32 m0, s18, 0xc000
	ds_read_b128 v[198:201], v171
	ds_read_b128 v[202:205], v171 offset:1024
	ds_read_b128 v[206:209], v171 offset:2048
	ds_read_b128 v[212:215], v171 offset:3072
	ds_read_b128 v[216:219], v171 offset:4096
	ds_read_b128 v[220:223], v171 offset:5120
	ds_read_b128 v[224:227], v171 offset:6144
	ds_read_b128 v[228:231], v171 offset:7168
	global_load_lds_dwordx4 v[166:167], off
	v_lshl_add_u64 v[166:167], s[0:1], 0, v[160:161]
	s_add_i32 m0, s18, 0xe000
	s_nop 0
	global_load_lds_dwordx4 v[166:167], off
	s_waitcnt vmcnt(8)
	s_waitcnt lgkmcnt(0)
	s_barrier
	s_setprio 1
	s_waitcnt lgkmcnt(0)
	v_mfma_i32_16x16x64_i8 v[138:141], v[122:125], v[198:201], 0
	v_mfma_i32_16x16x64_i8 v[138:141], v[126:129], v[202:205], v[138:141]
	v_mfma_i32_16x16x64_i8 v[130:133], v[142:145], v[202:205], 0
	v_mfma_i32_16x16x64_i8 v[130:133], v[134:137], v[198:201], v[130:133]
	v_mfma_i32_16x16x64_i8 v[106:109], v[134:137], v[206:209], 0
	v_mfma_i32_16x16x64_i8 v[106:109], v[142:145], v[212:215], v[106:109]
	v_mfma_i32_16x16x64_i8 v[110:113], v[126:129], v[212:215], 0
	v_mfma_i32_16x16x64_i8 v[110:113], v[122:125], v[206:209], v[110:113]
	v_mfma_i32_16x16x64_i8 v[94:97], v[122:125], v[216:219], 0
	v_mfma_i32_16x16x64_i8 v[94:97], v[126:129], v[220:223], v[94:97]
	v_mfma_i32_16x16x64_i8 v[90:93], v[142:145], v[220:223], 0
	v_mfma_i32_16x16x64_i8 v[90:93], v[134:137], v[216:219], v[90:93]
	v_mfma_i32_16x16x64_i8 v[74:77], v[134:137], v[224:227], 0
	v_mfma_i32_16x16x64_i8 v[74:77], v[142:145], v[228:231], v[74:77]
	v_mfma_i32_16x16x64_i8 v[78:81], v[126:129], v[228:231], 0
	v_mfma_i32_16x16x64_i8 v[78:81], v[122:125], v[224:227], v[78:81]
	s_setprio 0
	s_setprio 1
	v_mfma_i32_16x16x64_i8 v[118:121], v[182:185], v[198:201], 0
	v_mfma_i32_16x16x64_i8 v[118:121], v[186:189], v[202:205], v[118:121]
	v_mfma_i32_16x16x64_i8 v[114:117], v[194:197], v[202:205], 0
	v_mfma_i32_16x16x64_i8 v[114:117], v[190:193], v[198:201], v[114:117]
	v_mfma_i32_16x16x64_i8 v[98:101], v[190:193], v[206:209], 0
	v_mfma_i32_16x16x64_i8 v[98:101], v[194:197], v[212:215], v[98:101]
	v_mfma_i32_16x16x64_i8 v[102:105], v[186:189], v[212:215], 0
	v_mfma_i32_16x16x64_i8 v[102:105], v[182:185], v[206:209], v[102:105]
	v_mfma_i32_16x16x64_i8 v[86:89], v[182:185], v[216:219], 0
	v_mfma_i32_16x16x64_i8 v[86:89], v[186:189], v[220:223], v[86:89]
	v_mfma_i32_16x16x64_i8 v[82:85], v[194:197], v[220:223], 0
	v_mfma_i32_16x16x64_i8 v[82:85], v[190:193], v[216:219], v[82:85]
	v_mfma_i32_16x16x64_i8 v[66:69], v[190:193], v[224:227], 0
	v_mfma_i32_16x16x64_i8 v[66:69], v[194:197], v[228:231], v[66:69]
	v_mfma_i32_16x16x64_i8 v[70:73], v[186:189], v[228:231], 0
	v_mfma_i32_16x16x64_i8 v[70:73], v[182:185], v[224:227], v[70:73]
	s_setprio 0
	s_barrier
	s_add_i32 s51, s28, s12
	v_lshl_add_u64 v[166:167], s[64:65], 0, v[148:149]
	s_mov_b32 m0, s51
	ds_read_b128 v[198:201], v171 offset:16384
	ds_read_b128 v[202:205], v171 offset:17408
	ds_read_b128 v[206:209], v171 offset:18432
	ds_read_b128 v[212:215], v171 offset:19456
	ds_read_b128 v[216:219], v171 offset:20480
	ds_read_b128 v[220:223], v171 offset:21504
	ds_read_b128 v[224:227], v171 offset:22528
	ds_read_b128 v[228:231], v171 offset:23552
	global_load_lds_dwordx4 v[166:167], off
	s_add_i32 m0, s51, 0x2000
	s_add_u32 s68, s64, 0x80000
	v_lshl_add_u64 v[176:177], s[64:65], 0, v[152:153]
	s_addc_u32 s69, s65, 0
	s_add_i32 s51, s29, s12
	global_load_lds_dwordx4 v[176:177], off
	v_lshl_add_u64 v[232:233], s[68:69], 0, v[148:149]
	s_mov_b32 m0, s51
	v_lshl_add_u64 v[234:235], s[66:67], 0, v[150:151]
	global_load_lds_dwordx4 v[232:233], off
	v_lshl_add_u64 v[232:233], s[68:69], 0, v[152:153]
	s_add_i32 m0, s51, 0x2000
	s_nop 0
	global_load_lds_dwordx4 v[232:233], off
	v_lshl_add_u64 v[232:233], s[66:67], 0, v[146:147]
	s_mov_b32 m0, s18
	s_nop 0
	global_load_lds_dwordx4 v[232:233], off
	s_mov_b32 m0, s19
	s_nop 0
	global_load_lds_dwordx4 v[234:235], off
	s_waitcnt vmcnt(8)
	s_waitcnt lgkmcnt(0)
	s_barrier
; #define PG8_STAGE(bufoff, gbase, voff) do { _Pragma("unroll") for (int _i = 0; _i < 2; ++_i) \
;         __builtin_amdgcn_global_load_lds((const unsigned*)((const char*)(gbase) + (voff)[_i]), (PG8_LAS unsigned*)(lds + (bufoff) + ldsw + _i * 8192), 16, 0, 0); } while (0)
; #define PG8_LDA(dst, b, h) do { _Pragma("unroll") for (int m = 0; m < 4; ++m) _Pragma("unroll") for (int k = 0; k < 2; ++k) dst[m][k] = *(const PG8_LAS bf16x8*)(lds + PG8_SA(b, h) + aoff + m * 2048 + k * 1024); } while (0)
; #define PG8_LDB(dst, b, h) do { _Pragma("unroll") for (int n = 0; n < 2; ++n) _Pragma("unroll") for (int k = 0; k < 2; ++k) dst[n][k] = *(const PG8_LAS bf16x8*)(lds + PG8_SB(b, h) + boff + n * 2048 + k * 1024); } while (0)
; #define PG8_MMA(ai, bj, At, Bt) do { __builtin_amdgcn_s_setprio(1); _Pragma("unroll") for (int m = 0; m < 4; ++m) _Pragma("unroll") for (int n = 0; n < 2; ++n) _Pragma("unroll") for (int k = 0; k < 2; ++k) \
;         acc[ai][bj][m][n] = mma16(Bt[n][k], At[m][k], acc[ai][bj][m][n]); __builtin_amdgcn_s_setprio(0); } while (0)
; #define PG8_WAIT_V(n) asm volatile("s_waitcnt vmcnt(" #n ")" ::: "memory")
; template <class Epi, class Sched, bool ALIGN_EPI = false, bool SP2 = false>
; __device__ __forceinline__ void gemm_phase(PG8_LAS unsigned char* lds, const Gemm g, const Sched& S, const Epi& E) {
;     ...
;             PG8_LDB(B0, 0, 0); PG8_LDB(B1, 0, 1); PG8_SCHED; PG8_LDA(At, 0, 0); PG8_STAGE(PG8_SA(1, 1), a1 + hstepA, voffA);
;             PG8_WAIT_V(8); PG8_WAIT_L(0); PG8_BAR; PG8_MMA(0, 0, At, B0); PG8_MMA(0, 1, At, B1); PG8_BAR; PG8_SCHED;
;             PG8_LDA(At, 0, 1); PG8_STAGE(PG8_SB(0, 0), b2, voffB); PG8_STAGE(PG8_SB(0, 1), b2 + hstepB, voffB); PG8_STAGE(PG8_SA(0, 0), a2, voffA);
;             PG8_WAIT_V(8); PG8_WAIT_L(0); PG8_BAR; PG8_MMA(1, 0, At, B0); PG8_MMA(1, 1, At, B1); PG8_BAR; PG8_SCHED;
;             PG8_LDB(B0, 1, 0); PG8_LDB(B1, 1, 1); PG8_SCHED; PG8_LDA(At, 1, 0); PG8_STAGE(PG8_SA(0, 1), a2 + hstepA, voffA);
;             PG8_WAIT_V(8); PG8_WAIT_L(0); PG8_BAR; PG8_MMA(0, 0, At, B0); PG8_MMA(0, 1, At, B1); PG8_BAR; PG8_SCHED;
;             PG8_LDA(At, 1, 1); PG8_STAGE(PG8_SB(1, 0), b3, voffB); PG8_STAGE(PG8_SB(1, 1), b3 + hstepB, voffB); PG8_STAGE(PG8_SA(1, 0), a3, voffA);
;             PG8_WAIT_V(8); PG8_WAIT_L(0); PG8_BAR; PG8_MMA(1, 0, At, B0); PG8_MMA(1, 1, At, B1); PG8_BAR; PG8_SCHED;
	s_setprio 1
	s_waitcnt lgkmcnt(0)
	v_mfma_i32_16x16x64_i8 v[62:65], v[122:125], v[198:201], 0
	v_mfma_i32_16x16x64_i8 v[62:65], v[126:129], v[202:205], v[62:65]
	v_mfma_i32_16x16x64_i8 v[58:61], v[142:145], v[202:205], 0
	v_mfma_i32_16x16x64_i8 v[58:61], v[134:137], v[198:201], v[58:61]
	v_mfma_i32_16x16x64_i8 v[42:45], v[134:137], v[206:209], 0
	v_mfma_i32_16x16x64_i8 v[42:45], v[142:145], v[212:215], v[42:45]
	v_mfma_i32_16x16x64_i8 v[46:49], v[126:129], v[212:215], 0
	v_mfma_i32_16x16x64_i8 v[46:49], v[122:125], v[206:209], v[46:49]
	v_mfma_i32_16x16x64_i8 v[30:33], v[122:125], v[216:219], 0
	v_mfma_i32_16x16x64_i8 v[30:33], v[126:129], v[220:223], v[30:33]
	v_mfma_i32_16x16x64_i8 v[26:29], v[142:145], v[220:223], 0
	v_mfma_i32_16x16x64_i8 v[26:29], v[134:137], v[216:219], v[26:29]
	v_mfma_i32_16x16x64_i8 v[10:13], v[134:137], v[224:227], 0
	v_mfma_i32_16x16x64_i8 v[10:13], v[142:145], v[228:231], v[10:13]
	v_mfma_i32_16x16x64_i8 v[14:17], v[126:129], v[228:231], 0
	v_mfma_i32_16x16x64_i8 v[14:17], v[122:125], v[224:227], v[14:17]
	s_setprio 0
	s_setprio 1
	v_mfma_i32_16x16x64_i8 v[54:57], v[182:185], v[198:201], 0
	v_mfma_i32_16x16x64_i8 v[54:57], v[186:189], v[202:205], v[54:57]
	v_mfma_i32_16x16x64_i8 v[50:53], v[194:197], v[202:205], 0
	v_mfma_i32_16x16x64_i8 v[50:53], v[190:193], v[198:201], v[50:53]
	v_mfma_i32_16x16x64_i8 v[34:37], v[190:193], v[206:209], 0
	v_mfma_i32_16x16x64_i8 v[34:37], v[194:197], v[212:215], v[34:37]
	v_mfma_i32_16x16x64_i8 v[38:41], v[186:189], v[212:215], 0
	v_mfma_i32_16x16x64_i8 v[38:41], v[182:185], v[206:209], v[38:41]
	v_mfma_i32_16x16x64_i8 v[22:25], v[182:185], v[216:219], 0
	v_mfma_i32_16x16x64_i8 v[22:25], v[186:189], v[220:223], v[22:25]
	v_mfma_i32_16x16x64_i8 v[18:21], v[194:197], v[220:223], 0
	v_mfma_i32_16x16x64_i8 v[18:21], v[190:193], v[216:219], v[18:21]
	v_mfma_i32_16x16x64_i8 v[2:5], v[190:193], v[224:227], 0
	v_mfma_i32_16x16x64_i8 v[2:5], v[194:197], v[228:231], v[2:5]
	v_mfma_i32_16x16x64_i8 v[6:9], v[186:189], v[228:231], 0
	v_mfma_i32_16x16x64_i8 v[6:9], v[182:185], v[224:227], v[6:9]
	s_setprio 0
	s_barrier
	s_add_i32 s51, 0, 0x18000
	s_add_i32 s63, 0, 0x1c000
	v_add_u32_e32 v142, s51, v173
	v_add_u32_e32 v172, s63, v173
	ds_read_b128 v[122:125], v142
	ds_read_b128 v[126:129], v142 offset:1024
	ds_read_b128 v[134:137], v142 offset:2048
	ds_read_b128 v[142:145], v142 offset:3072
	ds_read_b128 v[182:185], v172
	ds_read_b128 v[186:189], v172 offset:1024
	ds_read_b128 v[190:193], v172 offset:2048
	ds_read_b128 v[194:197], v172 offset:3072
	s_add_u32 s66, s66, 0x80000
	s_addc_u32 s67, s67, 0
	s_mov_b32 m0, s20
	v_lshl_add_u64 v[236:237], s[66:67], 0, v[146:147]
	ds_read_b128 v[198:201], v171 offset:32768
	ds_read_b128 v[202:205], v171 offset:33792
	ds_read_b128 v[206:209], v171 offset:34816
	ds_read_b128 v[212:215], v171 offset:35840
	ds_read_b128 v[216:219], v171 offset:36864
	ds_read_b128 v[220:223], v171 offset:37888
	ds_read_b128 v[224:227], v171 offset:38912
	ds_read_b128 v[228:231], v171 offset:39936
	global_load_lds_dwordx4 v[236:237], off
	v_lshl_add_u64 v[236:237], s[66:67], 0, v[150:151]
	s_mov_b32 m0, s21
	s_nop 0
	global_load_lds_dwordx4 v[236:237], off
	s_waitcnt vmcnt(8)
	s_waitcnt lgkmcnt(0)
	s_barrier
	s_setprio 1
	s_waitcnt lgkmcnt(0)
	v_mfma_i32_16x16x64_i8 v[138:141], v[122:125], v[198:201], v[138:141]
	v_mfma_i32_16x16x64_i8 v[138:141], v[126:129], v[202:205], v[138:141]
	v_mfma_i32_16x16x64_i8 v[130:133], v[142:145], v[202:205], v[130:133]
	v_mfma_i32_16x16x64_i8 v[130:133], v[134:137], v[198:201], v[130:133]
	v_mfma_i32_16x16x64_i8 v[106:109], v[134:137], v[206:209], v[106:109]
	v_mfma_i32_16x16x64_i8 v[106:109], v[142:145], v[212:215], v[106:109]
	v_mfma_i32_16x16x64_i8 v[110:113], v[126:129], v[212:215], v[110:113]
	v_mfma_i32_16x16x64_i8 v[110:113], v[122:125], v[206:209], v[110:113]
	v_mfma_i32_16x16x64_i8 v[94:97], v[122:125], v[216:219], v[94:97]
	v_mfma_i32_16x16x64_i8 v[94:97], v[126:129], v[220:223], v[94:97]
	v_mfma_i32_16x16x64_i8 v[90:93], v[142:145], v[220:223], v[90:93]
	v_mfma_i32_16x16x64_i8 v[90:93], v[134:137], v[216:219], v[90:93]
	v_mfma_i32_16x16x64_i8 v[74:77], v[134:137], v[224:227], v[74:77]
	v_mfma_i32_16x16x64_i8 v[74:77], v[142:145], v[228:231], v[74:77]
	v_mfma_i32_16x16x64_i8 v[78:81], v[126:129], v[228:231], v[78:81]
	v_mfma_i32_16x16x64_i8 v[78:81], v[122:125], v[224:227], v[78:81]
	s_setprio 0
	s_setprio 1
	v_mfma_i32_16x16x64_i8 v[118:121], v[182:185], v[198:201], v[118:121]
	v_mfma_i32_16x16x64_i8 v[118:121], v[186:189], v[202:205], v[118:121]
	v_mfma_i32_16x16x64_i8 v[114:117], v[194:197], v[202:205], v[114:117]
	v_mfma_i32_16x16x64_i8 v[114:117], v[190:193], v[198:201], v[114:117]
	v_mfma_i32_16x16x64_i8 v[98:101], v[190:193], v[206:209], v[98:101]
	v_mfma_i32_16x16x64_i8 v[98:101], v[194:197], v[212:215], v[98:101]
	v_mfma_i32_16x16x64_i8 v[102:105], v[186:189], v[212:215], v[102:105]
	v_mfma_i32_16x16x64_i8 v[102:105], v[182:185], v[206:209], v[102:105]
	v_mfma_i32_16x16x64_i8 v[86:89], v[182:185], v[216:219], v[86:89]
	v_mfma_i32_16x16x64_i8 v[86:89], v[186:189], v[220:223], v[86:89]
	v_mfma_i32_16x16x64_i8 v[82:85], v[194:197], v[220:223], v[82:85]
	v_mfma_i32_16x16x64_i8 v[82:85], v[190:193], v[216:219], v[82:85]
	v_mfma_i32_16x16x64_i8 v[66:69], v[190:193], v[224:227], v[66:69]
	v_mfma_i32_16x16x64_i8 v[66:69], v[194:197], v[228:231], v[66:69]
	v_mfma_i32_16x16x64_i8 v[70:73], v[186:189], v[228:231], v[70:73]
	v_mfma_i32_16x16x64_i8 v[70:73], v[182:185], v[224:227], v[70:73]
	s_setprio 0
	s_barrier
; #define PG8_STAGE(bufoff, gbase, voff) do { _Pragma("unroll") for (int _i = 0; _i < 2; ++_i) \
;         __builtin_amdgcn_global_load_lds((const unsigned*)((const char*)(gbase) + (voff)[_i]), (PG8_LAS unsigned*)(lds + (bufoff) + ldsw + _i * 8192), 16, 0, 0); } while (0)
; #define PG8_LDA(dst, b, h) do { _Pragma("unroll") for (int m = 0; m < 4; ++m) _Pragma("unroll") for (int k = 0; k < 2; ++k) dst[m][k] = *(const PG8_LAS bf16x8*)(lds + PG8_SA(b, h) + aoff + m * 2048 + k * 1024); } while (0)
; #define PG8_MMA(ai, bj, At, Bt) do { __builtin_amdgcn_s_setprio(1); _Pragma("unroll") for (int m = 0; m < 4; ++m) _Pragma("unroll") for (int n = 0; n < 2; ++n) _Pragma("unroll") for (int k = 0; k < 2; ++k) \
;         acc[ai][bj][m][n] = mma16(Bt[n][k], At[m][k], acc[ai][bj][m][n]); __builtin_amdgcn_s_setprio(0); } while (0)
; #define PG8_WAIT_V(n) asm volatile("s_waitcnt vmcnt(" #n ")" ::: "memory")
; #define PG8_WAIT_L(n) asm volatile("s_waitcnt lgkmcnt(" #n ")" ::: "memory")
; #define PG8_BAR __builtin_amdgcn_s_barrier()
; #define PG8_SCHED __builtin_amdgcn_sched_barrier(0)
; template <class Epi, class Sched, bool ALIGN_EPI = false, bool SP2 = false>
; __device__ __forceinline__ void gemm_phase(PG8_LAS unsigned char* lds, const Gemm g, const Sched& S, const Epi& E) {
;     ...
;             PG8_LDA(At, 1, 1); PG8_STAGE(PG8_SB(1, 0), b3, voffB); PG8_STAGE(PG8_SB(1, 1), b3 + hstepB, voffB); PG8_STAGE(PG8_SA(1, 0), a3, voffA);
;             PG8_WAIT_V(8); PG8_WAIT_L(0); PG8_BAR; PG8_MMA(1, 0, At, B0); PG8_MMA(1, 1, At, B1); PG8_BAR; PG8_SCHED;
	s_add_i32 s51, s51, s12
	v_lshl_add_u64 v[166:167], v[166:167], 0, s[42:43]
	s_mov_b32 m0, s51
	ds_read_b128 v[198:201], v171 offset:49152
	ds_read_b128 v[202:205], v171 offset:50176
	ds_read_b128 v[206:209], v171 offset:51200
	ds_read_b128 v[212:215], v171 offset:52224
	ds_read_b128 v[216:219], v171 offset:53248
	ds_read_b128 v[220:223], v171 offset:54272
	ds_read_b128 v[224:227], v171 offset:55296
	ds_read_b128 v[228:231], v171 offset:56320
	global_load_lds_dwordx4 v[166:167], off
	s_add_i32 m0, s51, 0x2000
	s_add_u32 s64, s64, 0x80080
	v_lshl_add_u64 v[166:167], v[176:177], 0, s[42:43]
	s_addc_u32 s65, s65, 0
	s_add_i32 s51, s63, s12
	global_load_lds_dwordx4 v[166:167], off
	v_lshl_add_u64 v[166:167], s[64:65], 0, v[148:149]
	s_mov_b32 m0, s51
	s_nop 0
	global_load_lds_dwordx4 v[166:167], off
	v_lshl_add_u64 v[166:167], s[64:65], 0, v[152:153]
	s_add_i32 m0, s51, 0x2000
	s_nop 0
	global_load_lds_dwordx4 v[166:167], off
	v_lshl_add_u64 v[166:167], v[232:233], 0, s[42:43]
	s_mov_b32 m0, s24
	s_nop 0
	global_load_lds_dwordx4 v[166:167], off
	v_lshl_add_u64 v[166:167], v[234:235], 0, s[42:43]
	s_mov_b32 m0, s25
	s_nop 0
	global_load_lds_dwordx4 v[166:167], off
	s_waitcnt vmcnt(8)
	s_waitcnt lgkmcnt(0)
	s_barrier
	s_setprio 1
	s_waitcnt lgkmcnt(0)
	v_mfma_i32_16x16x64_i8 v[62:65], v[122:125], v[198:201], v[62:65]
	v_mfma_i32_16x16x64_i8 v[62:65], v[126:129], v[202:205], v[62:65]
	v_mfma_i32_16x16x64_i8 v[58:61], v[142:145], v[202:205], v[58:61]
	v_mfma_i32_16x16x64_i8 v[58:61], v[134:137], v[198:201], v[58:61]
	v_mfma_i32_16x16x64_i8 v[42:45], v[134:137], v[206:209], v[42:45]
	v_mfma_i32_16x16x64_i8 v[42:45], v[142:145], v[212:215], v[42:45]
	v_mfma_i32_16x16x64_i8 v[46:49], v[126:129], v[212:215], v[46:49]
	v_mfma_i32_16x16x64_i8 v[46:49], v[122:125], v[206:209], v[46:49]
	v_mfma_i32_16x16x64_i8 v[30:33], v[122:125], v[216:219], v[30:33]
	v_mfma_i32_16x16x64_i8 v[30:33], v[126:129], v[220:223], v[30:33]
	v_mfma_i32_16x16x64_i8 v[26:29], v[142:145], v[220:223], v[26:29]
	v_mfma_i32_16x16x64_i8 v[26:29], v[134:137], v[216:219], v[26:29]
	v_mfma_i32_16x16x64_i8 v[10:13], v[134:137], v[224:227], v[10:13]
	v_mfma_i32_16x16x64_i8 v[10:13], v[142:145], v[228:231], v[10:13]
	v_mfma_i32_16x16x64_i8 v[14:17], v[126:129], v[228:231], v[14:17]
	v_mfma_i32_16x16x64_i8 v[14:17], v[122:125], v[224:227], v[14:17]
	s_setprio 0
	s_setprio 1
	v_mfma_i32_16x16x64_i8 v[54:57], v[182:185], v[198:201], v[54:57]
	v_mfma_i32_16x16x64_i8 v[54:57], v[186:189], v[202:205], v[54:57]
	v_mfma_i32_16x16x64_i8 v[50:53], v[194:197], v[202:205], v[50:53]
	v_mfma_i32_16x16x64_i8 v[50:53], v[190:193], v[198:201], v[50:53]
	v_mfma_i32_16x16x64_i8 v[34:37], v[190:193], v[206:209], v[34:37]
	v_mfma_i32_16x16x64_i8 v[34:37], v[194:197], v[212:215], v[34:37]
	v_mfma_i32_16x16x64_i8 v[38:41], v[186:189], v[212:215], v[38:41]
	v_mfma_i32_16x16x64_i8 v[38:41], v[182:185], v[206:209], v[38:41]
	v_mfma_i32_16x16x64_i8 v[22:25], v[182:185], v[216:219], v[22:25]
	v_mfma_i32_16x16x64_i8 v[22:25], v[186:189], v[220:223], v[22:25]
	v_mfma_i32_16x16x64_i8 v[18:21], v[194:197], v[220:223], v[18:21]
	v_mfma_i32_16x16x64_i8 v[18:21], v[190:193], v[216:219], v[18:21]
	v_mfma_i32_16x16x64_i8 v[2:5], v[190:193], v[224:227], v[2:5]
	v_mfma_i32_16x16x64_i8 v[2:5], v[194:197], v[228:231], v[2:5]
	v_mfma_i32_16x16x64_i8 v[6:9], v[186:189], v[228:231], v[6:9]
	v_mfma_i32_16x16x64_i8 v[6:9], v[182:185], v[224:227], v[6:9]
	s_setprio 0
	s_barrier
	s_add_i32 s50, s50, 2
	s_add_u32 s0, s0, 0x100
	s_addc_u32 s1, s1, 0
	s_add_u32 s47, s47, 0x100
	s_addc_u32 s49, s49, 0

; #define PG8_STAGE(bufoff, gbase, voff) do { _Pragma("unroll") for (int _i = 0; _i < 2; ++_i) \
;         __builtin_amdgcn_global_load_lds((const unsigned*)((const char*)(gbase) + (voff)[_i]), (PG8_LAS unsigned*)(lds + (bufoff) + ldsw + _i * 8192), 16, 0, 0); } while (0)
; #define PG8_LDA(dst, b, h) do { _Pragma("unroll") for (int m = 0; m < 4; ++m) _Pragma("unroll") for (int k = 0; k < 2; ++k) dst[m][k] = *(const PG8_LAS bf16x8*)(lds + PG8_SA(b, h) + aoff + m * 2048 + k * 1024); } while (0)
; #define PG8_BAR __builtin_amdgcn_s_barrier()
; template <class Epi, class Sched, bool ALIGN_EPI = false, bool SP2 = false>
; __device__ __forceinline__ void gemm_phase(PG8_LAS unsigned char* lds, const Gemm g, const Sched& S, const Epi& E) {
;     ...
;         const bool has_next = S.next(ui + 1, nxt);
;         const char* nA = has_next ? PG8_ABASE(nxt) : cA; const char* nB = has_next ? PG8_BBASE(nxt) : cB;
; #pragma unroll 1
;         for (int t = 0; t < nt; t += 2) {
;             const bool last = (t == nt - 2);
;             const char* a1 = cA + (size_t)(t + 1) * kstep;
;             const char* a2 = last ? nA : cA + (size_t)(t + 2) * kstep; const char* b2 = last ? nB : cB + (size_t)(t + 2) * kstep;
;             const char* a3 = a2 + kstep; const char* b3 = b2 + kstep;
;             if (last && has_next) S.a_ready(nxt);
;             if constexpr (SP2) {
;             PG8_LDB(B0, 0, 0); PG8_LDB(B1, 0, 1); PG8_SCHED; PG8_LDA(At, 0, 0); PG8_STAGE(PG8_SA(1, 1), a1 + hstepA, voffA);
;             PG8_WAIT_V(8); PG8_WAIT_L(0); PG8_BAR; PG8_MMA(0, 0, At, B0); PG8_MMA(0, 1, At, B1); PG8_BAR; PG8_SCHED;
;             PG8_LDA(At, 0, 1); PG8_STAGE(PG8_SB(0, 0), b2, voffB); PG8_STAGE(PG8_SB(0, 1), b2 + hstepB, voffB); PG8_STAGE(PG8_SA(0, 0), a2, voffA);
;             PG8_WAIT_V(8); PG8_WAIT_L(0); PG8_BAR; PG8_MMA(1, 0, At, B0); PG8_MMA(1, 1, At, B1); PG8_BAR; PG8_SCHED;
;             PG8_LDB(B0, 1, 0); PG8_LDB(B1, 1, 1); PG8_SCHED; PG8_LDA(At, 1, 0); PG8_STAGE(PG8_SA(0, 1), a2 + hstepA, voffA);
;             PG8_WAIT_V(8); PG8_WAIT_L(0); PG8_BAR; PG8_MMA(0, 0, At, B0); PG8_MMA(0, 1, At, B1); PG8_BAR; PG8_SCHED;
;             PG8_LDA(At, 1, 1); PG8_STAGE(PG8_SB(1, 0), b3, voffB); PG8_STAGE(PG8_SB(1, 1), b3 + hstepB, voffB); PG8_STAGE(PG8_SA(1, 0), a3, voffA);
;             PG8_WAIT_V(8); PG8_WAIT_L(0); PG8_BAR; PG8_MMA(1, 0, At, B0); PG8_MMA(1, 1, At, B1); PG8_BAR; PG8_SCHED;
.LBB0_388:
	s_ashr_i32 s43, s42, 31
	s_lshl_b64 s[26:27], s[42:43], 19
	s_add_u32 s50, s8, s26
	s_addc_u32 s51, s11, s27
	s_and_b64 s[0:1], s[0:1], exec
	s_cselect_b32 s25, s51, s55
	s_cselect_b32 s26, s50, s54
	s_add_u32 s0, s58, 0x100080
	s_addc_u32 s1, s59, 0
	s_add_u32 s27, s54, 0x100
	s_addc_u32 s28, s55, 0
	s_mov_b32 s29, -2
	ds_read_b128 v[154:157], v150
	ds_read_b128 v[158:161], v150 offset:1024
	ds_read_b128 v[162:165], v150 offset:2048
	ds_read_b128 v[166:169], v150 offset:3072
	ds_read_b128 v[170:173], v151
	ds_read_b128 v[174:177], v151 offset:1024
	ds_read_b128 v[182:185], v151 offset:2048
	ds_read_b128 v[186:189], v151 offset:3072
	s_add_u32 s33, s0, 0xfff00080
	s_addc_u32 s35, s1, -1
	s_cmp_eq_u32 s29, 12
	s_cselect_b32 s59, s49, s35
	s_cselect_b32 s58, s48, s33
	s_cselect_b32 s55, s25, s28
	s_cselect_b32 s54, s26, s27
	v_lshl_add_u64 v[146:147], s[0:1], 0, v[138:139]
	s_add_i32 m0, s12, 0xc000
	ds_read_b128 v[190:193], v152
	ds_read_b128 v[194:197], v152 offset:1024
	ds_read_b128 v[198:201], v152 offset:2048
	ds_read_b128 v[202:205], v152 offset:3072
	ds_read_b128 v[206:209], v152 offset:4096
	ds_read_b128 v[212:215], v152 offset:5120
	ds_read_b128 v[216:219], v152 offset:6144
	ds_read_b128 v[220:223], v152 offset:7168
	global_load_lds_dwordx4 v[146:147], off
	v_lshl_add_u64 v[146:147], s[0:1], 0, v[140:141]
	s_add_i32 m0, s12, 0xe000
	s_nop 0
	global_load_lds_dwordx4 v[146:147], off
	s_waitcnt vmcnt(8)
	s_waitcnt lgkmcnt(0)
	s_barrier
	s_setprio 1
	s_waitcnt lgkmcnt(0)
	v_mfma_f32_16x16x32_bf16 v[126:129], v[154:157], v[190:193], 0
	v_mfma_f32_16x16x32_bf16 v[126:129], v[158:161], v[194:197], v[126:129]
	v_mfma_f32_16x16x32_bf16 v[122:125], v[166:169], v[194:197], 0
	v_mfma_f32_16x16x32_bf16 v[122:125], v[162:165], v[190:193], v[122:125]
	v_mfma_f32_16x16x32_bf16 v[110:113], v[162:165], v[198:201], 0
	v_mfma_f32_16x16x32_bf16 v[110:113], v[166:169], v[202:205], v[110:113]
	v_mfma_f32_16x16x32_bf16 v[118:121], v[158:161], v[202:205], 0
	v_mfma_f32_16x16x32_bf16 v[118:121], v[154:157], v[198:201], v[118:121]
	v_mfma_f32_16x16x32_bf16 v[102:105], v[154:157], v[206:209], 0
	v_mfma_f32_16x16x32_bf16 v[102:105], v[158:161], v[212:215], v[102:105]
	v_mfma_f32_16x16x32_bf16 v[94:97], v[166:169], v[212:215], 0
	v_mfma_f32_16x16x32_bf16 v[94:97], v[162:165], v[206:209], v[94:97]
	v_mfma_f32_16x16x32_bf16 v[78:81], v[162:165], v[216:219], 0
	v_mfma_f32_16x16x32_bf16 v[78:81], v[166:169], v[220:223], v[78:81]
	v_mfma_f32_16x16x32_bf16 v[86:89], v[158:161], v[220:223], 0
	v_mfma_f32_16x16x32_bf16 v[86:89], v[154:157], v[216:219], v[86:89]
	s_setprio 0
	s_setprio 1
	v_mfma_f32_16x16x32_bf16 v[114:117], v[170:173], v[190:193], 0
	v_mfma_f32_16x16x32_bf16 v[114:117], v[174:177], v[194:197], v[114:117]
	v_mfma_f32_16x16x32_bf16 v[106:109], v[186:189], v[194:197], 0
	v_mfma_f32_16x16x32_bf16 v[106:109], v[182:185], v[190:193], v[106:109]
	v_mfma_f32_16x16x32_bf16 v[90:93], v[182:185], v[198:201], 0
	v_mfma_f32_16x16x32_bf16 v[90:93], v[186:189], v[202:205], v[90:93]
	v_mfma_f32_16x16x32_bf16 v[98:101], v[174:177], v[202:205], 0
	v_mfma_f32_16x16x32_bf16 v[98:101], v[170:173], v[198:201], v[98:101]
	v_mfma_f32_16x16x32_bf16 v[82:85], v[170:173], v[206:209], 0
	v_mfma_f32_16x16x32_bf16 v[82:85], v[174:177], v[212:215], v[82:85]
	v_mfma_f32_16x16x32_bf16 v[74:77], v[186:189], v[212:215], 0
	v_mfma_f32_16x16x32_bf16 v[74:77], v[182:185], v[206:209], v[74:77]
	v_mfma_f32_16x16x32_bf16 v[66:69], v[182:185], v[216:219], 0
	v_mfma_f32_16x16x32_bf16 v[66:69], v[186:189], v[220:223], v[66:69]
	v_mfma_f32_16x16x32_bf16 v[70:73], v[174:177], v[220:223], 0
	v_mfma_f32_16x16x32_bf16 v[70:73], v[170:173], v[216:219], v[70:73]
	s_setprio 0
	s_barrier
	s_add_i32 s33, s22, s7
	v_lshl_add_u64 v[146:147], s[54:55], 0, v[132:133]
	s_mov_b32 m0, s33
	ds_read_b128 v[190:193], v152 offset:16384
	ds_read_b128 v[194:197], v152 offset:17408
	ds_read_b128 v[198:201], v152 offset:18432
	ds_read_b128 v[202:205], v152 offset:19456
	ds_read_b128 v[206:209], v152 offset:20480
	ds_read_b128 v[212:215], v152 offset:21504
	ds_read_b128 v[216:219], v152 offset:22528
	ds_read_b128 v[220:223], v152 offset:23552
	global_load_lds_dwordx4 v[146:147], off
	s_add_i32 m0, s33, 0x2000
	s_add_u32 s36, s54, 0x40000
	v_lshl_add_u64 v[224:225], s[54:55], 0, v[136:137]
	s_addc_u32 s37, s55, 0
	s_add_i32 s33, s23, s7
	global_load_lds_dwordx4 v[224:225], off
	v_lshl_add_u64 v[226:227], s[36:37], 0, v[132:133]
	s_mov_b32 m0, s33
	v_lshl_add_u64 v[228:229], s[58:59], 0, v[134:135]
	global_load_lds_dwordx4 v[226:227], off
	v_lshl_add_u64 v[226:227], s[36:37], 0, v[136:137]
	s_add_i32 m0, s33, 0x2000
	s_nop 0
	global_load_lds_dwordx4 v[226:227], off
	v_lshl_add_u64 v[226:227], s[58:59], 0, v[130:131]
	s_mov_b32 m0, s12
	s_nop 0
	global_load_lds_dwordx4 v[226:227], off
	s_mov_b32 m0, s13
	s_nop 0
	global_load_lds_dwordx4 v[228:229], off
	s_waitcnt vmcnt(8)
	s_waitcnt lgkmcnt(0)
	s_barrier
; #define PG8_STAGE(bufoff, gbase, voff) do { _Pragma("unroll") for (int _i = 0; _i < 2; ++_i) \
;         __builtin_amdgcn_global_load_lds((const unsigned*)((const char*)(gbase) + (voff)[_i]), (PG8_LAS unsigned*)(lds + (bufoff) + ldsw + _i * 8192), 16, 0, 0); } while (0)
; #define PG8_LDA(dst, b, h) do { _Pragma("unroll") for (int m = 0; m < 4; ++m) _Pragma("unroll") for (int k = 0; k < 2; ++k) dst[m][k] = *(const PG8_LAS bf16x8*)(lds + PG8_SA(b, h) + aoff + m * 2048 + k * 1024); } while (0)
; #define PG8_LDB(dst, b, h) do { _Pragma("unroll") for (int n = 0; n < 2; ++n) _Pragma("unroll") for (int k = 0; k < 2; ++k) dst[n][k] = *(const PG8_LAS bf16x8*)(lds + PG8_SB(b, h) + boff + n * 2048 + k * 1024); } while (0)
; #define PG8_MMA(ai, bj, At, Bt) do { __builtin_amdgcn_s_setprio(1); _Pragma("unroll") for (int m = 0; m < 4; ++m) _Pragma("unroll") for (int n = 0; n < 2; ++n) _Pragma("unroll") for (int k = 0; k < 2; ++k) \
;         acc[ai][bj][m][n] = mma16(Bt[n][k], At[m][k], acc[ai][bj][m][n]); __builtin_amdgcn_s_setprio(0); } while (0)
; #define PG8_WAIT_V(n) asm volatile("s_waitcnt vmcnt(" #n ")" ::: "memory")
; template <class Epi, class Sched, bool ALIGN_EPI = false, bool SP2 = false>
; __device__ __forceinline__ void gemm_phase(PG8_LAS unsigned char* lds, const Gemm g, const Sched& S, const Epi& E) {
;     ...
;             PG8_LDB(B0, 0, 0); PG8_LDB(B1, 0, 1); PG8_SCHED; PG8_LDA(At, 0, 0); PG8_STAGE(PG8_SA(1, 1), a1 + hstepA, voffA);
;             PG8_WAIT_V(8); PG8_WAIT_L(0); PG8_BAR; PG8_MMA(0, 0, At, B0); PG8_MMA(0, 1, At, B1); PG8_BAR; PG8_SCHED;
;             PG8_LDA(At, 0, 1); PG8_STAGE(PG8_SB(0, 0), b2, voffB); PG8_STAGE(PG8_SB(0, 1), b2 + hstepB, voffB); PG8_STAGE(PG8_SA(0, 0), a2, voffA);
;             PG8_WAIT_V(8); PG8_WAIT_L(0); PG8_BAR; PG8_MMA(1, 0, At, B0); PG8_MMA(1, 1, At, B1); PG8_BAR; PG8_SCHED;
;             PG8_LDB(B0, 1, 0); PG8_LDB(B1, 1, 1); PG8_SCHED; PG8_LDA(At, 1, 0); PG8_STAGE(PG8_SA(0, 1), a2 + hstepA, voffA);
;             PG8_WAIT_V(8); PG8_WAIT_L(0); PG8_BAR; PG8_MMA(0, 0, At, B0); PG8_MMA(0, 1, At, B1); PG8_BAR; PG8_SCHED;
;             PG8_LDA(At, 1, 1); PG8_STAGE(PG8_SB(1, 0), b3, voffB); PG8_STAGE(PG8_SB(1, 1), b3 + hstepB, voffB); PG8_STAGE(PG8_SA(1, 0), a3, voffA);
;             PG8_WAIT_V(8); PG8_WAIT_L(0); PG8_BAR; PG8_MMA(1, 0, At, B0); PG8_MMA(1, 1, At, B1); PG8_BAR; PG8_SCHED;
	s_setprio 1
	s_waitcnt lgkmcnt(0)
	v_mfma_f32_16x16x32_bf16 v[62:65], v[154:157], v[190:193], 0
	v_mfma_f32_16x16x32_bf16 v[62:65], v[158:161], v[194:197], v[62:65]
	v_mfma_f32_16x16x32_bf16 v[58:61], v[166:169], v[194:197], 0
	v_mfma_f32_16x16x32_bf16 v[58:61], v[162:165], v[190:193], v[58:61]
	v_mfma_f32_16x16x32_bf16 v[46:49], v[162:165], v[198:201], 0
	v_mfma_f32_16x16x32_bf16 v[46:49], v[166:169], v[202:205], v[46:49]
	v_mfma_f32_16x16x32_bf16 v[54:57], v[158:161], v[202:205], 0
	v_mfma_f32_16x16x32_bf16 v[54:57], v[154:157], v[198:201], v[54:57]
	v_mfma_f32_16x16x32_bf16 v[38:41], v[154:157], v[206:209], 0
	v_mfma_f32_16x16x32_bf16 v[38:41], v[158:161], v[212:215], v[38:41]
	v_mfma_f32_16x16x32_bf16 v[30:33], v[166:169], v[212:215], 0
	v_mfma_f32_16x16x32_bf16 v[30:33], v[162:165], v[206:209], v[30:33]
	v_mfma_f32_16x16x32_bf16 v[14:17], v[162:165], v[216:219], 0
	v_mfma_f32_16x16x32_bf16 v[14:17], v[166:169], v[220:223], v[14:17]
	v_mfma_f32_16x16x32_bf16 v[22:25], v[158:161], v[220:223], 0
	v_mfma_f32_16x16x32_bf16 v[22:25], v[154:157], v[216:219], v[22:25]
	s_setprio 0
	s_setprio 1
	v_mfma_f32_16x16x32_bf16 v[50:53], v[170:173], v[190:193], 0
	v_mfma_f32_16x16x32_bf16 v[50:53], v[174:177], v[194:197], v[50:53]
	v_mfma_f32_16x16x32_bf16 v[42:45], v[186:189], v[194:197], 0
	v_mfma_f32_16x16x32_bf16 v[42:45], v[182:185], v[190:193], v[42:45]
	v_mfma_f32_16x16x32_bf16 v[26:29], v[182:185], v[198:201], 0
	v_mfma_f32_16x16x32_bf16 v[26:29], v[186:189], v[202:205], v[26:29]
	v_mfma_f32_16x16x32_bf16 v[34:37], v[174:177], v[202:205], 0
	v_mfma_f32_16x16x32_bf16 v[34:37], v[170:173], v[198:201], v[34:37]
	v_mfma_f32_16x16x32_bf16 v[18:21], v[170:173], v[206:209], 0
	v_mfma_f32_16x16x32_bf16 v[18:21], v[174:177], v[212:215], v[18:21]
	v_mfma_f32_16x16x32_bf16 v[10:13], v[186:189], v[212:215], 0
	v_mfma_f32_16x16x32_bf16 v[10:13], v[182:185], v[206:209], v[10:13]
	v_mfma_f32_16x16x32_bf16 v[2:5], v[182:185], v[216:219], 0
	v_mfma_f32_16x16x32_bf16 v[2:5], v[186:189], v[220:223], v[2:5]
	v_mfma_f32_16x16x32_bf16 v[6:9], v[174:177], v[220:223], 0
	v_mfma_f32_16x16x32_bf16 v[6:9], v[170:173], v[216:219], v[6:9]
	s_setprio 0
	s_barrier
	s_add_i32 s33, 0, 0x18000
	v_add_u32_e32 v153, s33, v148
	s_add_i32 s35, 0, 0x1c000
	ds_read_b128 v[154:157], v153
	ds_read_b128 v[158:161], v153 offset:1024
	ds_read_b128 v[162:165], v153 offset:2048
	ds_read_b128 v[166:169], v153 offset:3072
	v_add_u32_e32 v153, s35, v148
	ds_read_b128 v[170:173], v153
	ds_read_b128 v[174:177], v153 offset:1024
	ds_read_b128 v[182:185], v153 offset:2048
	ds_read_b128 v[186:189], v153 offset:3072
	s_add_u32 s36, s58, 0x100000
	s_addc_u32 s37, s59, 0
	s_mov_b32 m0, s16
	v_lshl_add_u64 v[230:231], s[36:37], 0, v[130:131]
	ds_read_b128 v[190:193], v152 offset:32768
	ds_read_b128 v[194:197], v152 offset:33792
	ds_read_b128 v[198:201], v152 offset:34816
	ds_read_b128 v[202:205], v152 offset:35840
	ds_read_b128 v[206:209], v152 offset:36864
	ds_read_b128 v[212:215], v152 offset:37888
	ds_read_b128 v[216:219], v152 offset:38912
	ds_read_b128 v[220:223], v152 offset:39936
	global_load_lds_dwordx4 v[230:231], off
	v_lshl_add_u64 v[230:231], s[36:37], 0, v[134:135]
	s_mov_b32 m0, s17
	s_nop 0
	global_load_lds_dwordx4 v[230:231], off
	s_waitcnt vmcnt(8)
	s_waitcnt lgkmcnt(0)
	s_barrier
	s_setprio 1
	s_waitcnt lgkmcnt(0)
	v_mfma_f32_16x16x32_bf16 v[126:129], v[154:157], v[190:193], v[126:129]
	v_mfma_f32_16x16x32_bf16 v[126:129], v[158:161], v[194:197], v[126:129]
	v_mfma_f32_16x16x32_bf16 v[122:125], v[166:169], v[194:197], v[122:125]
	v_mfma_f32_16x16x32_bf16 v[122:125], v[162:165], v[190:193], v[122:125]
	v_mfma_f32_16x16x32_bf16 v[110:113], v[162:165], v[198:201], v[110:113]
	v_mfma_f32_16x16x32_bf16 v[110:113], v[166:169], v[202:205], v[110:113]
	v_mfma_f32_16x16x32_bf16 v[118:121], v[158:161], v[202:205], v[118:121]
	v_mfma_f32_16x16x32_bf16 v[118:121], v[154:157], v[198:201], v[118:121]
	v_mfma_f32_16x16x32_bf16 v[102:105], v[154:157], v[206:209], v[102:105]
	v_mfma_f32_16x16x32_bf16 v[102:105], v[158:161], v[212:215], v[102:105]
	v_mfma_f32_16x16x32_bf16 v[94:97], v[166:169], v[212:215], v[94:97]
	v_mfma_f32_16x16x32_bf16 v[94:97], v[162:165], v[206:209], v[94:97]
	v_mfma_f32_16x16x32_bf16 v[78:81], v[162:165], v[216:219], v[78:81]
	v_mfma_f32_16x16x32_bf16 v[78:81], v[166:169], v[220:223], v[78:81]
	v_mfma_f32_16x16x32_bf16 v[86:89], v[158:161], v[220:223], v[86:89]
	v_mfma_f32_16x16x32_bf16 v[86:89], v[154:157], v[216:219], v[86:89]
	s_setprio 0
	s_setprio 1
	v_mfma_f32_16x16x32_bf16 v[114:117], v[170:173], v[190:193], v[114:117]
	v_mfma_f32_16x16x32_bf16 v[114:117], v[174:177], v[194:197], v[114:117]
	v_mfma_f32_16x16x32_bf16 v[106:109], v[186:189], v[194:197], v[106:109]
	v_mfma_f32_16x16x32_bf16 v[106:109], v[182:185], v[190:193], v[106:109]
	v_mfma_f32_16x16x32_bf16 v[90:93], v[182:185], v[198:201], v[90:93]
	v_mfma_f32_16x16x32_bf16 v[90:93], v[186:189], v[202:205], v[90:93]
	v_mfma_f32_16x16x32_bf16 v[98:101], v[174:177], v[202:205], v[98:101]
	v_mfma_f32_16x16x32_bf16 v[98:101], v[170:173], v[198:201], v[98:101]
	v_mfma_f32_16x16x32_bf16 v[82:85], v[170:173], v[206:209], v[82:85]
	v_mfma_f32_16x16x32_bf16 v[82:85], v[174:177], v[212:215], v[82:85]
	v_mfma_f32_16x16x32_bf16 v[74:77], v[186:189], v[212:215], v[74:77]
	v_mfma_f32_16x16x32_bf16 v[74:77], v[182:185], v[206:209], v[74:77]
	v_mfma_f32_16x16x32_bf16 v[66:69], v[182:185], v[216:219], v[66:69]
	v_mfma_f32_16x16x32_bf16 v[66:69], v[186:189], v[220:223], v[66:69]
	v_mfma_f32_16x16x32_bf16 v[70:73], v[174:177], v[220:223], v[70:73]
	v_mfma_f32_16x16x32_bf16 v[70:73], v[170:173], v[216:219], v[70:73]
	s_setprio 0
	s_barrier
; #define PG8_STAGE(bufoff, gbase, voff) do { _Pragma("unroll") for (int _i = 0; _i < 2; ++_i) \
;         __builtin_amdgcn_global_load_lds((const unsigned*)((const char*)(gbase) + (voff)[_i]), (PG8_LAS unsigned*)(lds + (bufoff) + ldsw + _i * 8192), 16, 0, 0); } while (0)
; #define PG8_LDA(dst, b, h) do { _Pragma("unroll") for (int m = 0; m < 4; ++m) _Pragma("unroll") for (int k = 0; k < 2; ++k) dst[m][k] = *(const PG8_LAS bf16x8*)(lds + PG8_SA(b, h) + aoff + m * 2048 + k * 1024); } while (0)
; #define PG8_MMA(ai, bj, At, Bt) do { __builtin_amdgcn_s_setprio(1); _Pragma("unroll") for (int m = 0; m < 4; ++m) _Pragma("unroll") for (int n = 0; n < 2; ++n) _Pragma("unroll") for (int k = 0; k < 2; ++k) \
;         acc[ai][bj][m][n] = mma16(Bt[n][k], At[m][k], acc[ai][bj][m][n]); __builtin_amdgcn_s_setprio(0); } while (0)
; #define PG8_WAIT_V(n) asm volatile("s_waitcnt vmcnt(" #n ")" ::: "memory")
; #define PG8_WAIT_L(n) asm volatile("s_waitcnt lgkmcnt(" #n ")" ::: "memory")
; #define PG8_BAR __builtin_amdgcn_s_barrier()
; #define PG8_SCHED __builtin_amdgcn_sched_barrier(0)
; template <class Epi, class Sched, bool ALIGN_EPI = false, bool SP2 = false>
; __device__ __forceinline__ void gemm_phase(PG8_LAS unsigned char* lds, const Gemm g, const Sched& S, const Epi& E) {
;     ...
;             PG8_LDA(At, 1, 1); PG8_STAGE(PG8_SB(1, 0), b3, voffB); PG8_STAGE(PG8_SB(1, 1), b3 + hstepB, voffB); PG8_STAGE(PG8_SA(1, 0), a3, voffA);
;             PG8_WAIT_V(8); PG8_WAIT_L(0); PG8_BAR; PG8_MMA(1, 0, At, B0); PG8_MMA(1, 1, At, B1); PG8_BAR; PG8_SCHED;
	s_add_i32 s33, s33, s7
	v_lshl_add_u64 v[146:147], v[146:147], 0, s[38:39]
	s_mov_b32 m0, s33
	ds_read_b128 v[190:193], v152 offset:49152
	ds_read_b128 v[194:197], v152 offset:50176
	ds_read_b128 v[198:201], v152 offset:51200
	ds_read_b128 v[202:205], v152 offset:52224
	ds_read_b128 v[206:209], v152 offset:53248
	ds_read_b128 v[212:215], v152 offset:54272
	ds_read_b128 v[216:219], v152 offset:55296
	ds_read_b128 v[220:223], v152 offset:56320
	global_load_lds_dwordx4 v[146:147], off
	s_add_i32 m0, s33, 0x2000
	s_add_u32 s36, s54, 0x40080
	v_lshl_add_u64 v[146:147], v[224:225], 0, s[38:39]
	s_addc_u32 s37, s55, 0
	s_add_i32 s33, s35, s7
	global_load_lds_dwordx4 v[146:147], off
	v_lshl_add_u64 v[146:147], s[36:37], 0, v[132:133]
	s_mov_b32 m0, s33
	s_nop 0
	global_load_lds_dwordx4 v[146:147], off
	v_lshl_add_u64 v[146:147], s[36:37], 0, v[136:137]
	s_add_i32 m0, s33, 0x2000
	s_nop 0
	global_load_lds_dwordx4 v[146:147], off
	v_lshl_add_u64 v[146:147], v[226:227], 0, s[38:39]
	s_mov_b32 m0, s19
	s_nop 0
	global_load_lds_dwordx4 v[146:147], off
	v_lshl_add_u64 v[146:147], v[228:229], 0, s[38:39]
	s_mov_b32 m0, s20
	s_nop 0
	global_load_lds_dwordx4 v[146:147], off
	s_waitcnt vmcnt(8)
	s_waitcnt lgkmcnt(0)
	s_barrier
	s_setprio 1
	s_waitcnt lgkmcnt(0)
	v_mfma_f32_16x16x32_bf16 v[62:65], v[154:157], v[190:193], v[62:65]
	v_mfma_f32_16x16x32_bf16 v[62:65], v[158:161], v[194:197], v[62:65]
	v_mfma_f32_16x16x32_bf16 v[58:61], v[166:169], v[194:197], v[58:61]
	v_mfma_f32_16x16x32_bf16 v[58:61], v[162:165], v[190:193], v[58:61]
	v_mfma_f32_16x16x32_bf16 v[46:49], v[162:165], v[198:201], v[46:49]
	v_mfma_f32_16x16x32_bf16 v[46:49], v[166:169], v[202:205], v[46:49]
	v_mfma_f32_16x16x32_bf16 v[54:57], v[158:161], v[202:205], v[54:57]
	v_mfma_f32_16x16x32_bf16 v[54:57], v[154:157], v[198:201], v[54:57]
	v_mfma_f32_16x16x32_bf16 v[38:41], v[154:157], v[206:209], v[38:41]
	v_mfma_f32_16x16x32_bf16 v[38:41], v[158:161], v[212:215], v[38:41]
	v_mfma_f32_16x16x32_bf16 v[30:33], v[166:169], v[212:215], v[30:33]
	v_mfma_f32_16x16x32_bf16 v[30:33], v[162:165], v[206:209], v[30:33]
	v_mfma_f32_16x16x32_bf16 v[14:17], v[162:165], v[216:219], v[14:17]
	v_mfma_f32_16x16x32_bf16 v[14:17], v[166:169], v[220:223], v[14:17]
	v_mfma_f32_16x16x32_bf16 v[22:25], v[158:161], v[220:223], v[22:25]
	v_mfma_f32_16x16x32_bf16 v[22:25], v[154:157], v[216:219], v[22:25]
	s_setprio 0
	s_setprio 1
	v_mfma_f32_16x16x32_bf16 v[50:53], v[170:173], v[190:193], v[50:53]
	v_mfma_f32_16x16x32_bf16 v[50:53], v[174:177], v[194:197], v[50:53]
	v_mfma_f32_16x16x32_bf16 v[42:45], v[186:189], v[194:197], v[42:45]
	v_mfma_f32_16x16x32_bf16 v[42:45], v[182:185], v[190:193], v[42:45]
	v_mfma_f32_16x16x32_bf16 v[26:29], v[182:185], v[198:201], v[26:29]
	v_mfma_f32_16x16x32_bf16 v[26:29], v[186:189], v[202:205], v[26:29]
	v_mfma_f32_16x16x32_bf16 v[34:37], v[174:177], v[202:205], v[34:37]
	v_mfma_f32_16x16x32_bf16 v[34:37], v[170:173], v[198:201], v[34:37]
	v_mfma_f32_16x16x32_bf16 v[18:21], v[170:173], v[206:209], v[18:21]
	v_mfma_f32_16x16x32_bf16 v[18:21], v[174:177], v[212:215], v[18:21]
	v_mfma_f32_16x16x32_bf16 v[10:13], v[186:189], v[212:215], v[10:13]
	v_mfma_f32_16x16x32_bf16 v[10:13], v[182:185], v[206:209], v[10:13]
	v_mfma_f32_16x16x32_bf16 v[2:5], v[182:185], v[216:219], v[2:5]
	v_mfma_f32_16x16x32_bf16 v[2:5], v[186:189], v[220:223], v[2:5]
	v_mfma_f32_16x16x32_bf16 v[6:9], v[174:177], v[220:223], v[6:9]
	v_mfma_f32_16x16x32_bf16 v[6:9], v[170:173], v[216:219], v[6:9]
	s_setprio 0
	s_barrier
	s_add_i32 s29, s29, 2
	s_add_u32 s0, s0, 0x100
	s_addc_u32 s1, s1, 0
	s_add_u32 s27, s27, 0x100
	s_addc_u32 s28, s28, 0

; #define PG8_STAGE(bufoff, gbase, voff) do { _Pragma("unroll") for (int _i = 0; _i < 2; ++_i) \
;         __builtin_amdgcn_global_load_lds((const unsigned*)((const char*)(gbase) + (voff)[_i]), (PG8_LAS unsigned*)(lds + (bufoff) + ldsw + _i * 8192), 16, 0, 0); } while (0)
; #define PG8_LDA(dst, b, h) do { _Pragma("unroll") for (int m = 0; m < 4; ++m) _Pragma("unroll") for (int k = 0; k < 2; ++k) dst[m][k] = *(const PG8_LAS bf16x8*)(lds + PG8_SA(b, h) + aoff + m * 2048 + k * 1024); } while (0)
; #define PG8_BAR __builtin_amdgcn_s_barrier()
; template <class Epi, class Sched, bool ALIGN_EPI = false, bool SP2 = false>
; __device__ __forceinline__ void gemm_phase(PG8_LAS unsigned char* lds, const Gemm g, const Sched& S, const Epi& E) {
;     ...
;         const bool has_next = S.next(ui + 1, nxt);
;         const char* nA = has_next ? PG8_ABASE(nxt) : cA; const char* nB = has_next ? PG8_BBASE(nxt) : cB;
; #pragma unroll 1
;         for (int t = 0; t < nt; t += 2) {
;             const bool last = (t == nt - 2);
;             const char* a1 = cA + (size_t)(t + 1) * kstep;
;             const char* a2 = last ? nA : cA + (size_t)(t + 2) * kstep; const char* b2 = last ? nB : cB + (size_t)(t + 2) * kstep;
;             const char* a3 = a2 + kstep; const char* b3 = b2 + kstep;
;             if (last && has_next) S.a_ready(nxt);
;             if constexpr (SP2) {
;             PG8_LDB(B0, 0, 0); PG8_LDB(B1, 0, 1); PG8_SCHED; PG8_LDA(At, 0, 0); PG8_STAGE(PG8_SA(1, 1), a1 + hstepA, voffA);
;             PG8_WAIT_V(8); PG8_WAIT_L(0); PG8_BAR; PG8_MMA(0, 0, At, B0); PG8_MMA(0, 1, At, B1); PG8_BAR; PG8_SCHED;
;             PG8_LDA(At, 0, 1); PG8_STAGE(PG8_SB(0, 0), b2, voffB); PG8_STAGE(PG8_SB(0, 1), b2 + hstepB, voffB); PG8_STAGE(PG8_SA(0, 0), a2, voffA);
;             PG8_WAIT_V(8); PG8_WAIT_L(0); PG8_BAR; PG8_MMA(1, 0, At, B0); PG8_MMA(1, 1, At, B1); PG8_BAR; PG8_SCHED;
;             PG8_LDB(B0, 1, 0); PG8_LDB(B1, 1, 1); PG8_SCHED; PG8_LDA(At, 1, 0); PG8_STAGE(PG8_SA(0, 1), a2 + hstepA, voffA);
;             PG8_WAIT_V(8); PG8_WAIT_L(0); PG8_BAR; PG8_MMA(0, 0, At, B0); PG8_MMA(0, 1, At, B1); PG8_BAR; PG8_SCHED;
;             PG8_LDA(At, 1, 1); PG8_STAGE(PG8_SB(1, 0), b3, voffB); PG8_STAGE(PG8_SB(1, 1), b3 + hstepB, voffB); PG8_STAGE(PG8_SA(1, 0), a3, voffA);
;             PG8_WAIT_V(8); PG8_WAIT_L(0); PG8_BAR; PG8_MMA(1, 0, At, B0); PG8_MMA(1, 1, At, B1); PG8_BAR; PG8_SCHED;
.LBB0_554:
	s_ashr_i32 s55, s54, 31
	s_lshl_b64 s[28:29], s[54:55], 20
	s_add_u32 s1, s14, s28
	s_addc_u32 s33, s15, s29
	s_ashr_i32 s28, s0, 30
	s_ashr_i32 s29, s28, 31
	s_lshl_b64 s[28:29], s[28:29], 12
	s_add_u32 s56, s1, s28
	s_addc_u32 s57, s33, s29
	s_and_b64 s[28:29], s[4:5], exec
	s_cselect_b32 s28, s57, s63
	s_cselect_b32 s29, s56, s62
	s_ashr_i32 s1, s0, 31
	s_lshl_b64 s[36:37], s[0:1], 20
	s_add_u32 s58, s74, s36
	s_addc_u32 s59, s75, s37
	s_and_b64 s[36:37], s[4:5], exec
	s_cselect_b32 s33, s59, s65
	s_cselect_b32 s35, s58, s64
	s_add_u32 s62, s62, 0x80080
	s_addc_u32 s63, s63, 0
	s_add_u32 s36, s64, 0x100
	s_addc_u32 s37, s65, 0
	s_mov_b32 s46, -2
	ds_read_b128 v[82:85], v181
	ds_read_b128 v[86:89], v181 offset:1024
	ds_read_b128 v[138:141], v181 offset:2048
	ds_read_b128 v[142:145], v181 offset:3072
	ds_read_b128 v[146:149], v213
	ds_read_b128 v[150:153], v213 offset:1024
	ds_read_b128 v[154:157], v213 offset:2048
	ds_read_b128 v[158:161], v213 offset:3072
	s_add_u32 s47, s62, 0xfff80080
	s_addc_u32 s61, s63, -1
	s_cmp_eq_u32 s46, 28
	s_cselect_b32 s67, s28, s61
	s_cselect_b32 s66, s29, s47
	s_cselect_b32 s65, s33, s37
	s_cselect_b32 s64, s35, s36
	v_lshl_add_u64 v[194:195], s[62:63], 0, v[174:175]
	s_add_i32 m0, s11, 0xc000
	ds_read_b128 v[186:189], v214
	ds_read_b128 v[190:193], v214 offset:1024
	ds_read_b128 v[216:219], v214 offset:2048
	ds_read_b128 v[220:223], v214 offset:3072
	ds_read_b128 v[224:227], v214 offset:4096
	ds_read_b128 v[228:231], v214 offset:5120
	ds_read_b128 v[232:235], v214 offset:6144
	ds_read_b128 v[236:239], v214 offset:7168
	global_load_lds_dwordx4 v[194:195], off
	v_lshl_add_u64 v[194:195], s[62:63], 0, v[176:177]
	s_add_i32 m0, s11, 0xe000
	s_nop 0
	global_load_lds_dwordx4 v[194:195], off
	s_waitcnt vmcnt(8)
	s_waitcnt lgkmcnt(0)
	s_barrier
	s_setprio 1
	s_waitcnt lgkmcnt(0)
	v_mfma_i32_16x16x64_i8 v[70:73], v[82:85], v[186:189], 0
	v_mfma_i32_16x16x64_i8 v[70:73], v[86:89], v[190:193], v[70:73]
	v_mfma_i32_16x16x64_i8 v[66:69], v[142:145], v[190:193], 0
	v_mfma_i32_16x16x64_i8 v[66:69], v[138:141], v[186:189], v[66:69]
	v_mfma_i32_16x16x64_i8 v[122:125], v[138:141], v[216:219], 0
	v_mfma_i32_16x16x64_i8 v[122:125], v[142:145], v[220:223], v[122:125]
	v_mfma_i32_16x16x64_i8 v[126:129], v[86:89], v[220:223], 0
	v_mfma_i32_16x16x64_i8 v[126:129], v[82:85], v[216:219], v[126:129]
	v_mfma_i32_16x16x64_i8 v[110:113], v[82:85], v[224:227], 0
	v_mfma_i32_16x16x64_i8 v[110:113], v[86:89], v[228:231], v[110:113]
	v_mfma_i32_16x16x64_i8 v[106:109], v[142:145], v[228:231], 0
	v_mfma_i32_16x16x64_i8 v[106:109], v[138:141], v[224:227], v[106:109]
	v_mfma_i32_16x16x64_i8 v[90:93], v[138:141], v[232:235], 0
	v_mfma_i32_16x16x64_i8 v[90:93], v[142:145], v[236:239], v[90:93]
	v_mfma_i32_16x16x64_i8 v[94:97], v[86:89], v[236:239], 0
	v_mfma_i32_16x16x64_i8 v[94:97], v[82:85], v[232:235], v[94:97]
	s_setprio 0
	s_setprio 1
	v_mfma_i32_16x16x64_i8 v[134:137], v[146:149], v[186:189], 0
	v_mfma_i32_16x16x64_i8 v[134:137], v[150:153], v[190:193], v[134:137]
	v_mfma_i32_16x16x64_i8 v[130:133], v[158:161], v[190:193], 0
	v_mfma_i32_16x16x64_i8 v[130:133], v[154:157], v[186:189], v[130:133]
	v_mfma_i32_16x16x64_i8 v[114:117], v[154:157], v[216:219], 0
	v_mfma_i32_16x16x64_i8 v[114:117], v[158:161], v[220:223], v[114:117]
	v_mfma_i32_16x16x64_i8 v[118:121], v[150:153], v[220:223], 0
	v_mfma_i32_16x16x64_i8 v[118:121], v[146:149], v[216:219], v[118:121]
	v_mfma_i32_16x16x64_i8 v[102:105], v[146:149], v[224:227], 0
	v_mfma_i32_16x16x64_i8 v[102:105], v[150:153], v[228:231], v[102:105]
	v_mfma_i32_16x16x64_i8 v[98:101], v[158:161], v[228:231], 0
	v_mfma_i32_16x16x64_i8 v[98:101], v[154:157], v[224:227], v[98:101]
	v_mfma_i32_16x16x64_i8 v[74:77], v[154:157], v[232:235], 0
	v_mfma_i32_16x16x64_i8 v[74:77], v[158:161], v[236:239], v[74:77]
	v_mfma_i32_16x16x64_i8 v[78:81], v[150:153], v[236:239], 0
	v_mfma_i32_16x16x64_i8 v[78:81], v[146:149], v[232:235], v[78:81]
	s_setprio 0
	s_barrier
	s_add_i32 s47, s23, s7
	v_lshl_add_u64 v[194:195], s[64:65], 0, v[164:165]
	s_mov_b32 m0, s47
	ds_read_b128 v[186:189], v214 offset:16384
	ds_read_b128 v[190:193], v214 offset:17408
	ds_read_b128 v[216:219], v214 offset:18432
	ds_read_b128 v[220:223], v214 offset:19456
	ds_read_b128 v[224:227], v214 offset:20480
	ds_read_b128 v[228:231], v214 offset:21504
	ds_read_b128 v[232:235], v214 offset:22528
	ds_read_b128 v[236:239], v214 offset:23552
	global_load_lds_dwordx4 v[194:195], off
	s_add_i32 m0, s47, 0x2000
	s_add_u32 s68, s64, 0x80000
	v_lshl_add_u64 v[240:241], s[64:65], 0, v[168:169]
	s_addc_u32 s69, s65, 0
	s_add_i32 s47, s24, s7
	global_load_lds_dwordx4 v[240:241], off
	v_lshl_add_u64 v[242:243], s[68:69], 0, v[164:165]
	s_mov_b32 m0, s47
	v_lshl_add_u64 v[244:245], s[66:67], 0, v[166:167]
	global_load_lds_dwordx4 v[242:243], off
	v_lshl_add_u64 v[242:243], s[68:69], 0, v[168:169]
	s_add_i32 m0, s47, 0x2000
	s_nop 0
	global_load_lds_dwordx4 v[242:243], off
	v_lshl_add_u64 v[242:243], s[66:67], 0, v[162:163]
	s_mov_b32 m0, s11
	s_nop 0
	global_load_lds_dwordx4 v[242:243], off
	s_mov_b32 m0, s12
	s_nop 0
	global_load_lds_dwordx4 v[244:245], off
	s_waitcnt vmcnt(8)
	s_waitcnt lgkmcnt(0)
	s_barrier
; #define PG8_STAGE(bufoff, gbase, voff) do { _Pragma("unroll") for (int _i = 0; _i < 2; ++_i) \
;         __builtin_amdgcn_global_load_lds((const unsigned*)((const char*)(gbase) + (voff)[_i]), (PG8_LAS unsigned*)(lds + (bufoff) + ldsw + _i * 8192), 16, 0, 0); } while (0)
; #define PG8_LDA(dst, b, h) do { _Pragma("unroll") for (int m = 0; m < 4; ++m) _Pragma("unroll") for (int k = 0; k < 2; ++k) dst[m][k] = *(const PG8_LAS bf16x8*)(lds + PG8_SA(b, h) + aoff + m * 2048 + k * 1024); } while (0)
; #define PG8_LDB(dst, b, h) do { _Pragma("unroll") for (int n = 0; n < 2; ++n) _Pragma("unroll") for (int k = 0; k < 2; ++k) dst[n][k] = *(const PG8_LAS bf16x8*)(lds + PG8_SB(b, h) + boff + n * 2048 + k * 1024); } while (0)
; #define PG8_MMA(ai, bj, At, Bt) do { __builtin_amdgcn_s_setprio(1); _Pragma("unroll") for (int m = 0; m < 4; ++m) _Pragma("unroll") for (int n = 0; n < 2; ++n) _Pragma("unroll") for (int k = 0; k < 2; ++k) \
;         acc[ai][bj][m][n] = mma16(Bt[n][k], At[m][k], acc[ai][bj][m][n]); __builtin_amdgcn_s_setprio(0); } while (0)
; #define PG8_WAIT_V(n) asm volatile("s_waitcnt vmcnt(" #n ")" ::: "memory")
; template <class Epi, class Sched, bool ALIGN_EPI = false, bool SP2 = false>
; __device__ __forceinline__ void gemm_phase(PG8_LAS unsigned char* lds, const Gemm g, const Sched& S, const Epi& E) {
;     ...
;             PG8_LDB(B0, 0, 0); PG8_LDB(B1, 0, 1); PG8_SCHED; PG8_LDA(At, 0, 0); PG8_STAGE(PG8_SA(1, 1), a1 + hstepA, voffA);
;             PG8_WAIT_V(8); PG8_WAIT_L(0); PG8_BAR; PG8_MMA(0, 0, At, B0); PG8_MMA(0, 1, At, B1); PG8_BAR; PG8_SCHED;
;             PG8_LDA(At, 0, 1); PG8_STAGE(PG8_SB(0, 0), b2, voffB); PG8_STAGE(PG8_SB(0, 1), b2 + hstepB, voffB); PG8_STAGE(PG8_SA(0, 0), a2, voffA);
;             PG8_WAIT_V(8); PG8_WAIT_L(0); PG8_BAR; PG8_MMA(1, 0, At, B0); PG8_MMA(1, 1, At, B1); PG8_BAR; PG8_SCHED;
;             PG8_LDB(B0, 1, 0); PG8_LDB(B1, 1, 1); PG8_SCHED; PG8_LDA(At, 1, 0); PG8_STAGE(PG8_SA(0, 1), a2 + hstepA, voffA);
;             PG8_WAIT_V(8); PG8_WAIT_L(0); PG8_BAR; PG8_MMA(0, 0, At, B0); PG8_MMA(0, 1, At, B1); PG8_BAR; PG8_SCHED;
;             PG8_LDA(At, 1, 1); PG8_STAGE(PG8_SB(1, 0), b3, voffB); PG8_STAGE(PG8_SB(1, 1), b3 + hstepB, voffB); PG8_STAGE(PG8_SA(1, 0), a3, voffA);
;             PG8_WAIT_V(8); PG8_WAIT_L(0); PG8_BAR; PG8_MMA(1, 0, At, B0); PG8_MMA(1, 1, At, B1); PG8_BAR; PG8_SCHED;
	s_setprio 1
	s_waitcnt lgkmcnt(0)
	v_mfma_i32_16x16x64_i8 v[62:65], v[82:85], v[186:189], 0
	v_mfma_i32_16x16x64_i8 v[62:65], v[86:89], v[190:193], v[62:65]
	v_mfma_i32_16x16x64_i8 v[58:61], v[142:145], v[190:193], 0
	v_mfma_i32_16x16x64_i8 v[58:61], v[138:141], v[186:189], v[58:61]
	v_mfma_i32_16x16x64_i8 v[42:45], v[138:141], v[216:219], 0
	v_mfma_i32_16x16x64_i8 v[42:45], v[142:145], v[220:223], v[42:45]
	v_mfma_i32_16x16x64_i8 v[46:49], v[86:89], v[220:223], 0
	v_mfma_i32_16x16x64_i8 v[46:49], v[82:85], v[216:219], v[46:49]
	v_mfma_i32_16x16x64_i8 v[30:33], v[82:85], v[224:227], 0
	v_mfma_i32_16x16x64_i8 v[30:33], v[86:89], v[228:231], v[30:33]
	v_mfma_i32_16x16x64_i8 v[26:29], v[142:145], v[228:231], 0
	v_mfma_i32_16x16x64_i8 v[26:29], v[138:141], v[224:227], v[26:29]
	v_mfma_i32_16x16x64_i8 v[10:13], v[138:141], v[232:235], 0
	v_mfma_i32_16x16x64_i8 v[10:13], v[142:145], v[236:239], v[10:13]
	v_mfma_i32_16x16x64_i8 v[14:17], v[86:89], v[236:239], 0
	v_mfma_i32_16x16x64_i8 v[14:17], v[82:85], v[232:235], v[14:17]
	s_setprio 0
	s_setprio 1
	v_mfma_i32_16x16x64_i8 v[54:57], v[146:149], v[186:189], 0
	v_mfma_i32_16x16x64_i8 v[54:57], v[150:153], v[190:193], v[54:57]
	v_mfma_i32_16x16x64_i8 v[50:53], v[158:161], v[190:193], 0
	v_mfma_i32_16x16x64_i8 v[50:53], v[154:157], v[186:189], v[50:53]
	v_mfma_i32_16x16x64_i8 v[34:37], v[154:157], v[216:219], 0
	v_mfma_i32_16x16x64_i8 v[34:37], v[158:161], v[220:223], v[34:37]
	v_mfma_i32_16x16x64_i8 v[38:41], v[150:153], v[220:223], 0
	v_mfma_i32_16x16x64_i8 v[38:41], v[146:149], v[216:219], v[38:41]
	v_mfma_i32_16x16x64_i8 v[22:25], v[146:149], v[224:227], 0
	v_mfma_i32_16x16x64_i8 v[22:25], v[150:153], v[228:231], v[22:25]
	v_mfma_i32_16x16x64_i8 v[18:21], v[158:161], v[228:231], 0
	v_mfma_i32_16x16x64_i8 v[18:21], v[154:157], v[224:227], v[18:21]
	v_mfma_i32_16x16x64_i8 v[2:5], v[154:157], v[232:235], 0
	v_mfma_i32_16x16x64_i8 v[2:5], v[158:161], v[236:239], v[2:5]
	v_mfma_i32_16x16x64_i8 v[6:9], v[150:153], v[236:239], 0
	v_mfma_i32_16x16x64_i8 v[6:9], v[146:149], v[232:235], v[6:9]
	s_setprio 0
	s_barrier
	s_add_i32 s47, 0, 0x18000
	s_add_i32 s61, 0, 0x1c000
	v_add_u32_e32 v142, s47, v209
	v_add_u32_e32 v158, s61, v209
	ds_read_b128 v[82:85], v142
	ds_read_b128 v[86:89], v142 offset:1024
	ds_read_b128 v[138:141], v142 offset:2048
	ds_read_b128 v[142:145], v142 offset:3072
	ds_read_b128 v[146:149], v158
	ds_read_b128 v[150:153], v158 offset:1024
	ds_read_b128 v[154:157], v158 offset:2048
	ds_read_b128 v[158:161], v158 offset:3072
	s_add_u32 s66, s66, 0x80000
	s_addc_u32 s67, s67, 0
	s_mov_b32 m0, s13
	v_lshl_add_u64 v[246:247], s[66:67], 0, v[162:163]
	ds_read_b128 v[186:189], v214 offset:32768
	ds_read_b128 v[190:193], v214 offset:33792
	ds_read_b128 v[216:219], v214 offset:34816
	ds_read_b128 v[220:223], v214 offset:35840
	ds_read_b128 v[224:227], v214 offset:36864
	ds_read_b128 v[228:231], v214 offset:37888
	ds_read_b128 v[232:235], v214 offset:38912
	ds_read_b128 v[236:239], v214 offset:39936
	global_load_lds_dwordx4 v[246:247], off
	v_lshl_add_u64 v[246:247], s[66:67], 0, v[166:167]
	s_mov_b32 m0, s16
	s_nop 0
	global_load_lds_dwordx4 v[246:247], off
	s_waitcnt vmcnt(8)
	s_waitcnt lgkmcnt(0)
	s_barrier
	s_setprio 1
	s_waitcnt lgkmcnt(0)
	v_mfma_i32_16x16x64_i8 v[70:73], v[82:85], v[186:189], v[70:73]
	v_mfma_i32_16x16x64_i8 v[70:73], v[86:89], v[190:193], v[70:73]
	v_mfma_i32_16x16x64_i8 v[66:69], v[142:145], v[190:193], v[66:69]
	v_mfma_i32_16x16x64_i8 v[66:69], v[138:141], v[186:189], v[66:69]
	v_mfma_i32_16x16x64_i8 v[122:125], v[138:141], v[216:219], v[122:125]
	v_mfma_i32_16x16x64_i8 v[122:125], v[142:145], v[220:223], v[122:125]
	v_mfma_i32_16x16x64_i8 v[126:129], v[86:89], v[220:223], v[126:129]
	v_mfma_i32_16x16x64_i8 v[126:129], v[82:85], v[216:219], v[126:129]
	v_mfma_i32_16x16x64_i8 v[110:113], v[82:85], v[224:227], v[110:113]
	v_mfma_i32_16x16x64_i8 v[110:113], v[86:89], v[228:231], v[110:113]
	v_mfma_i32_16x16x64_i8 v[106:109], v[142:145], v[228:231], v[106:109]
	v_mfma_i32_16x16x64_i8 v[106:109], v[138:141], v[224:227], v[106:109]
	v_mfma_i32_16x16x64_i8 v[90:93], v[138:141], v[232:235], v[90:93]
	v_mfma_i32_16x16x64_i8 v[90:93], v[142:145], v[236:239], v[90:93]
	v_mfma_i32_16x16x64_i8 v[94:97], v[86:89], v[236:239], v[94:97]
	v_mfma_i32_16x16x64_i8 v[94:97], v[82:85], v[232:235], v[94:97]
	s_setprio 0
	s_setprio 1
	v_mfma_i32_16x16x64_i8 v[134:137], v[146:149], v[186:189], v[134:137]
	v_mfma_i32_16x16x64_i8 v[134:137], v[150:153], v[190:193], v[134:137]
	v_mfma_i32_16x16x64_i8 v[130:133], v[158:161], v[190:193], v[130:133]
	v_mfma_i32_16x16x64_i8 v[130:133], v[154:157], v[186:189], v[130:133]
	v_mfma_i32_16x16x64_i8 v[114:117], v[154:157], v[216:219], v[114:117]
	v_mfma_i32_16x16x64_i8 v[114:117], v[158:161], v[220:223], v[114:117]
	v_mfma_i32_16x16x64_i8 v[118:121], v[150:153], v[220:223], v[118:121]
	v_mfma_i32_16x16x64_i8 v[118:121], v[146:149], v[216:219], v[118:121]
	v_mfma_i32_16x16x64_i8 v[102:105], v[146:149], v[224:227], v[102:105]
	v_mfma_i32_16x16x64_i8 v[102:105], v[150:153], v[228:231], v[102:105]
	v_mfma_i32_16x16x64_i8 v[98:101], v[158:161], v[228:231], v[98:101]
	v_mfma_i32_16x16x64_i8 v[98:101], v[154:157], v[224:227], v[98:101]
	v_mfma_i32_16x16x64_i8 v[74:77], v[154:157], v[232:235], v[74:77]
	v_mfma_i32_16x16x64_i8 v[74:77], v[158:161], v[236:239], v[74:77]
	v_mfma_i32_16x16x64_i8 v[78:81], v[150:153], v[236:239], v[78:81]
	v_mfma_i32_16x16x64_i8 v[78:81], v[146:149], v[232:235], v[78:81]
	s_setprio 0
	s_barrier
; #define PG8_STAGE(bufoff, gbase, voff) do { _Pragma("unroll") for (int _i = 0; _i < 2; ++_i) \
;         __builtin_amdgcn_global_load_lds((const unsigned*)((const char*)(gbase) + (voff)[_i]), (PG8_LAS unsigned*)(lds + (bufoff) + ldsw + _i * 8192), 16, 0, 0); } while (0)
; #define PG8_LDA(dst, b, h) do { _Pragma("unroll") for (int m = 0; m < 4; ++m) _Pragma("unroll") for (int k = 0; k < 2; ++k) dst[m][k] = *(const PG8_LAS bf16x8*)(lds + PG8_SA(b, h) + aoff + m * 2048 + k * 1024); } while (0)
; #define PG8_MMA(ai, bj, At, Bt) do { __builtin_amdgcn_s_setprio(1); _Pragma("unroll") for (int m = 0; m < 4; ++m) _Pragma("unroll") for (int n = 0; n < 2; ++n) _Pragma("unroll") for (int k = 0; k < 2; ++k) \
;         acc[ai][bj][m][n] = mma16(Bt[n][k], At[m][k], acc[ai][bj][m][n]); __builtin_amdgcn_s_setprio(0); } while (0)
; #define PG8_WAIT_V(n) asm volatile("s_waitcnt vmcnt(" #n ")" ::: "memory")
; #define PG8_WAIT_L(n) asm volatile("s_waitcnt lgkmcnt(" #n ")" ::: "memory")
; #define PG8_BAR __builtin_amdgcn_s_barrier()
; #define PG8_SCHED __builtin_amdgcn_sched_barrier(0)
; template <class Epi, class Sched, bool ALIGN_EPI = false, bool SP2 = false>
; __device__ __forceinline__ void gemm_phase(PG8_LAS unsigned char* lds, const Gemm g, const Sched& S, const Epi& E) {
;     ...
;             PG8_LDA(At, 1, 1); PG8_STAGE(PG8_SB(1, 0), b3, voffB); PG8_STAGE(PG8_SB(1, 1), b3 + hstepB, voffB); PG8_STAGE(PG8_SA(1, 0), a3, voffA);
;             PG8_WAIT_V(8); PG8_WAIT_L(0); PG8_BAR; PG8_MMA(1, 0, At, B0); PG8_MMA(1, 1, At, B1); PG8_BAR; PG8_SCHED;
	s_add_i32 s47, s47, s7
	v_lshl_add_u64 v[194:195], v[194:195], 0, s[50:51]
	s_mov_b32 m0, s47
	ds_read_b128 v[186:189], v214 offset:49152
	ds_read_b128 v[190:193], v214 offset:50176
	ds_read_b128 v[216:219], v214 offset:51200
	ds_read_b128 v[220:223], v214 offset:52224
	ds_read_b128 v[224:227], v214 offset:53248
	ds_read_b128 v[228:231], v214 offset:54272
	ds_read_b128 v[232:235], v214 offset:55296
	ds_read_b128 v[236:239], v214 offset:56320
	global_load_lds_dwordx4 v[194:195], off
	s_add_i32 m0, s47, 0x2000
	s_add_u32 s64, s64, 0x80080
	v_lshl_add_u64 v[194:195], v[240:241], 0, s[50:51]
	s_addc_u32 s65, s65, 0
	s_add_i32 s47, s61, s7
	global_load_lds_dwordx4 v[194:195], off
	v_lshl_add_u64 v[194:195], s[64:65], 0, v[164:165]
	s_mov_b32 m0, s47
	s_nop 0
	global_load_lds_dwordx4 v[194:195], off
	v_lshl_add_u64 v[194:195], s[64:65], 0, v[168:169]
	s_add_i32 m0, s47, 0x2000
	s_nop 0
	global_load_lds_dwordx4 v[194:195], off
	v_lshl_add_u64 v[194:195], v[242:243], 0, s[50:51]
	s_mov_b32 m0, s19
	s_nop 0
	global_load_lds_dwordx4 v[194:195], off
	v_lshl_add_u64 v[194:195], v[244:245], 0, s[50:51]
	s_mov_b32 m0, s20
	s_nop 0
	global_load_lds_dwordx4 v[194:195], off
	s_waitcnt vmcnt(8)
	s_waitcnt lgkmcnt(0)
	s_barrier
	s_setprio 1
	s_waitcnt lgkmcnt(0)
	v_mfma_i32_16x16x64_i8 v[62:65], v[82:85], v[186:189], v[62:65]
	v_mfma_i32_16x16x64_i8 v[62:65], v[86:89], v[190:193], v[62:65]
	v_mfma_i32_16x16x64_i8 v[58:61], v[142:145], v[190:193], v[58:61]
	v_mfma_i32_16x16x64_i8 v[58:61], v[138:141], v[186:189], v[58:61]
	v_mfma_i32_16x16x64_i8 v[42:45], v[138:141], v[216:219], v[42:45]
	v_mfma_i32_16x16x64_i8 v[42:45], v[142:145], v[220:223], v[42:45]
	v_mfma_i32_16x16x64_i8 v[46:49], v[86:89], v[220:223], v[46:49]
	v_mfma_i32_16x16x64_i8 v[46:49], v[82:85], v[216:219], v[46:49]
	v_mfma_i32_16x16x64_i8 v[30:33], v[82:85], v[224:227], v[30:33]
	v_mfma_i32_16x16x64_i8 v[30:33], v[86:89], v[228:231], v[30:33]
	v_mfma_i32_16x16x64_i8 v[26:29], v[142:145], v[228:231], v[26:29]
	v_mfma_i32_16x16x64_i8 v[26:29], v[138:141], v[224:227], v[26:29]
	v_mfma_i32_16x16x64_i8 v[10:13], v[138:141], v[232:235], v[10:13]
	v_mfma_i32_16x16x64_i8 v[10:13], v[142:145], v[236:239], v[10:13]
	v_mfma_i32_16x16x64_i8 v[14:17], v[86:89], v[236:239], v[14:17]
	v_mfma_i32_16x16x64_i8 v[14:17], v[82:85], v[232:235], v[14:17]
	s_setprio 0
	s_setprio 1
	v_mfma_i32_16x16x64_i8 v[54:57], v[146:149], v[186:189], v[54:57]
	v_mfma_i32_16x16x64_i8 v[54:57], v[150:153], v[190:193], v[54:57]
	v_mfma_i32_16x16x64_i8 v[50:53], v[158:161], v[190:193], v[50:53]
	v_mfma_i32_16x16x64_i8 v[50:53], v[154:157], v[186:189], v[50:53]
	v_mfma_i32_16x16x64_i8 v[34:37], v[154:157], v[216:219], v[34:37]
	v_mfma_i32_16x16x64_i8 v[34:37], v[158:161], v[220:223], v[34:37]
	v_mfma_i32_16x16x64_i8 v[38:41], v[150:153], v[220:223], v[38:41]
	v_mfma_i32_16x16x64_i8 v[38:41], v[146:149], v[216:219], v[38:41]
	v_mfma_i32_16x16x64_i8 v[22:25], v[146:149], v[224:227], v[22:25]
	v_mfma_i32_16x16x64_i8 v[22:25], v[150:153], v[228:231], v[22:25]
	v_mfma_i32_16x16x64_i8 v[18:21], v[158:161], v[228:231], v[18:21]
	v_mfma_i32_16x16x64_i8 v[18:21], v[154:157], v[224:227], v[18:21]
	v_mfma_i32_16x16x64_i8 v[2:5], v[154:157], v[232:235], v[2:5]
	v_mfma_i32_16x16x64_i8 v[2:5], v[158:161], v[236:239], v[2:5]
	v_mfma_i32_16x16x64_i8 v[6:9], v[150:153], v[236:239], v[6:9]
	v_mfma_i32_16x16x64_i8 v[6:9], v[146:149], v[232:235], v[6:9]
	s_setprio 0
	s_barrier
	s_add_i32 s46, s46, 2
	s_add_u32 s62, s62, 0x100
	s_addc_u32 s63, s63, 0
	s_add_u32 s36, s36, 0x100
	s_addc_u32 s37, s37, 0

; #define PG8_STAGE(bufoff, gbase, voff) do { _Pragma("unroll") for (int _i = 0; _i < 2; ++_i) \
;         __builtin_amdgcn_global_load_lds((const unsigned*)((const char*)(gbase) + (voff)[_i]), (PG8_LAS unsigned*)(lds + (bufoff) + ldsw + _i * 8192), 16, 0, 0); } while (0)
; #define PG8_LDA(dst, b, h) do { _Pragma("unroll") for (int m = 0; m < 4; ++m) _Pragma("unroll") for (int k = 0; k < 2; ++k) dst[m][k] = *(const PG8_LAS bf16x8*)(lds + PG8_SA(b, h) + aoff + m * 2048 + k * 1024); } while (0)
; #define PG8_BAR __builtin_amdgcn_s_barrier()
; template <class Epi, class Sched, bool ALIGN_EPI = false, bool SP2 = false>
; __device__ __forceinline__ void gemm_phase(PG8_LAS unsigned char* lds, const Gemm g, const Sched& S, const Epi& E) {
;     ...
;         const bool has_next = S.next(ui + 1, nxt);
;         const char* nA = has_next ? PG8_ABASE(nxt) : cA; const char* nB = has_next ? PG8_BBASE(nxt) : cB;
; #pragma unroll 1
;         for (int t = 0; t < nt; t += 2) {
;             const bool last = (t == nt - 2);
;             const char* a1 = cA + (size_t)(t + 1) * kstep;
;             const char* a2 = last ? nA : cA + (size_t)(t + 2) * kstep; const char* b2 = last ? nB : cB + (size_t)(t + 2) * kstep;
;             const char* a3 = a2 + kstep; const char* b3 = b2 + kstep;
;             if (last && has_next) S.a_ready(nxt);
;             if constexpr (SP2) {
;             PG8_LDB(B0, 0, 0); PG8_LDB(B1, 0, 1); PG8_SCHED; PG8_LDA(At, 0, 0); PG8_STAGE(PG8_SA(1, 1), a1 + hstepA, voffA);
;             PG8_WAIT_V(8); PG8_WAIT_L(0); PG8_BAR; PG8_MMA(0, 0, At, B0); PG8_MMA(0, 1, At, B1); PG8_BAR; PG8_SCHED;
;             PG8_LDA(At, 0, 1); PG8_STAGE(PG8_SB(0, 0), b2, voffB); PG8_STAGE(PG8_SB(0, 1), b2 + hstepB, voffB); PG8_STAGE(PG8_SA(0, 0), a2, voffA);
;             PG8_WAIT_V(8); PG8_WAIT_L(0); PG8_BAR; PG8_MMA(1, 0, At, B0); PG8_MMA(1, 1, At, B1); PG8_BAR; PG8_SCHED;
;             PG8_LDB(B0, 1, 0); PG8_LDB(B1, 1, 1); PG8_SCHED; PG8_LDA(At, 1, 0); PG8_STAGE(PG8_SA(0, 1), a2 + hstepA, voffA);
;             PG8_WAIT_V(8); PG8_WAIT_L(0); PG8_BAR; PG8_MMA(0, 0, At, B0); PG8_MMA(0, 1, At, B1); PG8_BAR; PG8_SCHED;
;             PG8_LDA(At, 1, 1); PG8_STAGE(PG8_SB(1, 0), b3, voffB); PG8_STAGE(PG8_SB(1, 1), b3 + hstepB, voffB); PG8_STAGE(PG8_SA(1, 0), a3, voffA);
;             PG8_WAIT_V(8); PG8_WAIT_L(0); PG8_BAR; PG8_MMA(1, 0, At, B0); PG8_MMA(1, 1, At, B1); PG8_BAR; PG8_SCHED;
.LBB0_578:
	s_ashr_i32 s49, s48, 31
	s_lshl_b64 s[24:25], s[48:49], 21
	s_add_u32 s26, s44, s24
	s_addc_u32 s27, s45, s25
	s_ashr_i32 s24, s42, 30
	s_ashr_i32 s25, s24, 31
	s_lshl_b64 s[24:25], s[24:25], 13
	s_add_u32 s50, s26, s24
	s_addc_u32 s51, s27, s25
	s_and_b64 s[24:25], s[2:3], exec
	s_cselect_b32 s24, s51, s57
	s_cselect_b32 s25, s50, s56
	s_ashr_i32 s43, s42, 31
	s_lshl_b64 s[26:27], s[42:43], 21
	s_add_u32 s52, s62, s26
	s_addc_u32 s53, s63, s27
	s_and_b64 s[26:27], s[2:3], exec
	s_cselect_b32 s26, s53, s59
	s_cselect_b32 s27, s52, s58
	s_add_u32 s56, s56, 0x100080
	s_addc_u32 s57, s57, 0
	s_add_u32 s28, s58, 0x100
	s_addc_u32 s29, s59, 0
	s_mov_b32 s33, -2
	ds_read_b128 v[130:133], v1
	ds_read_b128 v[134:137], v1 offset:1024
	ds_read_b128 v[138:141], v1 offset:2048
	ds_read_b128 v[142:145], v1 offset:3072
	ds_read_b128 v[146:149], v214
	ds_read_b128 v[150:153], v214 offset:1024
	ds_read_b128 v[154:157], v214 offset:2048
	ds_read_b128 v[158:161], v214 offset:3072
	s_add_u32 s35, s56, 0xfff00080
	s_addc_u32 s36, s57, -1
	s_cmp_eq_u32 s33, 60
	s_cselect_b32 s61, s24, s36
	s_cselect_b32 s60, s25, s35
	s_cselect_b32 s59, s26, s29
	s_cselect_b32 s58, s27, s28
	v_lshl_add_u64 v[220:221], s[56:57], 0, v[190:191]
	s_add_i32 m0, s8, 0xc000
	ds_read_b128 v[162:165], v215
	ds_read_b128 v[166:169], v215 offset:1024
	ds_read_b128 v[170:173], v215 offset:2048
	ds_read_b128 v[174:177], v215 offset:3072
	ds_read_b128 v[198:201], v215 offset:4096
	ds_read_b128 v[202:205], v215 offset:5120
	ds_read_b128 v[206:209], v215 offset:6144
	ds_read_b128 v[216:219], v215 offset:7168
	global_load_lds_dwordx4 v[220:221], off
	v_lshl_add_u64 v[220:221], s[56:57], 0, v[192:193]
	s_add_i32 m0, s8, 0xe000
	s_nop 0
	global_load_lds_dwordx4 v[220:221], off
	s_waitcnt vmcnt(8)
	s_waitcnt lgkmcnt(0)
	s_barrier
	s_setprio 1
	s_waitcnt lgkmcnt(0)
	v_mfma_f32_16x16x32_bf16 v[126:129], v[130:133], v[162:165], 0
	v_mfma_f32_16x16x32_bf16 v[126:129], v[134:137], v[166:169], v[126:129]
	v_mfma_f32_16x16x32_bf16 v[122:125], v[142:145], v[166:169], 0
	v_mfma_f32_16x16x32_bf16 v[122:125], v[138:141], v[162:165], v[122:125]
	v_mfma_f32_16x16x32_bf16 v[106:109], v[138:141], v[170:173], 0
	v_mfma_f32_16x16x32_bf16 v[106:109], v[142:145], v[174:177], v[106:109]
	v_mfma_f32_16x16x32_bf16 v[110:113], v[134:137], v[174:177], 0
	v_mfma_f32_16x16x32_bf16 v[110:113], v[130:133], v[170:173], v[110:113]
	v_mfma_f32_16x16x32_bf16 v[94:97], v[130:133], v[198:201], 0
	v_mfma_f32_16x16x32_bf16 v[94:97], v[134:137], v[202:205], v[94:97]
	v_mfma_f32_16x16x32_bf16 v[90:93], v[142:145], v[202:205], 0
	v_mfma_f32_16x16x32_bf16 v[90:93], v[138:141], v[198:201], v[90:93]
	v_mfma_f32_16x16x32_bf16 v[74:77], v[138:141], v[206:209], 0
	v_mfma_f32_16x16x32_bf16 v[74:77], v[142:145], v[216:219], v[74:77]
	v_mfma_f32_16x16x32_bf16 v[78:81], v[134:137], v[216:219], 0
	v_mfma_f32_16x16x32_bf16 v[78:81], v[130:133], v[206:209], v[78:81]
	s_setprio 0
	s_setprio 1
	v_mfma_f32_16x16x32_bf16 v[118:121], v[146:149], v[162:165], 0
	v_mfma_f32_16x16x32_bf16 v[118:121], v[150:153], v[166:169], v[118:121]
	v_mfma_f32_16x16x32_bf16 v[114:117], v[158:161], v[166:169], 0
	v_mfma_f32_16x16x32_bf16 v[114:117], v[154:157], v[162:165], v[114:117]
	v_mfma_f32_16x16x32_bf16 v[98:101], v[154:157], v[170:173], 0
	v_mfma_f32_16x16x32_bf16 v[98:101], v[158:161], v[174:177], v[98:101]
	v_mfma_f32_16x16x32_bf16 v[102:105], v[150:153], v[174:177], 0
	v_mfma_f32_16x16x32_bf16 v[102:105], v[146:149], v[170:173], v[102:105]
	v_mfma_f32_16x16x32_bf16 v[86:89], v[146:149], v[198:201], 0
	v_mfma_f32_16x16x32_bf16 v[86:89], v[150:153], v[202:205], v[86:89]
	v_mfma_f32_16x16x32_bf16 v[82:85], v[158:161], v[202:205], 0
	v_mfma_f32_16x16x32_bf16 v[82:85], v[154:157], v[198:201], v[82:85]
	v_mfma_f32_16x16x32_bf16 v[66:69], v[154:157], v[206:209], 0
	v_mfma_f32_16x16x32_bf16 v[66:69], v[158:161], v[216:219], v[66:69]
	v_mfma_f32_16x16x32_bf16 v[70:73], v[150:153], v[216:219], 0
	v_mfma_f32_16x16x32_bf16 v[70:73], v[146:149], v[206:209], v[70:73]
	s_setprio 0
	s_barrier
	s_add_i32 s35, s21, s7
	v_lshl_add_u64 v[220:221], s[58:59], 0, v[184:185]
	s_mov_b32 m0, s35
	ds_read_b128 v[162:165], v215 offset:16384
	ds_read_b128 v[166:169], v215 offset:17408
	ds_read_b128 v[170:173], v215 offset:18432
	ds_read_b128 v[174:177], v215 offset:19456
	ds_read_b128 v[198:201], v215 offset:20480
	ds_read_b128 v[202:205], v215 offset:21504
	ds_read_b128 v[206:209], v215 offset:22528
	ds_read_b128 v[216:219], v215 offset:23552
	global_load_lds_dwordx4 v[220:221], off
	s_add_i32 m0, s35, 0x2000
	s_add_u32 s36, s58, 0x100000
	v_lshl_add_u64 v[222:223], s[58:59], 0, v[188:189]
	s_addc_u32 s37, s59, 0
	s_add_i32 s35, s22, s7
	global_load_lds_dwordx4 v[222:223], off
	v_lshl_add_u64 v[224:225], s[36:37], 0, v[184:185]
	s_mov_b32 m0, s35
	v_lshl_add_u64 v[226:227], s[60:61], 0, v[186:187]
	global_load_lds_dwordx4 v[224:225], off
	v_lshl_add_u64 v[224:225], s[36:37], 0, v[188:189]
	s_add_i32 m0, s35, 0x2000
	s_nop 0
	global_load_lds_dwordx4 v[224:225], off
	v_lshl_add_u64 v[224:225], s[60:61], 0, v[182:183]
	s_mov_b32 m0, s8
	s_nop 0
	global_load_lds_dwordx4 v[224:225], off
	s_mov_b32 m0, s11
	s_nop 0
	global_load_lds_dwordx4 v[226:227], off
	s_waitcnt vmcnt(8)
	s_waitcnt lgkmcnt(0)
	s_barrier
; #define PG8_STAGE(bufoff, gbase, voff) do { _Pragma("unroll") for (int _i = 0; _i < 2; ++_i) \
;         __builtin_amdgcn_global_load_lds((const unsigned*)((const char*)(gbase) + (voff)[_i]), (PG8_LAS unsigned*)(lds + (bufoff) + ldsw + _i * 8192), 16, 0, 0); } while (0)
; #define PG8_LDA(dst, b, h) do { _Pragma("unroll") for (int m = 0; m < 4; ++m) _Pragma("unroll") for (int k = 0; k < 2; ++k) dst[m][k] = *(const PG8_LAS bf16x8*)(lds + PG8_SA(b, h) + aoff + m * 2048 + k * 1024); } while (0)
; #define PG8_LDB(dst, b, h) do { _Pragma("unroll") for (int n = 0; n < 2; ++n) _Pragma("unroll") for (int k = 0; k < 2; ++k) dst[n][k] = *(const PG8_LAS bf16x8*)(lds + PG8_SB(b, h) + boff + n * 2048 + k * 1024); } while (0)
; #define PG8_MMA(ai, bj, At, Bt) do { __builtin_amdgcn_s_setprio(1); _Pragma("unroll") for (int m = 0; m < 4; ++m) _Pragma("unroll") for (int n = 0; n < 2; ++n) _Pragma("unroll") for (int k = 0; k < 2; ++k) \
;         acc[ai][bj][m][n] = mma16(Bt[n][k], At[m][k], acc[ai][bj][m][n]); __builtin_amdgcn_s_setprio(0); } while (0)
; #define PG8_WAIT_V(n) asm volatile("s_waitcnt vmcnt(" #n ")" ::: "memory")
; template <class Epi, class Sched, bool ALIGN_EPI = false, bool SP2 = false>
; __device__ __forceinline__ void gemm_phase(PG8_LAS unsigned char* lds, const Gemm g, const Sched& S, const Epi& E) {
;     ...
;             PG8_LDB(B0, 0, 0); PG8_LDB(B1, 0, 1); PG8_SCHED; PG8_LDA(At, 0, 0); PG8_STAGE(PG8_SA(1, 1), a1 + hstepA, voffA);
;             PG8_WAIT_V(8); PG8_WAIT_L(0); PG8_BAR; PG8_MMA(0, 0, At, B0); PG8_MMA(0, 1, At, B1); PG8_BAR; PG8_SCHED;
;             PG8_LDA(At, 0, 1); PG8_STAGE(PG8_SB(0, 0), b2, voffB); PG8_STAGE(PG8_SB(0, 1), b2 + hstepB, voffB); PG8_STAGE(PG8_SA(0, 0), a2, voffA);
;             PG8_WAIT_V(8); PG8_WAIT_L(0); PG8_BAR; PG8_MMA(1, 0, At, B0); PG8_MMA(1, 1, At, B1); PG8_BAR; PG8_SCHED;
;             PG8_LDB(B0, 1, 0); PG8_LDB(B1, 1, 1); PG8_SCHED; PG8_LDA(At, 1, 0); PG8_STAGE(PG8_SA(0, 1), a2 + hstepA, voffA);
;             PG8_WAIT_V(8); PG8_WAIT_L(0); PG8_BAR; PG8_MMA(0, 0, At, B0); PG8_MMA(0, 1, At, B1); PG8_BAR; PG8_SCHED;
;             PG8_LDA(At, 1, 1); PG8_STAGE(PG8_SB(1, 0), b3, voffB); PG8_STAGE(PG8_SB(1, 1), b3 + hstepB, voffB); PG8_STAGE(PG8_SA(1, 0), a3, voffA);
;             PG8_WAIT_V(8); PG8_WAIT_L(0); PG8_BAR; PG8_MMA(1, 0, At, B0); PG8_MMA(1, 1, At, B1); PG8_BAR; PG8_SCHED;
	s_setprio 1
	s_waitcnt lgkmcnt(0)
	v_mfma_f32_16x16x32_bf16 v[62:65], v[130:133], v[162:165], 0
	v_mfma_f32_16x16x32_bf16 v[62:65], v[134:137], v[166:169], v[62:65]
	v_mfma_f32_16x16x32_bf16 v[58:61], v[142:145], v[166:169], 0
	v_mfma_f32_16x16x32_bf16 v[58:61], v[138:141], v[162:165], v[58:61]
	v_mfma_f32_16x16x32_bf16 v[42:45], v[138:141], v[170:173], 0
	v_mfma_f32_16x16x32_bf16 v[42:45], v[142:145], v[174:177], v[42:45]
	v_mfma_f32_16x16x32_bf16 v[46:49], v[134:137], v[174:177], 0
	v_mfma_f32_16x16x32_bf16 v[46:49], v[130:133], v[170:173], v[46:49]
	v_mfma_f32_16x16x32_bf16 v[30:33], v[130:133], v[198:201], 0
	v_mfma_f32_16x16x32_bf16 v[30:33], v[134:137], v[202:205], v[30:33]
	v_mfma_f32_16x16x32_bf16 v[26:29], v[142:145], v[202:205], 0
	v_mfma_f32_16x16x32_bf16 v[26:29], v[138:141], v[198:201], v[26:29]
	v_mfma_f32_16x16x32_bf16 v[10:13], v[138:141], v[206:209], 0
	v_mfma_f32_16x16x32_bf16 v[10:13], v[142:145], v[216:219], v[10:13]
	v_mfma_f32_16x16x32_bf16 v[14:17], v[134:137], v[216:219], 0
	v_mfma_f32_16x16x32_bf16 v[14:17], v[130:133], v[206:209], v[14:17]
	s_setprio 0
	s_setprio 1
	v_mfma_f32_16x16x32_bf16 v[54:57], v[146:149], v[162:165], 0
	v_mfma_f32_16x16x32_bf16 v[54:57], v[150:153], v[166:169], v[54:57]
	v_mfma_f32_16x16x32_bf16 v[50:53], v[158:161], v[166:169], 0
	v_mfma_f32_16x16x32_bf16 v[50:53], v[154:157], v[162:165], v[50:53]
	v_mfma_f32_16x16x32_bf16 v[34:37], v[154:157], v[170:173], 0
	v_mfma_f32_16x16x32_bf16 v[34:37], v[158:161], v[174:177], v[34:37]
	v_mfma_f32_16x16x32_bf16 v[38:41], v[150:153], v[174:177], 0
	v_mfma_f32_16x16x32_bf16 v[38:41], v[146:149], v[170:173], v[38:41]
	v_mfma_f32_16x16x32_bf16 v[22:25], v[146:149], v[198:201], 0
	v_mfma_f32_16x16x32_bf16 v[22:25], v[150:153], v[202:205], v[22:25]
	v_mfma_f32_16x16x32_bf16 v[18:21], v[158:161], v[202:205], 0
	v_mfma_f32_16x16x32_bf16 v[18:21], v[154:157], v[198:201], v[18:21]
	v_mfma_f32_16x16x32_bf16 v[2:5], v[154:157], v[206:209], 0
	v_mfma_f32_16x16x32_bf16 v[2:5], v[158:161], v[216:219], v[2:5]
	v_mfma_f32_16x16x32_bf16 v[6:9], v[150:153], v[216:219], 0
	v_mfma_f32_16x16x32_bf16 v[6:9], v[146:149], v[206:209], v[6:9]
	s_setprio 0
	s_barrier
	s_add_i32 s35, 0, 0x18000
	s_add_i32 s43, 0, 0x1c000
	v_add_u32_e32 v142, s35, v212
	v_add_u32_e32 v158, s43, v212
	ds_read_b128 v[130:133], v142
	ds_read_b128 v[134:137], v142 offset:1024
	ds_read_b128 v[138:141], v142 offset:2048
	ds_read_b128 v[142:145], v142 offset:3072
	ds_read_b128 v[146:149], v158
	ds_read_b128 v[150:153], v158 offset:1024
	ds_read_b128 v[154:157], v158 offset:2048
	ds_read_b128 v[158:161], v158 offset:3072
	s_add_u32 s36, s60, 0x100000
	s_addc_u32 s37, s61, 0
	s_mov_b32 m0, s12
	v_lshl_add_u64 v[228:229], s[36:37], 0, v[182:183]
	ds_read_b128 v[162:165], v215 offset:32768
	ds_read_b128 v[166:169], v215 offset:33792
	ds_read_b128 v[170:173], v215 offset:34816
	ds_read_b128 v[174:177], v215 offset:35840
	ds_read_b128 v[198:201], v215 offset:36864
	ds_read_b128 v[202:205], v215 offset:37888
	ds_read_b128 v[206:209], v215 offset:38912
	ds_read_b128 v[216:219], v215 offset:39936
	global_load_lds_dwordx4 v[228:229], off
	v_lshl_add_u64 v[228:229], s[36:37], 0, v[186:187]
	s_mov_b32 m0, s13
	s_nop 0
	global_load_lds_dwordx4 v[228:229], off
	s_waitcnt vmcnt(8)
	s_waitcnt lgkmcnt(0)
	s_barrier
	s_setprio 1
	s_waitcnt lgkmcnt(0)
	v_mfma_f32_16x16x32_bf16 v[126:129], v[130:133], v[162:165], v[126:129]
	v_mfma_f32_16x16x32_bf16 v[126:129], v[134:137], v[166:169], v[126:129]
	v_mfma_f32_16x16x32_bf16 v[122:125], v[142:145], v[166:169], v[122:125]
	v_mfma_f32_16x16x32_bf16 v[122:125], v[138:141], v[162:165], v[122:125]
	v_mfma_f32_16x16x32_bf16 v[106:109], v[138:141], v[170:173], v[106:109]
	v_mfma_f32_16x16x32_bf16 v[106:109], v[142:145], v[174:177], v[106:109]
	v_mfma_f32_16x16x32_bf16 v[110:113], v[134:137], v[174:177], v[110:113]
	v_mfma_f32_16x16x32_bf16 v[110:113], v[130:133], v[170:173], v[110:113]
	v_mfma_f32_16x16x32_bf16 v[94:97], v[130:133], v[198:201], v[94:97]
	v_mfma_f32_16x16x32_bf16 v[94:97], v[134:137], v[202:205], v[94:97]
	v_mfma_f32_16x16x32_bf16 v[90:93], v[142:145], v[202:205], v[90:93]
	v_mfma_f32_16x16x32_bf16 v[90:93], v[138:141], v[198:201], v[90:93]
	v_mfma_f32_16x16x32_bf16 v[74:77], v[138:141], v[206:209], v[74:77]
	v_mfma_f32_16x16x32_bf16 v[74:77], v[142:145], v[216:219], v[74:77]
	v_mfma_f32_16x16x32_bf16 v[78:81], v[134:137], v[216:219], v[78:81]
	v_mfma_f32_16x16x32_bf16 v[78:81], v[130:133], v[206:209], v[78:81]
	s_setprio 0
	s_setprio 1
	v_mfma_f32_16x16x32_bf16 v[118:121], v[146:149], v[162:165], v[118:121]
	v_mfma_f32_16x16x32_bf16 v[118:121], v[150:153], v[166:169], v[118:121]
	v_mfma_f32_16x16x32_bf16 v[114:117], v[158:161], v[166:169], v[114:117]
	v_mfma_f32_16x16x32_bf16 v[114:117], v[154:157], v[162:165], v[114:117]
	v_mfma_f32_16x16x32_bf16 v[98:101], v[154:157], v[170:173], v[98:101]
	v_mfma_f32_16x16x32_bf16 v[98:101], v[158:161], v[174:177], v[98:101]
	v_mfma_f32_16x16x32_bf16 v[102:105], v[150:153], v[174:177], v[102:105]
	v_mfma_f32_16x16x32_bf16 v[102:105], v[146:149], v[170:173], v[102:105]
	v_mfma_f32_16x16x32_bf16 v[86:89], v[146:149], v[198:201], v[86:89]
	v_mfma_f32_16x16x32_bf16 v[86:89], v[150:153], v[202:205], v[86:89]
	v_mfma_f32_16x16x32_bf16 v[82:85], v[158:161], v[202:205], v[82:85]
	v_mfma_f32_16x16x32_bf16 v[82:85], v[154:157], v[198:201], v[82:85]
	v_mfma_f32_16x16x32_bf16 v[66:69], v[154:157], v[206:209], v[66:69]
	v_mfma_f32_16x16x32_bf16 v[66:69], v[158:161], v[216:219], v[66:69]
	v_mfma_f32_16x16x32_bf16 v[70:73], v[150:153], v[216:219], v[70:73]
	v_mfma_f32_16x16x32_bf16 v[70:73], v[146:149], v[206:209], v[70:73]
	s_setprio 0
	s_barrier
; #define PG8_STAGE(bufoff, gbase, voff) do { _Pragma("unroll") for (int _i = 0; _i < 2; ++_i) \
;         __builtin_amdgcn_global_load_lds((const unsigned*)((const char*)(gbase) + (voff)[_i]), (PG8_LAS unsigned*)(lds + (bufoff) + ldsw + _i * 8192), 16, 0, 0); } while (0)
; #define PG8_LDA(dst, b, h) do { _Pragma("unroll") for (int m = 0; m < 4; ++m) _Pragma("unroll") for (int k = 0; k < 2; ++k) dst[m][k] = *(const PG8_LAS bf16x8*)(lds + PG8_SA(b, h) + aoff + m * 2048 + k * 1024); } while (0)
; #define PG8_MMA(ai, bj, At, Bt) do { __builtin_amdgcn_s_setprio(1); _Pragma("unroll") for (int m = 0; m < 4; ++m) _Pragma("unroll") for (int n = 0; n < 2; ++n) _Pragma("unroll") for (int k = 0; k < 2; ++k) \
;         acc[ai][bj][m][n] = mma16(Bt[n][k], At[m][k], acc[ai][bj][m][n]); __builtin_amdgcn_s_setprio(0); } while (0)
; #define PG8_WAIT_V(n) asm volatile("s_waitcnt vmcnt(" #n ")" ::: "memory")
; #define PG8_WAIT_L(n) asm volatile("s_waitcnt lgkmcnt(" #n ")" ::: "memory")
; #define PG8_BAR __builtin_amdgcn_s_barrier()
; #define PG8_SCHED __builtin_amdgcn_sched_barrier(0)
; template <class Epi, class Sched, bool ALIGN_EPI = false, bool SP2 = false>
; __device__ __forceinline__ void gemm_phase(PG8_LAS unsigned char* lds, const Gemm g, const Sched& S, const Epi& E) {
;     ...
;             PG8_LDA(At, 1, 1); PG8_STAGE(PG8_SB(1, 0), b3, voffB); PG8_STAGE(PG8_SB(1, 1), b3 + hstepB, voffB); PG8_STAGE(PG8_SA(1, 0), a3, voffA);
;             PG8_WAIT_V(8); PG8_WAIT_L(0); PG8_BAR; PG8_MMA(1, 0, At, B0); PG8_MMA(1, 1, At, B1); PG8_BAR; PG8_SCHED;
	s_add_i32 s35, s35, s7
	v_lshl_add_u64 v[220:221], v[220:221], 0, s[38:39]
	s_mov_b32 m0, s35
	ds_read_b128 v[162:165], v215 offset:49152
	ds_read_b128 v[166:169], v215 offset:50176
	ds_read_b128 v[170:173], v215 offset:51200
	ds_read_b128 v[174:177], v215 offset:52224
	ds_read_b128 v[198:201], v215 offset:53248
	ds_read_b128 v[202:205], v215 offset:54272
	ds_read_b128 v[206:209], v215 offset:55296
	ds_read_b128 v[216:219], v215 offset:56320
	global_load_lds_dwordx4 v[220:221], off
	s_add_i32 m0, s35, 0x2000
	s_add_u32 s36, s58, 0x100080
	v_lshl_add_u64 v[220:221], v[222:223], 0, s[38:39]
	s_addc_u32 s37, s59, 0
	s_add_i32 s35, s43, s7
	global_load_lds_dwordx4 v[220:221], off
	v_lshl_add_u64 v[220:221], s[36:37], 0, v[184:185]
	s_mov_b32 m0, s35
	s_nop 0
	global_load_lds_dwordx4 v[220:221], off
	v_lshl_add_u64 v[220:221], s[36:37], 0, v[188:189]
	s_add_i32 m0, s35, 0x2000
	s_nop 0
	global_load_lds_dwordx4 v[220:221], off
	v_lshl_add_u64 v[220:221], v[224:225], 0, s[38:39]
	s_mov_b32 m0, s17
	s_nop 0
	global_load_lds_dwordx4 v[220:221], off
	v_lshl_add_u64 v[220:221], v[226:227], 0, s[38:39]
	s_mov_b32 m0, s18
	s_nop 0
	global_load_lds_dwordx4 v[220:221], off
	s_waitcnt vmcnt(8)
	s_waitcnt lgkmcnt(0)
	s_barrier
	s_setprio 1
	s_waitcnt lgkmcnt(0)
	v_mfma_f32_16x16x32_bf16 v[62:65], v[130:133], v[162:165], v[62:65]
	v_mfma_f32_16x16x32_bf16 v[62:65], v[134:137], v[166:169], v[62:65]
	v_mfma_f32_16x16x32_bf16 v[58:61], v[142:145], v[166:169], v[58:61]
	v_mfma_f32_16x16x32_bf16 v[58:61], v[138:141], v[162:165], v[58:61]
	v_mfma_f32_16x16x32_bf16 v[42:45], v[138:141], v[170:173], v[42:45]
	v_mfma_f32_16x16x32_bf16 v[42:45], v[142:145], v[174:177], v[42:45]
	v_mfma_f32_16x16x32_bf16 v[46:49], v[134:137], v[174:177], v[46:49]
	v_mfma_f32_16x16x32_bf16 v[46:49], v[130:133], v[170:173], v[46:49]
	v_mfma_f32_16x16x32_bf16 v[30:33], v[130:133], v[198:201], v[30:33]
	v_mfma_f32_16x16x32_bf16 v[30:33], v[134:137], v[202:205], v[30:33]
	v_mfma_f32_16x16x32_bf16 v[26:29], v[142:145], v[202:205], v[26:29]
	v_mfma_f32_16x16x32_bf16 v[26:29], v[138:141], v[198:201], v[26:29]
	v_mfma_f32_16x16x32_bf16 v[10:13], v[138:141], v[206:209], v[10:13]
	v_mfma_f32_16x16x32_bf16 v[10:13], v[142:145], v[216:219], v[10:13]
	v_mfma_f32_16x16x32_bf16 v[14:17], v[134:137], v[216:219], v[14:17]
	v_mfma_f32_16x16x32_bf16 v[14:17], v[130:133], v[206:209], v[14:17]
	s_setprio 0
	s_setprio 1
	v_mfma_f32_16x16x32_bf16 v[54:57], v[146:149], v[162:165], v[54:57]
	v_mfma_f32_16x16x32_bf16 v[54:57], v[150:153], v[166:169], v[54:57]
	v_mfma_f32_16x16x32_bf16 v[50:53], v[158:161], v[166:169], v[50:53]
	v_mfma_f32_16x16x32_bf16 v[50:53], v[154:157], v[162:165], v[50:53]
	v_mfma_f32_16x16x32_bf16 v[34:37], v[154:157], v[170:173], v[34:37]
	v_mfma_f32_16x16x32_bf16 v[34:37], v[158:161], v[174:177], v[34:37]
	v_mfma_f32_16x16x32_bf16 v[38:41], v[150:153], v[174:177], v[38:41]
	v_mfma_f32_16x16x32_bf16 v[38:41], v[146:149], v[170:173], v[38:41]
	v_mfma_f32_16x16x32_bf16 v[22:25], v[146:149], v[198:201], v[22:25]
	v_mfma_f32_16x16x32_bf16 v[22:25], v[150:153], v[202:205], v[22:25]
	v_mfma_f32_16x16x32_bf16 v[18:21], v[158:161], v[202:205], v[18:21]
	v_mfma_f32_16x16x32_bf16 v[18:21], v[154:157], v[198:201], v[18:21]
	v_mfma_f32_16x16x32_bf16 v[2:5], v[154:157], v[206:209], v[2:5]
	v_mfma_f32_16x16x32_bf16 v[2:5], v[158:161], v[216:219], v[2:5]
	v_mfma_f32_16x16x32_bf16 v[6:9], v[150:153], v[216:219], v[6:9]
	v_mfma_f32_16x16x32_bf16 v[6:9], v[146:149], v[206:209], v[6:9]
	s_setprio 0
	s_barrier
	s_add_i32 s33, s33, 2
	s_add_u32 s56, s56, 0x100
	s_addc_u32 s57, s57, 0
	s_add_u32 s28, s28, 0x100
	s_addc_u32 s29, s29, 0

; #define PG8_STAGE(bufoff, gbase, voff) do { _Pragma("unroll") for (int _i = 0; _i < 2; ++_i) \
;         __builtin_amdgcn_global_load_lds((const unsigned*)((const char*)(gbase) + (voff)[_i]), (PG8_LAS unsigned*)(lds + (bufoff) + ldsw + _i * 8192), 16, 0, 0); } while (0)
; #define PG8_LDA(dst, b, h) do { _Pragma("unroll") for (int m = 0; m < 4; ++m) _Pragma("unroll") for (int k = 0; k < 2; ++k) dst[m][k] = *(const PG8_LAS bf16x8*)(lds + PG8_SA(b, h) + aoff + m * 2048 + k * 1024); } while (0)
; #define PG8_BAR __builtin_amdgcn_s_barrier()
; template <class Epi, class Sched, bool ALIGN_EPI = false, bool SP2 = false>
; __device__ __forceinline__ void gemm_phase(PG8_LAS unsigned char* lds, const Gemm g, const Sched& S, const Epi& E) {
;     ...
;         const bool has_next = S.next(ui + 1, nxt);
;         const char* nA = has_next ? PG8_ABASE(nxt) : cA; const char* nB = has_next ? PG8_BBASE(nxt) : cB;
; #pragma unroll 1
;         for (int t = 0; t < nt; t += 2) {
;             const bool last = (t == nt - 2);
;             const char* a1 = cA + (size_t)(t + 1) * kstep;
;             const char* a2 = last ? nA : cA + (size_t)(t + 2) * kstep; const char* b2 = last ? nB : cB + (size_t)(t + 2) * kstep;
;             const char* a3 = a2 + kstep; const char* b3 = b2 + kstep;
;             if (last && has_next) S.a_ready(nxt);
;             if constexpr (SP2) {
;             PG8_LDB(B0, 0, 0); PG8_LDB(B1, 0, 1); PG8_SCHED; PG8_LDA(At, 0, 0); PG8_STAGE(PG8_SA(1, 1), a1 + hstepA, voffA);
;             PG8_WAIT_V(8); PG8_WAIT_L(0); PG8_BAR; PG8_MMA(0, 0, At, B0); PG8_MMA(0, 1, At, B1); PG8_BAR; PG8_SCHED;
;             PG8_LDA(At, 0, 1); PG8_STAGE(PG8_SB(0, 0), b2, voffB); PG8_STAGE(PG8_SB(0, 1), b2 + hstepB, voffB); PG8_STAGE(PG8_SA(0, 0), a2, voffA);
;             PG8_WAIT_V(8); PG8_WAIT_L(0); PG8_BAR; PG8_MMA(1, 0, At, B0); PG8_MMA(1, 1, At, B1); PG8_BAR; PG8_SCHED;
;             PG8_LDB(B0, 1, 0); PG8_LDB(B1, 1, 1); PG8_SCHED; PG8_LDA(At, 1, 0); PG8_STAGE(PG8_SA(0, 1), a2 + hstepA, voffA);
;             PG8_WAIT_V(8); PG8_WAIT_L(0); PG8_BAR; PG8_MMA(0, 0, At, B0); PG8_MMA(0, 1, At, B1); PG8_BAR; PG8_SCHED;
;             PG8_LDA(At, 1, 1); PG8_STAGE(PG8_SB(1, 0), b3, voffB); PG8_STAGE(PG8_SB(1, 1), b3 + hstepB, voffB); PG8_STAGE(PG8_SA(1, 0), a3, voffA);
;             PG8_WAIT_V(8); PG8_WAIT_L(0); PG8_BAR; PG8_MMA(1, 0, At, B0); PG8_MMA(1, 1, At, B1); PG8_BAR; PG8_SCHED;
.LBB0_659:
	s_ashr_i32 s55, s54, 31
	s_lshl_b64 s[28:29], s[54:55], 21
	s_add_u32 s60, s70, s28
	s_addc_u32 s61, s71, s29
	s_and_b64 s[0:1], s[0:1], exec
	s_cselect_b32 s27, s61, s65
	s_cselect_b32 s28, s60, s64
	s_add_u32 s0, s66, 0x100080
	s_addc_u32 s1, s67, 0
	s_add_u32 s29, s64, 0x100
	s_addc_u32 s33, s65, 0
	s_mov_b32 s35, -2
	ds_read_b128 v[154:157], v150
	ds_read_b128 v[158:161], v150 offset:1024
	ds_read_b128 v[162:165], v150 offset:2048
	ds_read_b128 v[166:169], v150 offset:3072
	ds_read_b128 v[170:173], v151
	ds_read_b128 v[174:177], v151 offset:1024
	ds_read_b128 v[182:185], v151 offset:2048
	ds_read_b128 v[186:189], v151 offset:3072
	s_add_u32 s36, s0, 0xfff00080
	s_addc_u32 s37, s1, -1
	s_cmp_eq_u32 s35, 60
	s_cselect_b32 s67, s59, s37
	s_cselect_b32 s66, s58, s36
	s_cselect_b32 s65, s27, s33
	s_cselect_b32 s64, s28, s29
	v_lshl_add_u64 v[146:147], s[0:1], 0, v[138:139]
	s_add_i32 m0, s8, 0xc000
	ds_read_b128 v[190:193], v152
	ds_read_b128 v[194:197], v152 offset:1024
	ds_read_b128 v[198:201], v152 offset:2048
	ds_read_b128 v[202:205], v152 offset:3072
	ds_read_b128 v[206:209], v152 offset:4096
	ds_read_b128 v[212:215], v152 offset:5120
	ds_read_b128 v[216:219], v152 offset:6144
	ds_read_b128 v[220:223], v152 offset:7168
	global_load_lds_dwordx4 v[146:147], off
	v_lshl_add_u64 v[146:147], s[0:1], 0, v[140:141]
	s_add_i32 m0, s8, 0xe000
	s_nop 0
	global_load_lds_dwordx4 v[146:147], off
	s_waitcnt vmcnt(8)
	s_waitcnt lgkmcnt(0)
	s_barrier
	s_setprio 1
	s_waitcnt lgkmcnt(0)
	v_mfma_f32_16x16x32_bf16 v[126:129], v[154:157], v[190:193], 0
	v_mfma_f32_16x16x32_bf16 v[126:129], v[158:161], v[194:197], v[126:129]
	v_mfma_f32_16x16x32_bf16 v[122:125], v[166:169], v[194:197], 0
	v_mfma_f32_16x16x32_bf16 v[122:125], v[162:165], v[190:193], v[122:125]
	v_mfma_f32_16x16x32_bf16 v[110:113], v[162:165], v[198:201], 0
	v_mfma_f32_16x16x32_bf16 v[110:113], v[166:169], v[202:205], v[110:113]
	v_mfma_f32_16x16x32_bf16 v[118:121], v[158:161], v[202:205], 0
	v_mfma_f32_16x16x32_bf16 v[118:121], v[154:157], v[198:201], v[118:121]
	v_mfma_f32_16x16x32_bf16 v[102:105], v[154:157], v[206:209], 0
	v_mfma_f32_16x16x32_bf16 v[102:105], v[158:161], v[212:215], v[102:105]
	v_mfma_f32_16x16x32_bf16 v[94:97], v[166:169], v[212:215], 0
	v_mfma_f32_16x16x32_bf16 v[94:97], v[162:165], v[206:209], v[94:97]
	v_mfma_f32_16x16x32_bf16 v[78:81], v[162:165], v[216:219], 0
	v_mfma_f32_16x16x32_bf16 v[78:81], v[166:169], v[220:223], v[78:81]
	v_mfma_f32_16x16x32_bf16 v[86:89], v[158:161], v[220:223], 0
	v_mfma_f32_16x16x32_bf16 v[86:89], v[154:157], v[216:219], v[86:89]
	s_setprio 0
	s_setprio 1
	v_mfma_f32_16x16x32_bf16 v[114:117], v[170:173], v[190:193], 0
	v_mfma_f32_16x16x32_bf16 v[114:117], v[174:177], v[194:197], v[114:117]
	v_mfma_f32_16x16x32_bf16 v[106:109], v[186:189], v[194:197], 0
	v_mfma_f32_16x16x32_bf16 v[106:109], v[182:185], v[190:193], v[106:109]
	v_mfma_f32_16x16x32_bf16 v[90:93], v[182:185], v[198:201], 0
	v_mfma_f32_16x16x32_bf16 v[90:93], v[186:189], v[202:205], v[90:93]
	v_mfma_f32_16x16x32_bf16 v[98:101], v[174:177], v[202:205], 0
	v_mfma_f32_16x16x32_bf16 v[98:101], v[170:173], v[198:201], v[98:101]
	v_mfma_f32_16x16x32_bf16 v[82:85], v[170:173], v[206:209], 0
	v_mfma_f32_16x16x32_bf16 v[82:85], v[174:177], v[212:215], v[82:85]
	v_mfma_f32_16x16x32_bf16 v[74:77], v[186:189], v[212:215], 0
	v_mfma_f32_16x16x32_bf16 v[74:77], v[182:185], v[206:209], v[74:77]
	v_mfma_f32_16x16x32_bf16 v[66:69], v[182:185], v[216:219], 0
	v_mfma_f32_16x16x32_bf16 v[66:69], v[186:189], v[220:223], v[66:69]
	v_mfma_f32_16x16x32_bf16 v[70:73], v[174:177], v[220:223], 0
	v_mfma_f32_16x16x32_bf16 v[70:73], v[170:173], v[216:219], v[70:73]
	s_setprio 0
	s_barrier
	s_add_i32 s36, s20, s7
	v_lshl_add_u64 v[146:147], s[64:65], 0, v[132:133]
	s_mov_b32 m0, s36
	ds_read_b128 v[190:193], v152 offset:16384
	ds_read_b128 v[194:197], v152 offset:17408
	ds_read_b128 v[198:201], v152 offset:18432
	ds_read_b128 v[202:205], v152 offset:19456
	ds_read_b128 v[206:209], v152 offset:20480
	ds_read_b128 v[212:215], v152 offset:21504
	ds_read_b128 v[216:219], v152 offset:22528
	ds_read_b128 v[220:223], v152 offset:23552
	global_load_lds_dwordx4 v[146:147], off
	s_add_i32 m0, s36, 0x2000
	s_add_u32 s36, s64, 0x100000
	v_lshl_add_u64 v[224:225], s[64:65], 0, v[136:137]
	s_addc_u32 s37, s65, 0
	s_add_i32 s46, s21, s7
	global_load_lds_dwordx4 v[224:225], off
	v_lshl_add_u64 v[226:227], s[36:37], 0, v[132:133]
	s_mov_b32 m0, s46
	v_lshl_add_u64 v[228:229], s[66:67], 0, v[134:135]
	global_load_lds_dwordx4 v[226:227], off
	v_lshl_add_u64 v[226:227], s[36:37], 0, v[136:137]
	s_add_i32 m0, s46, 0x2000
	s_nop 0
	global_load_lds_dwordx4 v[226:227], off
	v_lshl_add_u64 v[226:227], s[66:67], 0, v[130:131]
	s_mov_b32 m0, s8
	s_nop 0
	global_load_lds_dwordx4 v[226:227], off
	s_mov_b32 m0, s11
	s_nop 0
	global_load_lds_dwordx4 v[228:229], off
	s_waitcnt vmcnt(8)
	s_waitcnt lgkmcnt(0)
	s_barrier
; #define PG8_STAGE(bufoff, gbase, voff) do { _Pragma("unroll") for (int _i = 0; _i < 2; ++_i) \
;         __builtin_amdgcn_global_load_lds((const unsigned*)((const char*)(gbase) + (voff)[_i]), (PG8_LAS unsigned*)(lds + (bufoff) + ldsw + _i * 8192), 16, 0, 0); } while (0)
; #define PG8_LDA(dst, b, h) do { _Pragma("unroll") for (int m = 0; m < 4; ++m) _Pragma("unroll") for (int k = 0; k < 2; ++k) dst[m][k] = *(const PG8_LAS bf16x8*)(lds + PG8_SA(b, h) + aoff + m * 2048 + k * 1024); } while (0)
; #define PG8_LDB(dst, b, h) do { _Pragma("unroll") for (int n = 0; n < 2; ++n) _Pragma("unroll") for (int k = 0; k < 2; ++k) dst[n][k] = *(const PG8_LAS bf16x8*)(lds + PG8_SB(b, h) + boff + n * 2048 + k * 1024); } while (0)
; #define PG8_MMA(ai, bj, At, Bt) do { __builtin_amdgcn_s_setprio(1); _Pragma("unroll") for (int m = 0; m < 4; ++m) _Pragma("unroll") for (int n = 0; n < 2; ++n) _Pragma("unroll") for (int k = 0; k < 2; ++k) \
;         acc[ai][bj][m][n] = mma16(Bt[n][k], At[m][k], acc[ai][bj][m][n]); __builtin_amdgcn_s_setprio(0); } while (0)
; #define PG8_WAIT_V(n) asm volatile("s_waitcnt vmcnt(" #n ")" ::: "memory")
; template <class Epi, class Sched, bool ALIGN_EPI = false, bool SP2 = false>
; __device__ __forceinline__ void gemm_phase(PG8_LAS unsigned char* lds, const Gemm g, const Sched& S, const Epi& E) {
;     ...
;             PG8_LDB(B0, 0, 0); PG8_LDB(B1, 0, 1); PG8_SCHED; PG8_LDA(At, 0, 0); PG8_STAGE(PG8_SA(1, 1), a1 + hstepA, voffA);
;             PG8_WAIT_V(8); PG8_WAIT_L(0); PG8_BAR; PG8_MMA(0, 0, At, B0); PG8_MMA(0, 1, At, B1); PG8_BAR; PG8_SCHED;
;             PG8_LDA(At, 0, 1); PG8_STAGE(PG8_SB(0, 0), b2, voffB); PG8_STAGE(PG8_SB(0, 1), b2 + hstepB, voffB); PG8_STAGE(PG8_SA(0, 0), a2, voffA);
;             PG8_WAIT_V(8); PG8_WAIT_L(0); PG8_BAR; PG8_MMA(1, 0, At, B0); PG8_MMA(1, 1, At, B1); PG8_BAR; PG8_SCHED;
;             PG8_LDB(B0, 1, 0); PG8_LDB(B1, 1, 1); PG8_SCHED; PG8_LDA(At, 1, 0); PG8_STAGE(PG8_SA(0, 1), a2 + hstepA, voffA);
;             PG8_WAIT_V(8); PG8_WAIT_L(0); PG8_BAR; PG8_MMA(0, 0, At, B0); PG8_MMA(0, 1, At, B1); PG8_BAR; PG8_SCHED;
;             PG8_LDA(At, 1, 1); PG8_STAGE(PG8_SB(1, 0), b3, voffB); PG8_STAGE(PG8_SB(1, 1), b3 + hstepB, voffB); PG8_STAGE(PG8_SA(1, 0), a3, voffA);
;             PG8_WAIT_V(8); PG8_WAIT_L(0); PG8_BAR; PG8_MMA(1, 0, At, B0); PG8_MMA(1, 1, At, B1); PG8_BAR; PG8_SCHED;
	s_setprio 1
	s_waitcnt lgkmcnt(0)
	v_mfma_f32_16x16x32_bf16 v[62:65], v[154:157], v[190:193], 0
	v_mfma_f32_16x16x32_bf16 v[62:65], v[158:161], v[194:197], v[62:65]
	v_mfma_f32_16x16x32_bf16 v[58:61], v[166:169], v[194:197], 0
	v_mfma_f32_16x16x32_bf16 v[58:61], v[162:165], v[190:193], v[58:61]
	v_mfma_f32_16x16x32_bf16 v[46:49], v[162:165], v[198:201], 0
	v_mfma_f32_16x16x32_bf16 v[46:49], v[166:169], v[202:205], v[46:49]
	v_mfma_f32_16x16x32_bf16 v[54:57], v[158:161], v[202:205], 0
	v_mfma_f32_16x16x32_bf16 v[54:57], v[154:157], v[198:201], v[54:57]
	v_mfma_f32_16x16x32_bf16 v[38:41], v[154:157], v[206:209], 0
	v_mfma_f32_16x16x32_bf16 v[38:41], v[158:161], v[212:215], v[38:41]
	v_mfma_f32_16x16x32_bf16 v[30:33], v[166:169], v[212:215], 0
	v_mfma_f32_16x16x32_bf16 v[30:33], v[162:165], v[206:209], v[30:33]
	v_mfma_f32_16x16x32_bf16 v[14:17], v[162:165], v[216:219], 0
	v_mfma_f32_16x16x32_bf16 v[14:17], v[166:169], v[220:223], v[14:17]
	v_mfma_f32_16x16x32_bf16 v[22:25], v[158:161], v[220:223], 0
	v_mfma_f32_16x16x32_bf16 v[22:25], v[154:157], v[216:219], v[22:25]
	s_setprio 0
	s_setprio 1
	v_mfma_f32_16x16x32_bf16 v[50:53], v[170:173], v[190:193], 0
	v_mfma_f32_16x16x32_bf16 v[50:53], v[174:177], v[194:197], v[50:53]
	v_mfma_f32_16x16x32_bf16 v[42:45], v[186:189], v[194:197], 0
	v_mfma_f32_16x16x32_bf16 v[42:45], v[182:185], v[190:193], v[42:45]
	v_mfma_f32_16x16x32_bf16 v[26:29], v[182:185], v[198:201], 0
	v_mfma_f32_16x16x32_bf16 v[26:29], v[186:189], v[202:205], v[26:29]
	v_mfma_f32_16x16x32_bf16 v[34:37], v[174:177], v[202:205], 0
	v_mfma_f32_16x16x32_bf16 v[34:37], v[170:173], v[198:201], v[34:37]
	v_mfma_f32_16x16x32_bf16 v[18:21], v[170:173], v[206:209], 0
	v_mfma_f32_16x16x32_bf16 v[18:21], v[174:177], v[212:215], v[18:21]
	v_mfma_f32_16x16x32_bf16 v[10:13], v[186:189], v[212:215], 0
	v_mfma_f32_16x16x32_bf16 v[10:13], v[182:185], v[206:209], v[10:13]
	v_mfma_f32_16x16x32_bf16 v[2:5], v[182:185], v[216:219], 0
	v_mfma_f32_16x16x32_bf16 v[2:5], v[186:189], v[220:223], v[2:5]
	v_mfma_f32_16x16x32_bf16 v[6:9], v[174:177], v[220:223], 0
	v_mfma_f32_16x16x32_bf16 v[6:9], v[170:173], v[216:219], v[6:9]
	s_setprio 0
	s_barrier
	s_add_i32 s46, 0, 0x18000
	v_add_u32_e32 v153, s46, v148
	s_add_i32 s47, 0, 0x1c000
	ds_read_b128 v[154:157], v153
	ds_read_b128 v[158:161], v153 offset:1024
	ds_read_b128 v[162:165], v153 offset:2048
	ds_read_b128 v[166:169], v153 offset:3072
	v_add_u32_e32 v153, s47, v148
	ds_read_b128 v[170:173], v153
	ds_read_b128 v[174:177], v153 offset:1024
	ds_read_b128 v[182:185], v153 offset:2048
	ds_read_b128 v[186:189], v153 offset:3072
	s_add_u32 s36, s66, 0x100000
	s_addc_u32 s37, s67, 0
	s_mov_b32 m0, s12
	v_lshl_add_u64 v[230:231], s[36:37], 0, v[130:131]
	ds_read_b128 v[190:193], v152 offset:32768
	ds_read_b128 v[194:197], v152 offset:33792
	ds_read_b128 v[198:201], v152 offset:34816
	ds_read_b128 v[202:205], v152 offset:35840
	ds_read_b128 v[206:209], v152 offset:36864
	ds_read_b128 v[212:215], v152 offset:37888
	ds_read_b128 v[216:219], v152 offset:38912
	ds_read_b128 v[220:223], v152 offset:39936
	global_load_lds_dwordx4 v[230:231], off
	v_lshl_add_u64 v[230:231], s[36:37], 0, v[134:135]
	s_mov_b32 m0, s13
	s_nop 0
	global_load_lds_dwordx4 v[230:231], off
	s_waitcnt vmcnt(8)
	s_waitcnt lgkmcnt(0)
	s_barrier
	s_setprio 1
	s_waitcnt lgkmcnt(0)
	v_mfma_f32_16x16x32_bf16 v[126:129], v[154:157], v[190:193], v[126:129]
	v_mfma_f32_16x16x32_bf16 v[126:129], v[158:161], v[194:197], v[126:129]
	v_mfma_f32_16x16x32_bf16 v[122:125], v[166:169], v[194:197], v[122:125]
	v_mfma_f32_16x16x32_bf16 v[122:125], v[162:165], v[190:193], v[122:125]
	v_mfma_f32_16x16x32_bf16 v[110:113], v[162:165], v[198:201], v[110:113]
	v_mfma_f32_16x16x32_bf16 v[110:113], v[166:169], v[202:205], v[110:113]
	v_mfma_f32_16x16x32_bf16 v[118:121], v[158:161], v[202:205], v[118:121]
	v_mfma_f32_16x16x32_bf16 v[118:121], v[154:157], v[198:201], v[118:121]
	v_mfma_f32_16x16x32_bf16 v[102:105], v[154:157], v[206:209], v[102:105]
	v_mfma_f32_16x16x32_bf16 v[102:105], v[158:161], v[212:215], v[102:105]
	v_mfma_f32_16x16x32_bf16 v[94:97], v[166:169], v[212:215], v[94:97]
	v_mfma_f32_16x16x32_bf16 v[94:97], v[162:165], v[206:209], v[94:97]
	v_mfma_f32_16x16x32_bf16 v[78:81], v[162:165], v[216:219], v[78:81]
	v_mfma_f32_16x16x32_bf16 v[78:81], v[166:169], v[220:223], v[78:81]
	v_mfma_f32_16x16x32_bf16 v[86:89], v[158:161], v[220:223], v[86:89]
	v_mfma_f32_16x16x32_bf16 v[86:89], v[154:157], v[216:219], v[86:89]
	s_setprio 0
	s_setprio 1
	v_mfma_f32_16x16x32_bf16 v[114:117], v[170:173], v[190:193], v[114:117]
	v_mfma_f32_16x16x32_bf16 v[114:117], v[174:177], v[194:197], v[114:117]
	v_mfma_f32_16x16x32_bf16 v[106:109], v[186:189], v[194:197], v[106:109]
	v_mfma_f32_16x16x32_bf16 v[106:109], v[182:185], v[190:193], v[106:109]
	v_mfma_f32_16x16x32_bf16 v[90:93], v[182:185], v[198:201], v[90:93]
	v_mfma_f32_16x16x32_bf16 v[90:93], v[186:189], v[202:205], v[90:93]
	v_mfma_f32_16x16x32_bf16 v[98:101], v[174:177], v[202:205], v[98:101]
	v_mfma_f32_16x16x32_bf16 v[98:101], v[170:173], v[198:201], v[98:101]
	v_mfma_f32_16x16x32_bf16 v[82:85], v[170:173], v[206:209], v[82:85]
	v_mfma_f32_16x16x32_bf16 v[82:85], v[174:177], v[212:215], v[82:85]
	v_mfma_f32_16x16x32_bf16 v[74:77], v[186:189], v[212:215], v[74:77]
	v_mfma_f32_16x16x32_bf16 v[74:77], v[182:185], v[206:209], v[74:77]
	v_mfma_f32_16x16x32_bf16 v[66:69], v[182:185], v[216:219], v[66:69]
	v_mfma_f32_16x16x32_bf16 v[66:69], v[186:189], v[220:223], v[66:69]
	v_mfma_f32_16x16x32_bf16 v[70:73], v[174:177], v[220:223], v[70:73]
	v_mfma_f32_16x16x32_bf16 v[70:73], v[170:173], v[216:219], v[70:73]
	s_setprio 0
	s_barrier
; #define PG8_STAGE(bufoff, gbase, voff) do { _Pragma("unroll") for (int _i = 0; _i < 2; ++_i) \
;         __builtin_amdgcn_global_load_lds((const unsigned*)((const char*)(gbase) + (voff)[_i]), (PG8_LAS unsigned*)(lds + (bufoff) + ldsw + _i * 8192), 16, 0, 0); } while (0)
; #define PG8_LDA(dst, b, h) do { _Pragma("unroll") for (int m = 0; m < 4; ++m) _Pragma("unroll") for (int k = 0; k < 2; ++k) dst[m][k] = *(const PG8_LAS bf16x8*)(lds + PG8_SA(b, h) + aoff + m * 2048 + k * 1024); } while (0)
; #define PG8_MMA(ai, bj, At, Bt) do { __builtin_amdgcn_s_setprio(1); _Pragma("unroll") for (int m = 0; m < 4; ++m) _Pragma("unroll") for (int n = 0; n < 2; ++n) _Pragma("unroll") for (int k = 0; k < 2; ++k) \
;         acc[ai][bj][m][n] = mma16(Bt[n][k], At[m][k], acc[ai][bj][m][n]); __builtin_amdgcn_s_setprio(0); } while (0)
; #define PG8_WAIT_V(n) asm volatile("s_waitcnt vmcnt(" #n ")" ::: "memory")
; #define PG8_WAIT_L(n) asm volatile("s_waitcnt lgkmcnt(" #n ")" ::: "memory")
; #define PG8_BAR __builtin_amdgcn_s_barrier()
; #define PG8_SCHED __builtin_amdgcn_sched_barrier(0)
; template <class Epi, class Sched, bool ALIGN_EPI = false, bool SP2 = false>
; __device__ __forceinline__ void gemm_phase(PG8_LAS unsigned char* lds, const Gemm g, const Sched& S, const Epi& E) {
;     ...
;             PG8_LDA(At, 1, 1); PG8_STAGE(PG8_SB(1, 0), b3, voffB); PG8_STAGE(PG8_SB(1, 1), b3 + hstepB, voffB); PG8_STAGE(PG8_SA(1, 0), a3, voffA);
;             PG8_WAIT_V(8); PG8_WAIT_L(0); PG8_BAR; PG8_MMA(1, 0, At, B0); PG8_MMA(1, 1, At, B1); PG8_BAR; PG8_SCHED;
	s_add_i32 s36, s46, s7
	v_lshl_add_u64 v[146:147], v[146:147], 0, s[40:41]
	s_mov_b32 m0, s36
	ds_read_b128 v[190:193], v152 offset:49152
	ds_read_b128 v[194:197], v152 offset:50176
	ds_read_b128 v[198:201], v152 offset:51200
	ds_read_b128 v[202:205], v152 offset:52224
	ds_read_b128 v[206:209], v152 offset:53248
	ds_read_b128 v[212:215], v152 offset:54272
	ds_read_b128 v[216:219], v152 offset:55296
	ds_read_b128 v[220:223], v152 offset:56320
	global_load_lds_dwordx4 v[146:147], off
	s_add_i32 m0, s36, 0x2000
	s_add_u32 s36, s64, 0x100080
	v_lshl_add_u64 v[146:147], v[224:225], 0, s[40:41]
	s_addc_u32 s37, s65, 0
	s_add_i32 s46, s47, s7
	global_load_lds_dwordx4 v[146:147], off
	v_lshl_add_u64 v[146:147], s[36:37], 0, v[132:133]
	s_mov_b32 m0, s46
	s_nop 0
	global_load_lds_dwordx4 v[146:147], off
	v_lshl_add_u64 v[146:147], s[36:37], 0, v[136:137]
	s_add_i32 m0, s46, 0x2000
	s_nop 0
	global_load_lds_dwordx4 v[146:147], off
	v_lshl_add_u64 v[146:147], v[226:227], 0, s[40:41]
	s_mov_b32 m0, s17
	s_nop 0
	global_load_lds_dwordx4 v[146:147], off
	v_lshl_add_u64 v[146:147], v[228:229], 0, s[40:41]
	s_mov_b32 m0, s18
	s_nop 0
	global_load_lds_dwordx4 v[146:147], off
	s_waitcnt vmcnt(8)
	s_waitcnt lgkmcnt(0)
	s_barrier
	s_setprio 1
	s_waitcnt lgkmcnt(0)
	v_mfma_f32_16x16x32_bf16 v[62:65], v[154:157], v[190:193], v[62:65]
	v_mfma_f32_16x16x32_bf16 v[62:65], v[158:161], v[194:197], v[62:65]
	v_mfma_f32_16x16x32_bf16 v[58:61], v[166:169], v[194:197], v[58:61]
	v_mfma_f32_16x16x32_bf16 v[58:61], v[162:165], v[190:193], v[58:61]
	v_mfma_f32_16x16x32_bf16 v[46:49], v[162:165], v[198:201], v[46:49]
	v_mfma_f32_16x16x32_bf16 v[46:49], v[166:169], v[202:205], v[46:49]
	v_mfma_f32_16x16x32_bf16 v[54:57], v[158:161], v[202:205], v[54:57]
	v_mfma_f32_16x16x32_bf16 v[54:57], v[154:157], v[198:201], v[54:57]
	v_mfma_f32_16x16x32_bf16 v[38:41], v[154:157], v[206:209], v[38:41]
	v_mfma_f32_16x16x32_bf16 v[38:41], v[158:161], v[212:215], v[38:41]
	v_mfma_f32_16x16x32_bf16 v[30:33], v[166:169], v[212:215], v[30:33]
	v_mfma_f32_16x16x32_bf16 v[30:33], v[162:165], v[206:209], v[30:33]
	v_mfma_f32_16x16x32_bf16 v[14:17], v[162:165], v[216:219], v[14:17]
	v_mfma_f32_16x16x32_bf16 v[14:17], v[166:169], v[220:223], v[14:17]
	v_mfma_f32_16x16x32_bf16 v[22:25], v[158:161], v[220:223], v[22:25]
	v_mfma_f32_16x16x32_bf16 v[22:25], v[154:157], v[216:219], v[22:25]
	s_setprio 0
	s_setprio 1
	v_mfma_f32_16x16x32_bf16 v[50:53], v[170:173], v[190:193], v[50:53]
	v_mfma_f32_16x16x32_bf16 v[50:53], v[174:177], v[194:197], v[50:53]
	v_mfma_f32_16x16x32_bf16 v[42:45], v[186:189], v[194:197], v[42:45]
	v_mfma_f32_16x16x32_bf16 v[42:45], v[182:185], v[190:193], v[42:45]
	v_mfma_f32_16x16x32_bf16 v[26:29], v[182:185], v[198:201], v[26:29]
	v_mfma_f32_16x16x32_bf16 v[26:29], v[186:189], v[202:205], v[26:29]
	v_mfma_f32_16x16x32_bf16 v[34:37], v[174:177], v[202:205], v[34:37]
	v_mfma_f32_16x16x32_bf16 v[34:37], v[170:173], v[198:201], v[34:37]
	v_mfma_f32_16x16x32_bf16 v[18:21], v[170:173], v[206:209], v[18:21]
	v_mfma_f32_16x16x32_bf16 v[18:21], v[174:177], v[212:215], v[18:21]
	v_mfma_f32_16x16x32_bf16 v[10:13], v[186:189], v[212:215], v[10:13]
	v_mfma_f32_16x16x32_bf16 v[10:13], v[182:185], v[206:209], v[10:13]
	v_mfma_f32_16x16x32_bf16 v[2:5], v[182:185], v[216:219], v[2:5]
	v_mfma_f32_16x16x32_bf16 v[2:5], v[186:189], v[220:223], v[2:5]
	v_mfma_f32_16x16x32_bf16 v[6:9], v[174:177], v[220:223], v[6:9]
	v_mfma_f32_16x16x32_bf16 v[6:9], v[170:173], v[216:219], v[6:9]
	s_setprio 0
	s_barrier
	s_add_i32 s35, s35, 2
	s_add_u32 s0, s0, 0x100
	s_addc_u32 s1, s1, 0
	s_add_u32 s29, s29, 0x100
	s_addc_u32 s33, s33, 0

; #define PG8_STAGE(bufoff, gbase, voff) do { _Pragma("unroll") for (int _i = 0; _i < 2; ++_i) \
;         __builtin_amdgcn_global_load_lds((const unsigned*)((const char*)(gbase) + (voff)[_i]), (PG8_LAS unsigned*)(lds + (bufoff) + ldsw + _i * 8192), 16, 0, 0); } while (0)
; #define PG8_LDA(dst, b, h) do { _Pragma("unroll") for (int m = 0; m < 4; ++m) _Pragma("unroll") for (int k = 0; k < 2; ++k) dst[m][k] = *(const PG8_LAS bf16x8*)(lds + PG8_SA(b, h) + aoff + m * 2048 + k * 1024); } while (0)
; #define PG8_BAR __builtin_amdgcn_s_barrier()
; template <class Epi, class Sched, bool ALIGN_EPI = false, bool SP2 = false>
; __device__ __forceinline__ void gemm_phase(PG8_LAS unsigned char* lds, const Gemm g, const Sched& S, const Epi& E) {
;     ...
;         const bool has_next = S.next(ui + 1, nxt);
;         const char* nA = has_next ? PG8_ABASE(nxt) : cA; const char* nB = has_next ? PG8_BBASE(nxt) : cB;
; #pragma unroll 1
;         for (int t = 0; t < nt; t += 2) {
;             const bool last = (t == nt - 2);
;             const char* a1 = cA + (size_t)(t + 1) * kstep;
;             const char* a2 = last ? nA : cA + (size_t)(t + 2) * kstep; const char* b2 = last ? nB : cB + (size_t)(t + 2) * kstep;
;             const char* a3 = a2 + kstep; const char* b3 = b2 + kstep;
;             if (last && has_next) S.a_ready(nxt);
;             if constexpr (SP2) {
;             PG8_LDB(B0, 0, 0); PG8_LDB(B1, 0, 1); PG8_SCHED; PG8_LDA(At, 0, 0); PG8_STAGE(PG8_SA(1, 1), a1 + hstepA, voffA);
;             PG8_WAIT_V(8); PG8_WAIT_L(0); PG8_BAR; PG8_MMA(0, 0, At, B0); PG8_MMA(0, 1, At, B1); PG8_BAR; PG8_SCHED;
;             PG8_LDA(At, 0, 1); PG8_STAGE(PG8_SB(0, 0), b2, voffB); PG8_STAGE(PG8_SB(0, 1), b2 + hstepB, voffB); PG8_STAGE(PG8_SA(0, 0), a2, voffA);
;             PG8_WAIT_V(8); PG8_WAIT_L(0); PG8_BAR; PG8_MMA(1, 0, At, B0); PG8_MMA(1, 1, At, B1); PG8_BAR; PG8_SCHED;
;             PG8_LDB(B0, 1, 0); PG8_LDB(B1, 1, 1); PG8_SCHED; PG8_LDA(At, 1, 0); PG8_STAGE(PG8_SA(0, 1), a2 + hstepA, voffA);
;             PG8_WAIT_V(8); PG8_WAIT_L(0); PG8_BAR; PG8_MMA(0, 0, At, B0); PG8_MMA(0, 1, At, B1); PG8_BAR; PG8_SCHED;
;             PG8_LDA(At, 1, 1); PG8_STAGE(PG8_SB(1, 0), b3, voffB); PG8_STAGE(PG8_SB(1, 1), b3 + hstepB, voffB); PG8_STAGE(PG8_SA(1, 0), a3, voffA);
;             PG8_WAIT_V(8); PG8_WAIT_L(0); PG8_BAR; PG8_MMA(1, 0, At, B0); PG8_MMA(1, 1, At, B1); PG8_BAR; PG8_SCHED;
.LBB0_840:
	s_ashr_i32 s49, s48, 31
	s_lshl_b64 s[50:51], s[48:49], 20
	s_add_u32 s47, s38, s50
	s_addc_u32 s52, s39, s51
	s_ashr_i32 s50, s46, 30
	s_ashr_i32 s51, s50, 31
	s_lshl_b64 s[50:51], s[50:51], 12
	s_add_u32 s50, s47, s50
	s_addc_u32 s51, s52, s51
	s_and_b64 s[52:53], s[4:5], exec
	s_cselect_b32 s62, s51, s57
	s_cselect_b32 s63, s50, s56
	s_ashr_i32 s47, s46, 31
	s_lshl_b64 s[52:53], s[46:47], 20
	s_add_u32 s52, s96, s52
	s_addc_u32 s53, s97, s53
	s_and_b64 s[60:61], s[4:5], exec
	s_cselect_b32 s64, s53, s59
	s_cselect_b32 s65, s52, s58
	s_add_u32 s56, s56, 0x80080
	s_addc_u32 s57, s57, 0
	s_add_u32 s66, s58, 0x100
	s_addc_u32 s67, s59, 0
	s_mov_b32 s68, -2
	ds_read_b128 v[90:93], v173
	ds_read_b128 v[94:97], v173 offset:1024
	ds_read_b128 v[98:101], v173 offset:2048
	ds_read_b128 v[106:109], v173 offset:3072
	ds_read_b128 v[182:185], v174
	ds_read_b128 v[186:189], v174 offset:1024
	ds_read_b128 v[190:193], v174 offset:2048
	ds_read_b128 v[194:197], v174 offset:3072
	s_add_u32 s58, s56, 0xfff80080
	s_addc_u32 s59, s57, -1
	s_cmp_eq_u32 s68, 28
	s_cselect_b32 s61, s62, s59
	s_cselect_b32 s60, s63, s58
	s_cselect_b32 s59, s64, s67
	s_cselect_b32 s58, s65, s66
	v_lshl_add_u64 v[166:167], s[56:57], 0, v[158:159]
	s_add_i32 m0, s12, 0xc000
	ds_read_b128 v[198:201], v175
	ds_read_b128 v[202:205], v175 offset:1024
	ds_read_b128 v[206:209], v175 offset:2048
	ds_read_b128 v[212:215], v175 offset:3072
	ds_read_b128 v[216:219], v175 offset:4096
	ds_read_b128 v[220:223], v175 offset:5120
	ds_read_b128 v[224:227], v175 offset:6144
	ds_read_b128 v[228:231], v175 offset:7168
	global_load_lds_dwordx4 v[166:167], off
	v_lshl_add_u64 v[166:167], s[56:57], 0, v[160:161]
	s_add_i32 m0, s12, 0xe000
	s_nop 0
	global_load_lds_dwordx4 v[166:167], off
	s_waitcnt vmcnt(8)
	s_waitcnt lgkmcnt(0)
	s_barrier
	s_setprio 1
	s_waitcnt lgkmcnt(0)
	v_mfma_i32_16x16x64_i8 v[142:145], v[90:93], v[198:201], 0
	v_mfma_i32_16x16x64_i8 v[142:145], v[94:97], v[202:205], v[142:145]
	v_mfma_i32_16x16x64_i8 v[138:141], v[106:109], v[202:205], 0
	v_mfma_i32_16x16x64_i8 v[138:141], v[98:101], v[198:201], v[138:141]
	v_mfma_i32_16x16x64_i8 v[122:125], v[98:101], v[206:209], 0
	v_mfma_i32_16x16x64_i8 v[122:125], v[106:109], v[212:215], v[122:125]
	v_mfma_i32_16x16x64_i8 v[126:129], v[94:97], v[212:215], 0
	v_mfma_i32_16x16x64_i8 v[126:129], v[90:93], v[206:209], v[126:129]
	v_mfma_i32_16x16x64_i8 v[110:113], v[90:93], v[216:219], 0
	v_mfma_i32_16x16x64_i8 v[110:113], v[94:97], v[220:223], v[110:113]
	v_mfma_i32_16x16x64_i8 v[102:105], v[106:109], v[220:223], 0
	v_mfma_i32_16x16x64_i8 v[102:105], v[98:101], v[216:219], v[102:105]
	v_mfma_i32_16x16x64_i8 v[74:77], v[98:101], v[224:227], 0
	v_mfma_i32_16x16x64_i8 v[74:77], v[106:109], v[228:231], v[74:77]
	v_mfma_i32_16x16x64_i8 v[78:81], v[94:97], v[228:231], 0
	v_mfma_i32_16x16x64_i8 v[78:81], v[90:93], v[224:227], v[78:81]
	s_setprio 0
	s_setprio 1
	v_mfma_i32_16x16x64_i8 v[134:137], v[182:185], v[198:201], 0
	v_mfma_i32_16x16x64_i8 v[134:137], v[186:189], v[202:205], v[134:137]
	v_mfma_i32_16x16x64_i8 v[130:133], v[194:197], v[202:205], 0
	v_mfma_i32_16x16x64_i8 v[130:133], v[190:193], v[198:201], v[130:133]
	v_mfma_i32_16x16x64_i8 v[114:117], v[190:193], v[206:209], 0
	v_mfma_i32_16x16x64_i8 v[114:117], v[194:197], v[212:215], v[114:117]
	v_mfma_i32_16x16x64_i8 v[118:121], v[186:189], v[212:215], 0
	v_mfma_i32_16x16x64_i8 v[118:121], v[182:185], v[206:209], v[118:121]
	v_mfma_i32_16x16x64_i8 v[86:89], v[182:185], v[216:219], 0
	v_mfma_i32_16x16x64_i8 v[86:89], v[186:189], v[220:223], v[86:89]
	v_mfma_i32_16x16x64_i8 v[82:85], v[194:197], v[220:223], 0
	v_mfma_i32_16x16x64_i8 v[82:85], v[190:193], v[216:219], v[82:85]
	v_mfma_i32_16x16x64_i8 v[66:69], v[190:193], v[224:227], 0
	v_mfma_i32_16x16x64_i8 v[66:69], v[194:197], v[228:231], v[66:69]
	v_mfma_i32_16x16x64_i8 v[70:73], v[186:189], v[228:231], 0
	v_mfma_i32_16x16x64_i8 v[70:73], v[182:185], v[224:227], v[70:73]
	s_setprio 0
	s_barrier
	s_add_i32 s69, s27, s6
	v_lshl_add_u64 v[166:167], s[58:59], 0, v[150:151]
	s_mov_b32 m0, s69
	ds_read_b128 v[198:201], v175 offset:16384
	ds_read_b128 v[202:205], v175 offset:17408
	ds_read_b128 v[206:209], v175 offset:18432
	ds_read_b128 v[212:215], v175 offset:19456
	ds_read_b128 v[216:219], v175 offset:20480
	ds_read_b128 v[220:223], v175 offset:21504
	ds_read_b128 v[224:227], v175 offset:22528
	ds_read_b128 v[228:231], v175 offset:23552
	global_load_lds_dwordx4 v[166:167], off
	s_add_i32 m0, s69, 0x2000
	s_add_u32 s70, s58, 0x80000
	v_lshl_add_u64 v[176:177], s[58:59], 0, v[146:147]
	s_addc_u32 s71, s59, 0
	s_add_i32 s69, s28, s6
	global_load_lds_dwordx4 v[176:177], off
	v_lshl_add_u64 v[232:233], s[70:71], 0, v[150:151]
	s_mov_b32 m0, s69
	v_lshl_add_u64 v[234:235], s[60:61], 0, v[148:149]
	global_load_lds_dwordx4 v[232:233], off
	v_lshl_add_u64 v[232:233], s[70:71], 0, v[146:147]
	s_add_i32 m0, s69, 0x2000
	s_nop 0
	global_load_lds_dwordx4 v[232:233], off
	v_lshl_add_u64 v[232:233], s[60:61], 0, v[152:153]
	s_mov_b32 m0, s12
	s_nop 0
	global_load_lds_dwordx4 v[232:233], off
	s_mov_b32 m0, s13
	s_nop 0
	global_load_lds_dwordx4 v[234:235], off
	s_waitcnt vmcnt(8)
	s_waitcnt lgkmcnt(0)
	s_barrier
; #define PG8_STAGE(bufoff, gbase, voff) do { _Pragma("unroll") for (int _i = 0; _i < 2; ++_i) \
;         __builtin_amdgcn_global_load_lds((const unsigned*)((const char*)(gbase) + (voff)[_i]), (PG8_LAS unsigned*)(lds + (bufoff) + ldsw + _i * 8192), 16, 0, 0); } while (0)
; #define PG8_LDA(dst, b, h) do { _Pragma("unroll") for (int m = 0; m < 4; ++m) _Pragma("unroll") for (int k = 0; k < 2; ++k) dst[m][k] = *(const PG8_LAS bf16x8*)(lds + PG8_SA(b, h) + aoff + m * 2048 + k * 1024); } while (0)
; #define PG8_LDB(dst, b, h) do { _Pragma("unroll") for (int n = 0; n < 2; ++n) _Pragma("unroll") for (int k = 0; k < 2; ++k) dst[n][k] = *(const PG8_LAS bf16x8*)(lds + PG8_SB(b, h) + boff + n * 2048 + k * 1024); } while (0)
; #define PG8_MMA(ai, bj, At, Bt) do { __builtin_amdgcn_s_setprio(1); _Pragma("unroll") for (int m = 0; m < 4; ++m) _Pragma("unroll") for (int n = 0; n < 2; ++n) _Pragma("unroll") for (int k = 0; k < 2; ++k) \
;         acc[ai][bj][m][n] = mma16(Bt[n][k], At[m][k], acc[ai][bj][m][n]); __builtin_amdgcn_s_setprio(0); } while (0)
; #define PG8_WAIT_V(n) asm volatile("s_waitcnt vmcnt(" #n ")" ::: "memory")
; template <class Epi, class Sched, bool ALIGN_EPI = false, bool SP2 = false>
; __device__ __forceinline__ void gemm_phase(PG8_LAS unsigned char* lds, const Gemm g, const Sched& S, const Epi& E) {
;     ...
;             PG8_LDB(B0, 0, 0); PG8_LDB(B1, 0, 1); PG8_SCHED; PG8_LDA(At, 0, 0); PG8_STAGE(PG8_SA(1, 1), a1 + hstepA, voffA);
;             PG8_WAIT_V(8); PG8_WAIT_L(0); PG8_BAR; PG8_MMA(0, 0, At, B0); PG8_MMA(0, 1, At, B1); PG8_BAR; PG8_SCHED;
;             PG8_LDA(At, 0, 1); PG8_STAGE(PG8_SB(0, 0), b2, voffB); PG8_STAGE(PG8_SB(0, 1), b2 + hstepB, voffB); PG8_STAGE(PG8_SA(0, 0), a2, voffA);
;             PG8_WAIT_V(8); PG8_WAIT_L(0); PG8_BAR; PG8_MMA(1, 0, At, B0); PG8_MMA(1, 1, At, B1); PG8_BAR; PG8_SCHED;
;             PG8_LDB(B0, 1, 0); PG8_LDB(B1, 1, 1); PG8_SCHED; PG8_LDA(At, 1, 0); PG8_STAGE(PG8_SA(0, 1), a2 + hstepA, voffA);
;             PG8_WAIT_V(8); PG8_WAIT_L(0); PG8_BAR; PG8_MMA(0, 0, At, B0); PG8_MMA(0, 1, At, B1); PG8_BAR; PG8_SCHED;
;             PG8_LDA(At, 1, 1); PG8_STAGE(PG8_SB(1, 0), b3, voffB); PG8_STAGE(PG8_SB(1, 1), b3 + hstepB, voffB); PG8_STAGE(PG8_SA(1, 0), a3, voffA);
;             PG8_WAIT_V(8); PG8_WAIT_L(0); PG8_BAR; PG8_MMA(1, 0, At, B0); PG8_MMA(1, 1, At, B1); PG8_BAR; PG8_SCHED;
	s_setprio 1
	s_waitcnt lgkmcnt(0)
	v_mfma_i32_16x16x64_i8 v[62:65], v[90:93], v[198:201], 0
	v_mfma_i32_16x16x64_i8 v[62:65], v[94:97], v[202:205], v[62:65]
	v_mfma_i32_16x16x64_i8 v[58:61], v[106:109], v[202:205], 0
	v_mfma_i32_16x16x64_i8 v[58:61], v[98:101], v[198:201], v[58:61]
	v_mfma_i32_16x16x64_i8 v[42:45], v[98:101], v[206:209], 0
	v_mfma_i32_16x16x64_i8 v[42:45], v[106:109], v[212:215], v[42:45]
	v_mfma_i32_16x16x64_i8 v[46:49], v[94:97], v[212:215], 0
	v_mfma_i32_16x16x64_i8 v[46:49], v[90:93], v[206:209], v[46:49]
	v_mfma_i32_16x16x64_i8 v[30:33], v[90:93], v[216:219], 0
	v_mfma_i32_16x16x64_i8 v[30:33], v[94:97], v[220:223], v[30:33]
	v_mfma_i32_16x16x64_i8 v[26:29], v[106:109], v[220:223], 0
	v_mfma_i32_16x16x64_i8 v[26:29], v[98:101], v[216:219], v[26:29]
	v_mfma_i32_16x16x64_i8 v[10:13], v[98:101], v[224:227], 0
	v_mfma_i32_16x16x64_i8 v[10:13], v[106:109], v[228:231], v[10:13]
	v_mfma_i32_16x16x64_i8 v[14:17], v[94:97], v[228:231], 0
	v_mfma_i32_16x16x64_i8 v[14:17], v[90:93], v[224:227], v[14:17]
	s_setprio 0
	s_setprio 1
	v_mfma_i32_16x16x64_i8 v[54:57], v[182:185], v[198:201], 0
	v_mfma_i32_16x16x64_i8 v[54:57], v[186:189], v[202:205], v[54:57]
	v_mfma_i32_16x16x64_i8 v[50:53], v[194:197], v[202:205], 0
	v_mfma_i32_16x16x64_i8 v[50:53], v[190:193], v[198:201], v[50:53]
	v_mfma_i32_16x16x64_i8 v[34:37], v[190:193], v[206:209], 0
	v_mfma_i32_16x16x64_i8 v[34:37], v[194:197], v[212:215], v[34:37]
	v_mfma_i32_16x16x64_i8 v[38:41], v[186:189], v[212:215], 0
	v_mfma_i32_16x16x64_i8 v[38:41], v[182:185], v[206:209], v[38:41]
	v_mfma_i32_16x16x64_i8 v[22:25], v[182:185], v[216:219], 0
	v_mfma_i32_16x16x64_i8 v[22:25], v[186:189], v[220:223], v[22:25]
	v_mfma_i32_16x16x64_i8 v[18:21], v[194:197], v[220:223], 0
	v_mfma_i32_16x16x64_i8 v[18:21], v[190:193], v[216:219], v[18:21]
	v_mfma_i32_16x16x64_i8 v[2:5], v[190:193], v[224:227], 0
	v_mfma_i32_16x16x64_i8 v[2:5], v[194:197], v[228:231], v[2:5]
	v_mfma_i32_16x16x64_i8 v[6:9], v[186:189], v[228:231], 0
	v_mfma_i32_16x16x64_i8 v[6:9], v[182:185], v[224:227], v[6:9]
	s_setprio 0
	s_barrier
	s_add_i32 s69, 0, 0x18000
	s_add_i32 s70, 0, 0x1c000
	v_add_u32_e32 v106, s69, v171
	v_add_u32_e32 v181, s70, v171
	ds_read_b128 v[90:93], v106
	ds_read_b128 v[94:97], v106 offset:1024
	ds_read_b128 v[98:101], v106 offset:2048
	ds_read_b128 v[106:109], v106 offset:3072
	ds_read_b128 v[182:185], v181
	ds_read_b128 v[186:189], v181 offset:1024
	ds_read_b128 v[190:193], v181 offset:2048
	ds_read_b128 v[194:197], v181 offset:3072
	s_add_u32 s60, s60, 0x80000
	s_addc_u32 s61, s61, 0
	s_mov_b32 m0, s16
	v_lshl_add_u64 v[236:237], s[60:61], 0, v[152:153]
	ds_read_b128 v[198:201], v175 offset:32768
	ds_read_b128 v[202:205], v175 offset:33792
	ds_read_b128 v[206:209], v175 offset:34816
	ds_read_b128 v[212:215], v175 offset:35840
	ds_read_b128 v[216:219], v175 offset:36864
	ds_read_b128 v[220:223], v175 offset:37888
	ds_read_b128 v[224:227], v175 offset:38912
	ds_read_b128 v[228:231], v175 offset:39936
	global_load_lds_dwordx4 v[236:237], off
	v_lshl_add_u64 v[236:237], s[60:61], 0, v[148:149]
	s_mov_b32 m0, s17
	s_nop 0
	global_load_lds_dwordx4 v[236:237], off
	s_waitcnt vmcnt(8)
	s_waitcnt lgkmcnt(0)
	s_barrier
	s_setprio 1
	s_waitcnt lgkmcnt(0)
	v_mfma_i32_16x16x64_i8 v[142:145], v[90:93], v[198:201], v[142:145]
	v_mfma_i32_16x16x64_i8 v[142:145], v[94:97], v[202:205], v[142:145]
	v_mfma_i32_16x16x64_i8 v[138:141], v[106:109], v[202:205], v[138:141]
	v_mfma_i32_16x16x64_i8 v[138:141], v[98:101], v[198:201], v[138:141]
	v_mfma_i32_16x16x64_i8 v[122:125], v[98:101], v[206:209], v[122:125]
	v_mfma_i32_16x16x64_i8 v[122:125], v[106:109], v[212:215], v[122:125]
	v_mfma_i32_16x16x64_i8 v[126:129], v[94:97], v[212:215], v[126:129]
	v_mfma_i32_16x16x64_i8 v[126:129], v[90:93], v[206:209], v[126:129]
	v_mfma_i32_16x16x64_i8 v[110:113], v[90:93], v[216:219], v[110:113]
	v_mfma_i32_16x16x64_i8 v[110:113], v[94:97], v[220:223], v[110:113]
	v_mfma_i32_16x16x64_i8 v[102:105], v[106:109], v[220:223], v[102:105]
	v_mfma_i32_16x16x64_i8 v[102:105], v[98:101], v[216:219], v[102:105]
	v_mfma_i32_16x16x64_i8 v[74:77], v[98:101], v[224:227], v[74:77]
	v_mfma_i32_16x16x64_i8 v[74:77], v[106:109], v[228:231], v[74:77]
	v_mfma_i32_16x16x64_i8 v[78:81], v[94:97], v[228:231], v[78:81]
	v_mfma_i32_16x16x64_i8 v[78:81], v[90:93], v[224:227], v[78:81]
	s_setprio 0
	s_setprio 1
	v_mfma_i32_16x16x64_i8 v[134:137], v[182:185], v[198:201], v[134:137]
	v_mfma_i32_16x16x64_i8 v[134:137], v[186:189], v[202:205], v[134:137]
	v_mfma_i32_16x16x64_i8 v[130:133], v[194:197], v[202:205], v[130:133]
	v_mfma_i32_16x16x64_i8 v[130:133], v[190:193], v[198:201], v[130:133]
	v_mfma_i32_16x16x64_i8 v[114:117], v[190:193], v[206:209], v[114:117]
	v_mfma_i32_16x16x64_i8 v[114:117], v[194:197], v[212:215], v[114:117]
	v_mfma_i32_16x16x64_i8 v[118:121], v[186:189], v[212:215], v[118:121]
	v_mfma_i32_16x16x64_i8 v[118:121], v[182:185], v[206:209], v[118:121]
	v_mfma_i32_16x16x64_i8 v[86:89], v[182:185], v[216:219], v[86:89]
	v_mfma_i32_16x16x64_i8 v[86:89], v[186:189], v[220:223], v[86:89]
	v_mfma_i32_16x16x64_i8 v[82:85], v[194:197], v[220:223], v[82:85]
	v_mfma_i32_16x16x64_i8 v[82:85], v[190:193], v[216:219], v[82:85]
	v_mfma_i32_16x16x64_i8 v[66:69], v[190:193], v[224:227], v[66:69]
	v_mfma_i32_16x16x64_i8 v[66:69], v[194:197], v[228:231], v[66:69]
	v_mfma_i32_16x16x64_i8 v[70:73], v[186:189], v[228:231], v[70:73]
	v_mfma_i32_16x16x64_i8 v[70:73], v[182:185], v[224:227], v[70:73]
	s_setprio 0
	s_barrier
; #define PG8_STAGE(bufoff, gbase, voff) do { _Pragma("unroll") for (int _i = 0; _i < 2; ++_i) \
;         __builtin_amdgcn_global_load_lds((const unsigned*)((const char*)(gbase) + (voff)[_i]), (PG8_LAS unsigned*)(lds + (bufoff) + ldsw + _i * 8192), 16, 0, 0); } while (0)
; #define PG8_LDA(dst, b, h) do { _Pragma("unroll") for (int m = 0; m < 4; ++m) _Pragma("unroll") for (int k = 0; k < 2; ++k) dst[m][k] = *(const PG8_LAS bf16x8*)(lds + PG8_SA(b, h) + aoff + m * 2048 + k * 1024); } while (0)
; #define PG8_MMA(ai, bj, At, Bt) do { __builtin_amdgcn_s_setprio(1); _Pragma("unroll") for (int m = 0; m < 4; ++m) _Pragma("unroll") for (int n = 0; n < 2; ++n) _Pragma("unroll") for (int k = 0; k < 2; ++k) \
;         acc[ai][bj][m][n] = mma16(Bt[n][k], At[m][k], acc[ai][bj][m][n]); __builtin_amdgcn_s_setprio(0); } while (0)
; #define PG8_WAIT_V(n) asm volatile("s_waitcnt vmcnt(" #n ")" ::: "memory")
; #define PG8_WAIT_L(n) asm volatile("s_waitcnt lgkmcnt(" #n ")" ::: "memory")
; #define PG8_BAR __builtin_amdgcn_s_barrier()
; #define PG8_SCHED __builtin_amdgcn_sched_barrier(0)
; template <class Epi, class Sched, bool ALIGN_EPI = false, bool SP2 = false>
; __device__ __forceinline__ void gemm_phase(PG8_LAS unsigned char* lds, const Gemm g, const Sched& S, const Epi& E) {
;     ...
;             PG8_LDA(At, 1, 1); PG8_STAGE(PG8_SB(1, 0), b3, voffB); PG8_STAGE(PG8_SB(1, 1), b3 + hstepB, voffB); PG8_STAGE(PG8_SA(1, 0), a3, voffA);
;             PG8_WAIT_V(8); PG8_WAIT_L(0); PG8_BAR; PG8_MMA(1, 0, At, B0); PG8_MMA(1, 1, At, B1); PG8_BAR; PG8_SCHED;
	s_add_i32 s60, s69, s6
	v_lshl_add_u64 v[166:167], v[166:167], 0, s[36:37]
	s_mov_b32 m0, s60
	ds_read_b128 v[198:201], v175 offset:49152
	ds_read_b128 v[202:205], v175 offset:50176
	ds_read_b128 v[206:209], v175 offset:51200
	ds_read_b128 v[212:215], v175 offset:52224
	ds_read_b128 v[216:219], v175 offset:53248
	ds_read_b128 v[220:223], v175 offset:54272
	ds_read_b128 v[224:227], v175 offset:55296
	ds_read_b128 v[228:231], v175 offset:56320
	global_load_lds_dwordx4 v[166:167], off
	s_add_i32 m0, s60, 0x2000
	s_add_u32 s58, s58, 0x80080
	v_lshl_add_u64 v[166:167], v[176:177], 0, s[36:37]
	s_addc_u32 s59, s59, 0
	s_add_i32 s60, s70, s6
	global_load_lds_dwordx4 v[166:167], off
	v_lshl_add_u64 v[166:167], s[58:59], 0, v[150:151]
	s_mov_b32 m0, s60
	s_nop 0
	global_load_lds_dwordx4 v[166:167], off
	v_lshl_add_u64 v[166:167], s[58:59], 0, v[146:147]
	s_add_i32 m0, s60, 0x2000
	s_nop 0
	global_load_lds_dwordx4 v[166:167], off
	v_lshl_add_u64 v[166:167], v[232:233], 0, s[36:37]
	s_mov_b32 m0, s24
	s_nop 0
	global_load_lds_dwordx4 v[166:167], off
	v_lshl_add_u64 v[166:167], v[234:235], 0, s[36:37]
	s_mov_b32 m0, s25
	s_nop 0
	global_load_lds_dwordx4 v[166:167], off
	s_waitcnt vmcnt(8)
	s_waitcnt lgkmcnt(0)
	s_barrier
	s_setprio 1
	s_waitcnt lgkmcnt(0)
	v_mfma_i32_16x16x64_i8 v[62:65], v[90:93], v[198:201], v[62:65]
	v_mfma_i32_16x16x64_i8 v[62:65], v[94:97], v[202:205], v[62:65]
	v_mfma_i32_16x16x64_i8 v[58:61], v[106:109], v[202:205], v[58:61]
	v_mfma_i32_16x16x64_i8 v[58:61], v[98:101], v[198:201], v[58:61]
	v_mfma_i32_16x16x64_i8 v[42:45], v[98:101], v[206:209], v[42:45]
	v_mfma_i32_16x16x64_i8 v[42:45], v[106:109], v[212:215], v[42:45]
	v_mfma_i32_16x16x64_i8 v[46:49], v[94:97], v[212:215], v[46:49]
	v_mfma_i32_16x16x64_i8 v[46:49], v[90:93], v[206:209], v[46:49]
	v_mfma_i32_16x16x64_i8 v[30:33], v[90:93], v[216:219], v[30:33]
	v_mfma_i32_16x16x64_i8 v[30:33], v[94:97], v[220:223], v[30:33]
	v_mfma_i32_16x16x64_i8 v[26:29], v[106:109], v[220:223], v[26:29]
	v_mfma_i32_16x16x64_i8 v[26:29], v[98:101], v[216:219], v[26:29]
	v_mfma_i32_16x16x64_i8 v[10:13], v[98:101], v[224:227], v[10:13]
	v_mfma_i32_16x16x64_i8 v[10:13], v[106:109], v[228:231], v[10:13]
	v_mfma_i32_16x16x64_i8 v[14:17], v[94:97], v[228:231], v[14:17]
	v_mfma_i32_16x16x64_i8 v[14:17], v[90:93], v[224:227], v[14:17]
	s_setprio 0
	s_setprio 1
	v_mfma_i32_16x16x64_i8 v[54:57], v[182:185], v[198:201], v[54:57]
	v_mfma_i32_16x16x64_i8 v[54:57], v[186:189], v[202:205], v[54:57]
	v_mfma_i32_16x16x64_i8 v[50:53], v[194:197], v[202:205], v[50:53]
	v_mfma_i32_16x16x64_i8 v[50:53], v[190:193], v[198:201], v[50:53]
	v_mfma_i32_16x16x64_i8 v[34:37], v[190:193], v[206:209], v[34:37]
	v_mfma_i32_16x16x64_i8 v[34:37], v[194:197], v[212:215], v[34:37]
	v_mfma_i32_16x16x64_i8 v[38:41], v[186:189], v[212:215], v[38:41]
	v_mfma_i32_16x16x64_i8 v[38:41], v[182:185], v[206:209], v[38:41]
	v_mfma_i32_16x16x64_i8 v[22:25], v[182:185], v[216:219], v[22:25]
	v_mfma_i32_16x16x64_i8 v[22:25], v[186:189], v[220:223], v[22:25]
	v_mfma_i32_16x16x64_i8 v[18:21], v[194:197], v[220:223], v[18:21]
	v_mfma_i32_16x16x64_i8 v[18:21], v[190:193], v[216:219], v[18:21]
	v_mfma_i32_16x16x64_i8 v[2:5], v[190:193], v[224:227], v[2:5]
	v_mfma_i32_16x16x64_i8 v[2:5], v[194:197], v[228:231], v[2:5]
	v_mfma_i32_16x16x64_i8 v[6:9], v[186:189], v[228:231], v[6:9]
	v_mfma_i32_16x16x64_i8 v[6:9], v[182:185], v[224:227], v[6:9]
	s_setprio 0
	s_barrier
	s_add_i32 s68, s68, 2
	s_add_u32 s56, s56, 0x100
	s_addc_u32 s57, s57, 0
	s_add_u32 s66, s66, 0x100
	s_addc_u32 s67, s67, 0

; #define PG8_STAGE(bufoff, gbase, voff) do { _Pragma("unroll") for (int _i = 0; _i < 2; ++_i) \
;         __builtin_amdgcn_global_load_lds((const unsigned*)((const char*)(gbase) + (voff)[_i]), (PG8_LAS unsigned*)(lds + (bufoff) + ldsw + _i * 8192), 16, 0, 0); } while (0)
; #define PG8_LDA(dst, b, h) do { _Pragma("unroll") for (int m = 0; m < 4; ++m) _Pragma("unroll") for (int k = 0; k < 2; ++k) dst[m][k] = *(const PG8_LAS bf16x8*)(lds + PG8_SA(b, h) + aoff + m * 2048 + k * 1024); } while (0)
; #define PG8_LDB(dst, b, h) do { _Pragma("unroll") for (int n = 0; n < 2; ++n) _Pragma("unroll") for (int k = 0; k < 2; ++k) dst[n][k] = *(const PG8_LAS bf16x8*)(lds + PG8_SB(b, h) + boff + n * 2048 + k * 1024); } while (0)
; template <class Epi, class Sched, bool ALIGN_EPI = false, bool SP2 = false>
; __device__ __forceinline__ void gemm_phase(PG8_LAS unsigned char* lds, const Gemm g, const Sched& S, const Epi& E) {
;     ...
;         for (int t = 0; t < nt; t += 2) {
;             const bool last = (t == nt - 2);
;             const char* a1 = cA + (size_t)(t + 1) * kstep;
;             const char* a2 = last ? nA : cA + (size_t)(t + 2) * kstep; const char* b2 = last ? nB : cB + (size_t)(t + 2) * kstep;
;             const char* a3 = a2 + kstep; const char* b3 = b2 + kstep;
;             if (last && has_next) S.a_ready(nxt);
;             if constexpr (SP2) {
;             PG8_LDB(B0, 0, 0); PG8_LDB(B1, 0, 1); PG8_SCHED; PG8_LDA(At, 0, 0); PG8_STAGE(PG8_SA(1, 1), a1 + hstepA, voffA);
;             PG8_WAIT_V(8); PG8_WAIT_L(0); PG8_BAR; PG8_MMA(0, 0, At, B0); PG8_MMA(0, 1, At, B1); PG8_BAR; PG8_SCHED;
;             PG8_LDA(At, 0, 1); PG8_STAGE(PG8_SB(0, 0), b2, voffB); PG8_STAGE(PG8_SB(0, 1), b2 + hstepB, voffB); PG8_STAGE(PG8_SA(0, 0), a2, voffA);
;             PG8_WAIT_V(8); PG8_WAIT_L(0); PG8_BAR; PG8_MMA(1, 0, At, B0); PG8_MMA(1, 1, At, B1); PG8_BAR; PG8_SCHED;
;             PG8_LDB(B0, 1, 0); PG8_LDB(B1, 1, 1); PG8_SCHED; PG8_LDA(At, 1, 0); PG8_STAGE(PG8_SA(0, 1), a2 + hstepA, voffA);
;             PG8_WAIT_V(8); PG8_WAIT_L(0); PG8_BAR; PG8_MMA(0, 0, At, B0); PG8_MMA(0, 1, At, B1); PG8_BAR; PG8_SCHED;
;             PG8_LDA(At, 1, 1); PG8_STAGE(PG8_SB(1, 0), b3, voffB); PG8_STAGE(PG8_SB(1, 1), b3 + hstepB, voffB); PG8_STAGE(PG8_SA(1, 0), a3, voffA);
;             PG8_WAIT_V(8); PG8_WAIT_L(0); PG8_BAR; PG8_MMA(1, 0, At, B0); PG8_MMA(1, 1, At, B1); PG8_BAR; PG8_SCHED;
.LBB0_1019:
	s_add_u32 s56, s56, 0x158080
	s_addc_u32 s57, s57, 0
	s_add_u32 s65, s58, 0x100
	s_addc_u32 s66, s59, 0
	s_mov_b32 s67, -2
	ds_read_b128 v[122:125], v172
	ds_read_b128 v[126:129], v172 offset:1024
	ds_read_b128 v[130:133], v172 offset:2048
	ds_read_b128 v[138:141], v172 offset:3072
	ds_read_b128 v[182:185], v173
	ds_read_b128 v[186:189], v173 offset:1024
	ds_read_b128 v[190:193], v173 offset:2048
	ds_read_b128 v[194:197], v173 offset:3072
	s_add_u32 s58, s56, 0xffea8080
	s_addc_u32 s59, s57, -1
	s_cmpk_eq_i32 s67, 0x52
	s_cselect_b32 s61, s1, s59
	s_cselect_b32 s60, s0, s58
	s_cselect_b32 s59, s53, s66
	s_cselect_b32 s58, s52, s65
	v_lshl_add_u64 v[166:167], s[56:57], 0, v[158:159]
	s_add_i32 m0, s9, 0xc000
	ds_read_b128 v[198:201], v174
	ds_read_b128 v[202:205], v174 offset:1024
	ds_read_b128 v[206:209], v174 offset:2048
	ds_read_b128 v[212:215], v174 offset:3072
	ds_read_b128 v[216:219], v174 offset:4096
	ds_read_b128 v[220:223], v174 offset:5120
	ds_read_b128 v[224:227], v174 offset:6144
	ds_read_b128 v[228:231], v174 offset:7168
	global_load_lds_dwordx4 v[166:167], off
	v_lshl_add_u64 v[166:167], s[56:57], 0, v[160:161]
	s_add_i32 m0, s9, 0xe000
	s_nop 0
	global_load_lds_dwordx4 v[166:167], off
	s_waitcnt vmcnt(8)
	s_waitcnt lgkmcnt(0)
	s_barrier
	s_setprio 1
	s_waitcnt lgkmcnt(0)
	v_mfma_i32_16x16x64_i8 v[142:145], v[122:125], v[198:201], 0
	v_mfma_i32_16x16x64_i8 v[142:145], v[126:129], v[202:205], v[142:145]
	v_mfma_i32_16x16x64_i8 v[134:137], v[138:141], v[202:205], 0
	v_mfma_i32_16x16x64_i8 v[134:137], v[130:133], v[198:201], v[134:137]
	v_mfma_i32_16x16x64_i8 v[106:109], v[130:133], v[206:209], 0
	v_mfma_i32_16x16x64_i8 v[106:109], v[138:141], v[212:215], v[106:109]
	v_mfma_i32_16x16x64_i8 v[110:113], v[126:129], v[212:215], 0
	v_mfma_i32_16x16x64_i8 v[110:113], v[122:125], v[206:209], v[110:113]
	v_mfma_i32_16x16x64_i8 v[94:97], v[122:125], v[216:219], 0
	v_mfma_i32_16x16x64_i8 v[94:97], v[126:129], v[220:223], v[94:97]
	v_mfma_i32_16x16x64_i8 v[90:93], v[138:141], v[220:223], 0
	v_mfma_i32_16x16x64_i8 v[90:93], v[130:133], v[216:219], v[90:93]
	v_mfma_i32_16x16x64_i8 v[74:77], v[130:133], v[224:227], 0
	v_mfma_i32_16x16x64_i8 v[74:77], v[138:141], v[228:231], v[74:77]
	v_mfma_i32_16x16x64_i8 v[78:81], v[126:129], v[228:231], 0
	v_mfma_i32_16x16x64_i8 v[78:81], v[122:125], v[224:227], v[78:81]
	s_setprio 0
	s_setprio 1
	v_mfma_i32_16x16x64_i8 v[118:121], v[182:185], v[198:201], 0
	v_mfma_i32_16x16x64_i8 v[118:121], v[186:189], v[202:205], v[118:121]
	v_mfma_i32_16x16x64_i8 v[114:117], v[194:197], v[202:205], 0
	v_mfma_i32_16x16x64_i8 v[114:117], v[190:193], v[198:201], v[114:117]
	v_mfma_i32_16x16x64_i8 v[98:101], v[190:193], v[206:209], 0
	v_mfma_i32_16x16x64_i8 v[98:101], v[194:197], v[212:215], v[98:101]
	v_mfma_i32_16x16x64_i8 v[102:105], v[186:189], v[212:215], 0
	v_mfma_i32_16x16x64_i8 v[102:105], v[182:185], v[206:209], v[102:105]
	v_mfma_i32_16x16x64_i8 v[86:89], v[182:185], v[216:219], 0
	v_mfma_i32_16x16x64_i8 v[86:89], v[186:189], v[220:223], v[86:89]
	v_mfma_i32_16x16x64_i8 v[82:85], v[194:197], v[220:223], 0
	v_mfma_i32_16x16x64_i8 v[82:85], v[190:193], v[216:219], v[82:85]
	v_mfma_i32_16x16x64_i8 v[66:69], v[190:193], v[224:227], 0
	v_mfma_i32_16x16x64_i8 v[66:69], v[194:197], v[228:231], v[66:69]
	v_mfma_i32_16x16x64_i8 v[70:73], v[186:189], v[228:231], 0
	v_mfma_i32_16x16x64_i8 v[70:73], v[182:185], v[224:227], v[70:73]
	s_setprio 0
	s_barrier
	s_add_i32 s68, s29, s7
	v_lshl_add_u64 v[166:167], s[58:59], 0, v[148:149]
	s_mov_b32 m0, s68
	ds_read_b128 v[198:201], v174 offset:16384
	ds_read_b128 v[202:205], v174 offset:17408
	ds_read_b128 v[206:209], v174 offset:18432
	ds_read_b128 v[212:215], v174 offset:19456
	ds_read_b128 v[216:219], v174 offset:20480
	ds_read_b128 v[220:223], v174 offset:21504
	ds_read_b128 v[224:227], v174 offset:22528
	ds_read_b128 v[228:231], v174 offset:23552
	global_load_lds_dwordx4 v[166:167], off
	s_add_i32 m0, s68, 0x2000
	s_add_u32 s68, s58, 0x158000
	v_lshl_add_u64 v[176:177], s[58:59], 0, v[152:153]
	s_addc_u32 s69, s59, 0
	s_add_i32 s70, s33, s7
	global_load_lds_dwordx4 v[176:177], off
	v_lshl_add_u64 v[232:233], s[68:69], 0, v[148:149]
	s_mov_b32 m0, s70
	v_lshl_add_u64 v[234:235], s[60:61], 0, v[150:151]
	global_load_lds_dwordx4 v[232:233], off
	v_lshl_add_u64 v[232:233], s[68:69], 0, v[152:153]
	s_add_i32 m0, s70, 0x2000
	s_nop 0
	global_load_lds_dwordx4 v[232:233], off
	v_lshl_add_u64 v[232:233], s[60:61], 0, v[146:147]
	s_mov_b32 m0, s9
	s_nop 0
	global_load_lds_dwordx4 v[232:233], off
	s_mov_b32 m0, s11
	s_nop 0
	global_load_lds_dwordx4 v[234:235], off
	s_waitcnt vmcnt(8)
	s_waitcnt lgkmcnt(0)
	s_barrier
; #define PG8_STAGE(bufoff, gbase, voff) do { _Pragma("unroll") for (int _i = 0; _i < 2; ++_i) \
;         __builtin_amdgcn_global_load_lds((const unsigned*)((const char*)(gbase) + (voff)[_i]), (PG8_LAS unsigned*)(lds + (bufoff) + ldsw + _i * 8192), 16, 0, 0); } while (0)
; #define PG8_LDA(dst, b, h) do { _Pragma("unroll") for (int m = 0; m < 4; ++m) _Pragma("unroll") for (int k = 0; k < 2; ++k) dst[m][k] = *(const PG8_LAS bf16x8*)(lds + PG8_SA(b, h) + aoff + m * 2048 + k * 1024); } while (0)
; #define PG8_LDB(dst, b, h) do { _Pragma("unroll") for (int n = 0; n < 2; ++n) _Pragma("unroll") for (int k = 0; k < 2; ++k) dst[n][k] = *(const PG8_LAS bf16x8*)(lds + PG8_SB(b, h) + boff + n * 2048 + k * 1024); } while (0)
; #define PG8_MMA(ai, bj, At, Bt) do { __builtin_amdgcn_s_setprio(1); _Pragma("unroll") for (int m = 0; m < 4; ++m) _Pragma("unroll") for (int n = 0; n < 2; ++n) _Pragma("unroll") for (int k = 0; k < 2; ++k) \
;         acc[ai][bj][m][n] = mma16(Bt[n][k], At[m][k], acc[ai][bj][m][n]); __builtin_amdgcn_s_setprio(0); } while (0)
; #define PG8_WAIT_V(n) asm volatile("s_waitcnt vmcnt(" #n ")" ::: "memory")
; template <class Epi, class Sched, bool ALIGN_EPI = false, bool SP2 = false>
; __device__ __forceinline__ void gemm_phase(PG8_LAS unsigned char* lds, const Gemm g, const Sched& S, const Epi& E) {
;     ...
;             PG8_LDB(B0, 0, 0); PG8_LDB(B1, 0, 1); PG8_SCHED; PG8_LDA(At, 0, 0); PG8_STAGE(PG8_SA(1, 1), a1 + hstepA, voffA);
;             PG8_WAIT_V(8); PG8_WAIT_L(0); PG8_BAR; PG8_MMA(0, 0, At, B0); PG8_MMA(0, 1, At, B1); PG8_BAR; PG8_SCHED;
;             PG8_LDA(At, 0, 1); PG8_STAGE(PG8_SB(0, 0), b2, voffB); PG8_STAGE(PG8_SB(0, 1), b2 + hstepB, voffB); PG8_STAGE(PG8_SA(0, 0), a2, voffA);
;             PG8_WAIT_V(8); PG8_WAIT_L(0); PG8_BAR; PG8_MMA(1, 0, At, B0); PG8_MMA(1, 1, At, B1); PG8_BAR; PG8_SCHED;
;             PG8_LDB(B0, 1, 0); PG8_LDB(B1, 1, 1); PG8_SCHED; PG8_LDA(At, 1, 0); PG8_STAGE(PG8_SA(0, 1), a2 + hstepA, voffA);
;             PG8_WAIT_V(8); PG8_WAIT_L(0); PG8_BAR; PG8_MMA(0, 0, At, B0); PG8_MMA(0, 1, At, B1); PG8_BAR; PG8_SCHED;
;             PG8_LDA(At, 1, 1); PG8_STAGE(PG8_SB(1, 0), b3, voffB); PG8_STAGE(PG8_SB(1, 1), b3 + hstepB, voffB); PG8_STAGE(PG8_SA(1, 0), a3, voffA);
;             PG8_WAIT_V(8); PG8_WAIT_L(0); PG8_BAR; PG8_MMA(1, 0, At, B0); PG8_MMA(1, 1, At, B1); PG8_BAR; PG8_SCHED;
	s_setprio 1
	s_waitcnt lgkmcnt(0)
	v_mfma_i32_16x16x64_i8 v[62:65], v[122:125], v[198:201], 0
	v_mfma_i32_16x16x64_i8 v[62:65], v[126:129], v[202:205], v[62:65]
	v_mfma_i32_16x16x64_i8 v[58:61], v[138:141], v[202:205], 0
	v_mfma_i32_16x16x64_i8 v[58:61], v[130:133], v[198:201], v[58:61]
	v_mfma_i32_16x16x64_i8 v[42:45], v[130:133], v[206:209], 0
	v_mfma_i32_16x16x64_i8 v[42:45], v[138:141], v[212:215], v[42:45]
	v_mfma_i32_16x16x64_i8 v[46:49], v[126:129], v[212:215], 0
	v_mfma_i32_16x16x64_i8 v[46:49], v[122:125], v[206:209], v[46:49]
	v_mfma_i32_16x16x64_i8 v[30:33], v[122:125], v[216:219], 0
	v_mfma_i32_16x16x64_i8 v[30:33], v[126:129], v[220:223], v[30:33]
	v_mfma_i32_16x16x64_i8 v[26:29], v[138:141], v[220:223], 0
	v_mfma_i32_16x16x64_i8 v[26:29], v[130:133], v[216:219], v[26:29]
	v_mfma_i32_16x16x64_i8 v[10:13], v[130:133], v[224:227], 0
	v_mfma_i32_16x16x64_i8 v[10:13], v[138:141], v[228:231], v[10:13]
	v_mfma_i32_16x16x64_i8 v[14:17], v[126:129], v[228:231], 0
	v_mfma_i32_16x16x64_i8 v[14:17], v[122:125], v[224:227], v[14:17]
	s_setprio 0
	s_setprio 1
	v_mfma_i32_16x16x64_i8 v[54:57], v[182:185], v[198:201], 0
	v_mfma_i32_16x16x64_i8 v[54:57], v[186:189], v[202:205], v[54:57]
	v_mfma_i32_16x16x64_i8 v[50:53], v[194:197], v[202:205], 0
	v_mfma_i32_16x16x64_i8 v[50:53], v[190:193], v[198:201], v[50:53]
	v_mfma_i32_16x16x64_i8 v[34:37], v[190:193], v[206:209], 0
	v_mfma_i32_16x16x64_i8 v[34:37], v[194:197], v[212:215], v[34:37]
	v_mfma_i32_16x16x64_i8 v[38:41], v[186:189], v[212:215], 0
	v_mfma_i32_16x16x64_i8 v[38:41], v[182:185], v[206:209], v[38:41]
	v_mfma_i32_16x16x64_i8 v[22:25], v[182:185], v[216:219], 0
	v_mfma_i32_16x16x64_i8 v[22:25], v[186:189], v[220:223], v[22:25]
	v_mfma_i32_16x16x64_i8 v[18:21], v[194:197], v[220:223], 0
	v_mfma_i32_16x16x64_i8 v[18:21], v[190:193], v[216:219], v[18:21]
	v_mfma_i32_16x16x64_i8 v[2:5], v[190:193], v[224:227], 0
	v_mfma_i32_16x16x64_i8 v[2:5], v[194:197], v[228:231], v[2:5]
	v_mfma_i32_16x16x64_i8 v[6:9], v[186:189], v[228:231], 0
	v_mfma_i32_16x16x64_i8 v[6:9], v[182:185], v[224:227], v[6:9]
	s_setprio 0
	s_barrier
	s_add_i32 s68, 0, 0x18000
	s_add_i32 s69, 0, 0x1c000
	v_add_u32_e32 v138, s68, v170
	v_add_u32_e32 v175, s69, v170
	ds_read_b128 v[122:125], v138
	ds_read_b128 v[126:129], v138 offset:1024
	ds_read_b128 v[130:133], v138 offset:2048
	ds_read_b128 v[138:141], v138 offset:3072
	ds_read_b128 v[182:185], v175
	ds_read_b128 v[186:189], v175 offset:1024
	ds_read_b128 v[190:193], v175 offset:2048
	ds_read_b128 v[194:197], v175 offset:3072
	s_add_u32 s60, s60, 0x158000
	s_addc_u32 s61, s61, 0
	s_mov_b32 m0, s12
	v_lshl_add_u64 v[236:237], s[60:61], 0, v[146:147]
	ds_read_b128 v[198:201], v174 offset:32768
	ds_read_b128 v[202:205], v174 offset:33792
	ds_read_b128 v[206:209], v174 offset:34816
	ds_read_b128 v[212:215], v174 offset:35840
	ds_read_b128 v[216:219], v174 offset:36864
	ds_read_b128 v[220:223], v174 offset:37888
	ds_read_b128 v[224:227], v174 offset:38912
	ds_read_b128 v[228:231], v174 offset:39936
	global_load_lds_dwordx4 v[236:237], off
	v_lshl_add_u64 v[236:237], s[60:61], 0, v[150:151]
	s_mov_b32 m0, s13
	s_nop 0
	global_load_lds_dwordx4 v[236:237], off
	s_waitcnt vmcnt(8)
	s_waitcnt lgkmcnt(0)
	s_barrier
	s_setprio 1
	s_waitcnt lgkmcnt(0)
	v_mfma_i32_16x16x64_i8 v[142:145], v[122:125], v[198:201], v[142:145]
	v_mfma_i32_16x16x64_i8 v[142:145], v[126:129], v[202:205], v[142:145]
	v_mfma_i32_16x16x64_i8 v[134:137], v[138:141], v[202:205], v[134:137]
	v_mfma_i32_16x16x64_i8 v[134:137], v[130:133], v[198:201], v[134:137]
	v_mfma_i32_16x16x64_i8 v[106:109], v[130:133], v[206:209], v[106:109]
	v_mfma_i32_16x16x64_i8 v[106:109], v[138:141], v[212:215], v[106:109]
	v_mfma_i32_16x16x64_i8 v[110:113], v[126:129], v[212:215], v[110:113]
	v_mfma_i32_16x16x64_i8 v[110:113], v[122:125], v[206:209], v[110:113]
	v_mfma_i32_16x16x64_i8 v[94:97], v[122:125], v[216:219], v[94:97]
	v_mfma_i32_16x16x64_i8 v[94:97], v[126:129], v[220:223], v[94:97]
	v_mfma_i32_16x16x64_i8 v[90:93], v[138:141], v[220:223], v[90:93]
	v_mfma_i32_16x16x64_i8 v[90:93], v[130:133], v[216:219], v[90:93]
	v_mfma_i32_16x16x64_i8 v[74:77], v[130:133], v[224:227], v[74:77]
	v_mfma_i32_16x16x64_i8 v[74:77], v[138:141], v[228:231], v[74:77]
	v_mfma_i32_16x16x64_i8 v[78:81], v[126:129], v[228:231], v[78:81]
	v_mfma_i32_16x16x64_i8 v[78:81], v[122:125], v[224:227], v[78:81]
	s_setprio 0
	s_setprio 1
	v_mfma_i32_16x16x64_i8 v[118:121], v[182:185], v[198:201], v[118:121]
	v_mfma_i32_16x16x64_i8 v[118:121], v[186:189], v[202:205], v[118:121]
	v_mfma_i32_16x16x64_i8 v[114:117], v[194:197], v[202:205], v[114:117]
	v_mfma_i32_16x16x64_i8 v[114:117], v[190:193], v[198:201], v[114:117]
	v_mfma_i32_16x16x64_i8 v[98:101], v[190:193], v[206:209], v[98:101]
	v_mfma_i32_16x16x64_i8 v[98:101], v[194:197], v[212:215], v[98:101]
	v_mfma_i32_16x16x64_i8 v[102:105], v[186:189], v[212:215], v[102:105]
	v_mfma_i32_16x16x64_i8 v[102:105], v[182:185], v[206:209], v[102:105]
	v_mfma_i32_16x16x64_i8 v[86:89], v[182:185], v[216:219], v[86:89]
	v_mfma_i32_16x16x64_i8 v[86:89], v[186:189], v[220:223], v[86:89]
	v_mfma_i32_16x16x64_i8 v[82:85], v[194:197], v[220:223], v[82:85]
	v_mfma_i32_16x16x64_i8 v[82:85], v[190:193], v[216:219], v[82:85]
	v_mfma_i32_16x16x64_i8 v[66:69], v[190:193], v[224:227], v[66:69]
	v_mfma_i32_16x16x64_i8 v[66:69], v[194:197], v[228:231], v[66:69]
	v_mfma_i32_16x16x64_i8 v[70:73], v[186:189], v[228:231], v[70:73]
	v_mfma_i32_16x16x64_i8 v[70:73], v[182:185], v[224:227], v[70:73]
	s_setprio 0
	s_barrier
; #define PG8_STAGE(bufoff, gbase, voff) do { _Pragma("unroll") for (int _i = 0; _i < 2; ++_i) \
;         __builtin_amdgcn_global_load_lds((const unsigned*)((const char*)(gbase) + (voff)[_i]), (PG8_LAS unsigned*)(lds + (bufoff) + ldsw + _i * 8192), 16, 0, 0); } while (0)
; #define PG8_LDA(dst, b, h) do { _Pragma("unroll") for (int m = 0; m < 4; ++m) _Pragma("unroll") for (int k = 0; k < 2; ++k) dst[m][k] = *(const PG8_LAS bf16x8*)(lds + PG8_SA(b, h) + aoff + m * 2048 + k * 1024); } while (0)
; #define PG8_MMA(ai, bj, At, Bt) do { __builtin_amdgcn_s_setprio(1); _Pragma("unroll") for (int m = 0; m < 4; ++m) _Pragma("unroll") for (int n = 0; n < 2; ++n) _Pragma("unroll") for (int k = 0; k < 2; ++k) \
;         acc[ai][bj][m][n] = mma16(Bt[n][k], At[m][k], acc[ai][bj][m][n]); __builtin_amdgcn_s_setprio(0); } while (0)
; #define PG8_WAIT_V(n) asm volatile("s_waitcnt vmcnt(" #n ")" ::: "memory")
; #define PG8_WAIT_L(n) asm volatile("s_waitcnt lgkmcnt(" #n ")" ::: "memory")
; #define PG8_BAR __builtin_amdgcn_s_barrier()
; #define PG8_SCHED __builtin_amdgcn_sched_barrier(0)
; template <class Epi, class Sched, bool ALIGN_EPI = false, bool SP2 = false>
; __device__ __forceinline__ void gemm_phase(PG8_LAS unsigned char* lds, const Gemm g, const Sched& S, const Epi& E) {
;     ...
;             PG8_LDA(At, 1, 1); PG8_STAGE(PG8_SB(1, 0), b3, voffB); PG8_STAGE(PG8_SB(1, 1), b3 + hstepB, voffB); PG8_STAGE(PG8_SA(1, 0), a3, voffA);
;             PG8_WAIT_V(8); PG8_WAIT_L(0); PG8_BAR; PG8_MMA(1, 0, At, B0); PG8_MMA(1, 1, At, B1); PG8_BAR; PG8_SCHED;
	s_add_i32 s60, s68, s7
	v_lshl_add_u64 v[166:167], v[166:167], 0, s[24:25]
	s_mov_b32 m0, s60
	ds_read_b128 v[198:201], v174 offset:49152
	ds_read_b128 v[202:205], v174 offset:50176
	ds_read_b128 v[206:209], v174 offset:51200
	ds_read_b128 v[212:215], v174 offset:52224
	ds_read_b128 v[216:219], v174 offset:53248
	ds_read_b128 v[220:223], v174 offset:54272
	ds_read_b128 v[224:227], v174 offset:55296
	ds_read_b128 v[228:231], v174 offset:56320
	global_load_lds_dwordx4 v[166:167], off
	s_add_i32 m0, s60, 0x2000
	s_add_u32 s58, s58, 0x158080
	v_lshl_add_u64 v[166:167], v[176:177], 0, s[24:25]
	s_addc_u32 s59, s59, 0
	s_add_i32 s60, s69, s7
	global_load_lds_dwordx4 v[166:167], off
	v_lshl_add_u64 v[166:167], s[58:59], 0, v[148:149]
	s_mov_b32 m0, s60
	s_nop 0
	global_load_lds_dwordx4 v[166:167], off
	v_lshl_add_u64 v[166:167], s[58:59], 0, v[152:153]
	s_add_i32 m0, s60, 0x2000
	s_nop 0
	global_load_lds_dwordx4 v[166:167], off
	v_lshl_add_u64 v[166:167], v[232:233], 0, s[24:25]
	s_mov_b32 m0, s26
	s_nop 0
	global_load_lds_dwordx4 v[166:167], off
	v_lshl_add_u64 v[166:167], v[234:235], 0, s[24:25]
	s_mov_b32 m0, s27
	s_nop 0
	global_load_lds_dwordx4 v[166:167], off
	s_waitcnt vmcnt(8)
	s_waitcnt lgkmcnt(0)
	s_barrier
	s_setprio 1
	s_waitcnt lgkmcnt(0)
	v_mfma_i32_16x16x64_i8 v[62:65], v[122:125], v[198:201], v[62:65]
	v_mfma_i32_16x16x64_i8 v[62:65], v[126:129], v[202:205], v[62:65]
	v_mfma_i32_16x16x64_i8 v[58:61], v[138:141], v[202:205], v[58:61]
	v_mfma_i32_16x16x64_i8 v[58:61], v[130:133], v[198:201], v[58:61]
	v_mfma_i32_16x16x64_i8 v[42:45], v[130:133], v[206:209], v[42:45]
	v_mfma_i32_16x16x64_i8 v[42:45], v[138:141], v[212:215], v[42:45]
	v_mfma_i32_16x16x64_i8 v[46:49], v[126:129], v[212:215], v[46:49]
	v_mfma_i32_16x16x64_i8 v[46:49], v[122:125], v[206:209], v[46:49]
	v_mfma_i32_16x16x64_i8 v[30:33], v[122:125], v[216:219], v[30:33]
	v_mfma_i32_16x16x64_i8 v[30:33], v[126:129], v[220:223], v[30:33]
	v_mfma_i32_16x16x64_i8 v[26:29], v[138:141], v[220:223], v[26:29]
	v_mfma_i32_16x16x64_i8 v[26:29], v[130:133], v[216:219], v[26:29]
	v_mfma_i32_16x16x64_i8 v[10:13], v[130:133], v[224:227], v[10:13]
	v_mfma_i32_16x16x64_i8 v[10:13], v[138:141], v[228:231], v[10:13]
	v_mfma_i32_16x16x64_i8 v[14:17], v[126:129], v[228:231], v[14:17]
	v_mfma_i32_16x16x64_i8 v[14:17], v[122:125], v[224:227], v[14:17]
	s_setprio 0
	s_setprio 1
	v_mfma_i32_16x16x64_i8 v[54:57], v[182:185], v[198:201], v[54:57]
	v_mfma_i32_16x16x64_i8 v[54:57], v[186:189], v[202:205], v[54:57]
	v_mfma_i32_16x16x64_i8 v[50:53], v[194:197], v[202:205], v[50:53]
	v_mfma_i32_16x16x64_i8 v[50:53], v[190:193], v[198:201], v[50:53]
	v_mfma_i32_16x16x64_i8 v[34:37], v[190:193], v[206:209], v[34:37]
	v_mfma_i32_16x16x64_i8 v[34:37], v[194:197], v[212:215], v[34:37]
	v_mfma_i32_16x16x64_i8 v[38:41], v[186:189], v[212:215], v[38:41]
	v_mfma_i32_16x16x64_i8 v[38:41], v[182:185], v[206:209], v[38:41]
	v_mfma_i32_16x16x64_i8 v[22:25], v[182:185], v[216:219], v[22:25]
	v_mfma_i32_16x16x64_i8 v[22:25], v[186:189], v[220:223], v[22:25]
	v_mfma_i32_16x16x64_i8 v[18:21], v[194:197], v[220:223], v[18:21]
	v_mfma_i32_16x16x64_i8 v[18:21], v[190:193], v[216:219], v[18:21]
	v_mfma_i32_16x16x64_i8 v[2:5], v[190:193], v[224:227], v[2:5]
	v_mfma_i32_16x16x64_i8 v[2:5], v[194:197], v[228:231], v[2:5]
	v_mfma_i32_16x16x64_i8 v[6:9], v[186:189], v[228:231], v[6:9]
	v_mfma_i32_16x16x64_i8 v[6:9], v[182:185], v[224:227], v[6:9]
	s_setprio 0
	s_barrier
	s_add_i32 s67, s67, 2
	s_add_u32 s56, s56, 0x100
	s_addc_u32 s57, s57, 0
	s_add_u32 s65, s65, 0x100
	s_addc_u32 s66, s66, 0

; #define PG8_STAGE(bufoff, gbase, voff) do { _Pragma("unroll") for (int _i = 0; _i < 2; ++_i) \
;         __builtin_amdgcn_global_load_lds((const unsigned*)((const char*)(gbase) + (voff)[_i]), (PG8_LAS unsigned*)(lds + (bufoff) + ldsw + _i * 8192), 16, 0, 0); } while (0)
; #define PG8_LDA(dst, b, h) do { _Pragma("unroll") for (int m = 0; m < 4; ++m) _Pragma("unroll") for (int k = 0; k < 2; ++k) dst[m][k] = *(const PG8_LAS bf16x8*)(lds + PG8_SA(b, h) + aoff + m * 2048 + k * 1024); } while (0)
; #define PG8_LDB(dst, b, h) do { _Pragma("unroll") for (int n = 0; n < 2; ++n) _Pragma("unroll") for (int k = 0; k < 2; ++k) dst[n][k] = *(const PG8_LAS bf16x8*)(lds + PG8_SB(b, h) + boff + n * 2048 + k * 1024); } while (0)
; template <class Epi, class Sched, bool ALIGN_EPI = false, bool SP2 = false>
; __device__ __forceinline__ void gemm_phase(PG8_LAS unsigned char* lds, const Gemm g, const Sched& S, const Epi& E) {
;     ...
;         for (int t = 0; t < nt; t += 2) {
;             const bool last = (t == nt - 2);
;             const char* a1 = cA + (size_t)(t + 1) * kstep;
;             const char* a2 = last ? nA : cA + (size_t)(t + 2) * kstep; const char* b2 = last ? nB : cB + (size_t)(t + 2) * kstep;
;             const char* a3 = a2 + kstep; const char* b3 = b2 + kstep;
;             if (last && has_next) S.a_ready(nxt);
;             if constexpr (SP2) {
;             PG8_LDB(B0, 0, 0); PG8_LDB(B1, 0, 1); PG8_SCHED; PG8_LDA(At, 0, 0); PG8_STAGE(PG8_SA(1, 1), a1 + hstepA, voffA);
;             PG8_WAIT_V(8); PG8_WAIT_L(0); PG8_BAR; PG8_MMA(0, 0, At, B0); PG8_MMA(0, 1, At, B1); PG8_BAR; PG8_SCHED;
;             PG8_LDA(At, 0, 1); PG8_STAGE(PG8_SB(0, 0), b2, voffB); PG8_STAGE(PG8_SB(0, 1), b2 + hstepB, voffB); PG8_STAGE(PG8_SA(0, 0), a2, voffA);
;             PG8_WAIT_V(8); PG8_WAIT_L(0); PG8_BAR; PG8_MMA(1, 0, At, B0); PG8_MMA(1, 1, At, B1); PG8_BAR; PG8_SCHED;
;             PG8_LDB(B0, 1, 0); PG8_LDB(B1, 1, 1); PG8_SCHED; PG8_LDA(At, 1, 0); PG8_STAGE(PG8_SA(0, 1), a2 + hstepA, voffA);
;             PG8_WAIT_V(8); PG8_WAIT_L(0); PG8_BAR; PG8_MMA(0, 0, At, B0); PG8_MMA(0, 1, At, B1); PG8_BAR; PG8_SCHED;
;             PG8_LDA(At, 1, 1); PG8_STAGE(PG8_SB(1, 0), b3, voffB); PG8_STAGE(PG8_SB(1, 1), b3 + hstepB, voffB); PG8_STAGE(PG8_SA(1, 0), a3, voffA);
;             PG8_WAIT_V(8); PG8_WAIT_L(0); PG8_BAR; PG8_MMA(1, 0, At, B0); PG8_MMA(1, 1, At, B1); PG8_BAR; PG8_SCHED;
.LBB0_1036:
	s_add_u32 s50, s50, 0x158080
	s_addc_u32 s51, s51, 0
	s_add_u32 s45, s8, 0x100
	s_addc_u32 s70, s9, 0
	s_mov_b32 s71, -2
	ds_read_b128 v[118:121], v167
	ds_read_b128 v[126:129], v167 offset:1024
	ds_read_b128 v[130:133], v167 offset:2048
	ds_read_b128 v[134:137], v167 offset:3072
	ds_read_b128 v[172:175], v168
	ds_read_b128 v[182:185], v168 offset:1024
	ds_read_b128 v[186:189], v168 offset:2048
	ds_read_b128 v[190:193], v168 offset:3072
	s_add_u32 s52, s50, 0xffea8080
	s_addc_u32 s53, s51, -1
	s_cmpk_eq_i32 s71, 0x52
	s_cselect_b32 s55, s47, s53
	s_cselect_b32 s54, s46, s52
	s_cselect_b32 s53, s9, s70
	s_cselect_b32 s52, s8, s45
	s_mov_b32 m0, s35
	v_lshl_add_u64 v[162:163], s[50:51], 0, v[158:159]
	ds_read_b128 v[194:197], v169
	ds_read_b128 v[198:201], v169 offset:1024
	ds_read_b128 v[202:205], v169 offset:2048
	ds_read_b128 v[206:209], v169 offset:3072
	ds_read_b128 v[212:215], v169 offset:4096
	ds_read_b128 v[216:219], v169 offset:5120
	ds_read_b128 v[220:223], v169 offset:6144
	ds_read_b128 v[224:227], v169 offset:7168
	global_load_lds_dwordx4 v[162:163], off
	v_lshl_add_u64 v[162:163], s[50:51], 0, v[160:161]
	s_mov_b32 m0, s56
	s_nop 0
	global_load_lds_dwordx4 v[162:163], off
	s_waitcnt vmcnt(8)
	s_waitcnt lgkmcnt(0)
	s_barrier
	s_setprio 1
	s_waitcnt lgkmcnt(0)
	v_mfma_i32_16x16x64_i8 v[142:145], v[118:121], v[194:197], 0
	v_mfma_i32_16x16x64_i8 v[142:145], v[126:129], v[198:201], v[142:145]
	v_mfma_i32_16x16x64_i8 v[138:141], v[134:137], v[198:201], 0
	v_mfma_i32_16x16x64_i8 v[138:141], v[130:133], v[194:197], v[138:141]
	v_mfma_i32_16x16x64_i8 v[106:109], v[130:133], v[202:205], 0
	v_mfma_i32_16x16x64_i8 v[106:109], v[134:137], v[206:209], v[106:109]
	v_mfma_i32_16x16x64_i8 v[110:113], v[126:129], v[206:209], 0
	v_mfma_i32_16x16x64_i8 v[110:113], v[118:121], v[202:205], v[110:113]
	v_mfma_i32_16x16x64_i8 v[94:97], v[118:121], v[212:215], 0
	v_mfma_i32_16x16x64_i8 v[94:97], v[126:129], v[216:219], v[94:97]
	v_mfma_i32_16x16x64_i8 v[90:93], v[134:137], v[216:219], 0
	v_mfma_i32_16x16x64_i8 v[90:93], v[130:133], v[212:215], v[90:93]
	v_mfma_i32_16x16x64_i8 v[74:77], v[130:133], v[220:223], 0
	v_mfma_i32_16x16x64_i8 v[74:77], v[134:137], v[224:227], v[74:77]
	v_mfma_i32_16x16x64_i8 v[78:81], v[126:129], v[224:227], 0
	v_mfma_i32_16x16x64_i8 v[78:81], v[118:121], v[220:223], v[78:81]
	s_setprio 0
	s_setprio 1
	v_mfma_i32_16x16x64_i8 v[122:125], v[172:175], v[194:197], 0
	v_mfma_i32_16x16x64_i8 v[122:125], v[182:185], v[198:201], v[122:125]
	v_mfma_i32_16x16x64_i8 v[114:117], v[190:193], v[198:201], 0
	v_mfma_i32_16x16x64_i8 v[114:117], v[186:189], v[194:197], v[114:117]
	v_mfma_i32_16x16x64_i8 v[98:101], v[186:189], v[202:205], 0
	v_mfma_i32_16x16x64_i8 v[98:101], v[190:193], v[206:209], v[98:101]
	v_mfma_i32_16x16x64_i8 v[102:105], v[182:185], v[206:209], 0
	v_mfma_i32_16x16x64_i8 v[102:105], v[172:175], v[202:205], v[102:105]
	v_mfma_i32_16x16x64_i8 v[86:89], v[172:175], v[212:215], 0
	v_mfma_i32_16x16x64_i8 v[86:89], v[182:185], v[216:219], v[86:89]
	v_mfma_i32_16x16x64_i8 v[82:85], v[190:193], v[216:219], 0
	v_mfma_i32_16x16x64_i8 v[82:85], v[186:189], v[212:215], v[82:85]
	v_mfma_i32_16x16x64_i8 v[66:69], v[186:189], v[220:223], 0
	v_mfma_i32_16x16x64_i8 v[66:69], v[190:193], v[224:227], v[66:69]
	v_mfma_i32_16x16x64_i8 v[70:73], v[182:185], v[224:227], 0
	v_mfma_i32_16x16x64_i8 v[70:73], v[172:175], v[220:223], v[70:73]
	s_setprio 0
	s_barrier
	s_mov_b32 m0, s57
	v_lshl_add_u64 v[162:163], s[52:53], 0, v[150:151]
	s_add_u32 s74, s52, 0x158000
	ds_read_b128 v[194:197], v169 offset:16384
	ds_read_b128 v[198:201], v169 offset:17408
	ds_read_b128 v[202:205], v169 offset:18432
	ds_read_b128 v[206:209], v169 offset:19456
	ds_read_b128 v[212:215], v169 offset:20480
	ds_read_b128 v[216:219], v169 offset:21504
	ds_read_b128 v[220:223], v169 offset:22528
	ds_read_b128 v[224:227], v169 offset:23552
	global_load_lds_dwordx4 v[162:163], off
	v_lshl_add_u64 v[176:177], s[52:53], 0, v[146:147]
	s_mov_b32 m0, s58
	s_addc_u32 s75, s53, 0
	global_load_lds_dwordx4 v[176:177], off
	v_lshl_add_u64 v[228:229], s[74:75], 0, v[150:151]
	s_mov_b32 m0, s63
	v_lshl_add_u64 v[230:231], s[54:55], 0, v[148:149]
	global_load_lds_dwordx4 v[228:229], off
	v_lshl_add_u64 v[228:229], s[74:75], 0, v[146:147]
	s_mov_b32 m0, s64
	s_nop 0
	global_load_lds_dwordx4 v[228:229], off
	v_lshl_add_u64 v[228:229], s[54:55], 0, v[152:153]
	s_mov_b32 m0, s5
	s_nop 0
	global_load_lds_dwordx4 v[228:229], off
	s_mov_b32 m0, s6
	s_nop 0
	global_load_lds_dwordx4 v[230:231], off
	s_waitcnt vmcnt(8)
	s_waitcnt lgkmcnt(0)
	s_barrier
	s_setprio 1
	s_waitcnt lgkmcnt(0)
	v_mfma_i32_16x16x64_i8 v[62:65], v[118:121], v[194:197], 0
	v_mfma_i32_16x16x64_i8 v[62:65], v[126:129], v[198:201], v[62:65]
	v_mfma_i32_16x16x64_i8 v[58:61], v[134:137], v[198:201], 0
	v_mfma_i32_16x16x64_i8 v[58:61], v[130:133], v[194:197], v[58:61]
	v_mfma_i32_16x16x64_i8 v[42:45], v[130:133], v[202:205], 0
	v_mfma_i32_16x16x64_i8 v[42:45], v[134:137], v[206:209], v[42:45]
	v_mfma_i32_16x16x64_i8 v[46:49], v[126:129], v[206:209], 0
	v_mfma_i32_16x16x64_i8 v[46:49], v[118:121], v[202:205], v[46:49]
	v_mfma_i32_16x16x64_i8 v[30:33], v[118:121], v[212:215], 0
	v_mfma_i32_16x16x64_i8 v[30:33], v[126:129], v[216:219], v[30:33]
	v_mfma_i32_16x16x64_i8 v[26:29], v[134:137], v[216:219], 0
	v_mfma_i32_16x16x64_i8 v[26:29], v[130:133], v[212:215], v[26:29]
	v_mfma_i32_16x16x64_i8 v[10:13], v[130:133], v[220:223], 0
	v_mfma_i32_16x16x64_i8 v[10:13], v[134:137], v[224:227], v[10:13]
	v_mfma_i32_16x16x64_i8 v[14:17], v[126:129], v[224:227], 0
	v_mfma_i32_16x16x64_i8 v[14:17], v[118:121], v[220:223], v[14:17]
	s_setprio 0
	s_setprio 1
	v_mfma_i32_16x16x64_i8 v[54:57], v[172:175], v[194:197], 0
	v_mfma_i32_16x16x64_i8 v[54:57], v[182:185], v[198:201], v[54:57]
	v_mfma_i32_16x16x64_i8 v[50:53], v[190:193], v[198:201], 0
	v_mfma_i32_16x16x64_i8 v[50:53], v[186:189], v[194:197], v[50:53]
	v_mfma_i32_16x16x64_i8 v[34:37], v[186:189], v[202:205], 0
	v_mfma_i32_16x16x64_i8 v[34:37], v[190:193], v[206:209], v[34:37]
	v_mfma_i32_16x16x64_i8 v[38:41], v[182:185], v[206:209], 0
	v_mfma_i32_16x16x64_i8 v[38:41], v[172:175], v[202:205], v[38:41]
	v_mfma_i32_16x16x64_i8 v[22:25], v[172:175], v[212:215], 0
	v_mfma_i32_16x16x64_i8 v[22:25], v[182:185], v[216:219], v[22:25]
	v_mfma_i32_16x16x64_i8 v[18:21], v[190:193], v[216:219], 0
	v_mfma_i32_16x16x64_i8 v[18:21], v[186:189], v[212:215], v[18:21]
	v_mfma_i32_16x16x64_i8 v[2:5], v[186:189], v[220:223], 0
	v_mfma_i32_16x16x64_i8 v[2:5], v[190:193], v[224:227], v[2:5]
	v_mfma_i32_16x16x64_i8 v[6:9], v[182:185], v[224:227], 0
	v_mfma_i32_16x16x64_i8 v[6:9], v[172:175], v[220:223], v[6:9]
	s_setprio 0
	s_barrier
; #define PG8_STAGE(bufoff, gbase, voff) do { _Pragma("unroll") for (int _i = 0; _i < 2; ++_i) \
;         __builtin_amdgcn_global_load_lds((const unsigned*)((const char*)(gbase) + (voff)[_i]), (PG8_LAS unsigned*)(lds + (bufoff) + ldsw + _i * 8192), 16, 0, 0); } while (0)
; #define PG8_LDA(dst, b, h) do { _Pragma("unroll") for (int m = 0; m < 4; ++m) _Pragma("unroll") for (int k = 0; k < 2; ++k) dst[m][k] = *(const PG8_LAS bf16x8*)(lds + PG8_SA(b, h) + aoff + m * 2048 + k * 1024); } while (0)
; #define PG8_LDB(dst, b, h) do { _Pragma("unroll") for (int n = 0; n < 2; ++n) _Pragma("unroll") for (int k = 0; k < 2; ++k) dst[n][k] = *(const PG8_LAS bf16x8*)(lds + PG8_SB(b, h) + boff + n * 2048 + k * 1024); } while (0)
; #define PG8_MMA(ai, bj, At, Bt) do { __builtin_amdgcn_s_setprio(1); _Pragma("unroll") for (int m = 0; m < 4; ++m) _Pragma("unroll") for (int n = 0; n < 2; ++n) _Pragma("unroll") for (int k = 0; k < 2; ++k) \
;         acc[ai][bj][m][n] = mma16(Bt[n][k], At[m][k], acc[ai][bj][m][n]); __builtin_amdgcn_s_setprio(0); } while (0)
; #define PG8_WAIT_V(n) asm volatile("s_waitcnt vmcnt(" #n ")" ::: "memory")
; template <class Epi, class Sched, bool ALIGN_EPI = false, bool SP2 = false>
; __device__ __forceinline__ void gemm_phase(PG8_LAS unsigned char* lds, const Gemm g, const Sched& S, const Epi& E) {
;     ...
;             PG8_LDB(B0, 0, 0); PG8_LDB(B1, 0, 1); PG8_SCHED; PG8_LDA(At, 0, 0); PG8_STAGE(PG8_SA(1, 1), a1 + hstepA, voffA);
;             PG8_WAIT_V(8); PG8_WAIT_L(0); PG8_BAR; PG8_MMA(0, 0, At, B0); PG8_MMA(0, 1, At, B1); PG8_BAR; PG8_SCHED;
;             PG8_LDA(At, 0, 1); PG8_STAGE(PG8_SB(0, 0), b2, voffB); PG8_STAGE(PG8_SB(0, 1), b2 + hstepB, voffB); PG8_STAGE(PG8_SA(0, 0), a2, voffA);
;             PG8_WAIT_V(8); PG8_WAIT_L(0); PG8_BAR; PG8_MMA(1, 0, At, B0); PG8_MMA(1, 1, At, B1); PG8_BAR; PG8_SCHED;
;             PG8_LDB(B0, 1, 0); PG8_LDB(B1, 1, 1); PG8_SCHED; PG8_LDA(At, 1, 0); PG8_STAGE(PG8_SA(0, 1), a2 + hstepA, voffA);
;             PG8_WAIT_V(8); PG8_WAIT_L(0); PG8_BAR; PG8_MMA(0, 0, At, B0); PG8_MMA(0, 1, At, B1); PG8_BAR; PG8_SCHED;
;             PG8_LDA(At, 1, 1); PG8_STAGE(PG8_SB(1, 0), b3, voffB); PG8_STAGE(PG8_SB(1, 1), b3 + hstepB, voffB); PG8_STAGE(PG8_SA(1, 0), a3, voffA);
;             PG8_WAIT_V(8); PG8_WAIT_L(0); PG8_BAR; PG8_MMA(1, 0, At, B0); PG8_MMA(1, 1, At, B1); PG8_BAR; PG8_SCHED;
	ds_read_b128 v[118:121], v170
	ds_read_b128 v[126:129], v170 offset:1024
	ds_read_b128 v[130:133], v170 offset:2048
	ds_read_b128 v[134:137], v170 offset:3072
	ds_read_b128 v[172:175], v171
	ds_read_b128 v[182:185], v171 offset:1024
	ds_read_b128 v[186:189], v171 offset:2048
	ds_read_b128 v[190:193], v171 offset:3072
	s_add_u32 s54, s54, 0x158000
	s_addc_u32 s55, s55, 0
	s_mov_b32 m0, s7
	v_lshl_add_u64 v[232:233], s[54:55], 0, v[152:153]
	ds_read_b128 v[194:197], v169 offset:32768
	ds_read_b128 v[198:201], v169 offset:33792
	ds_read_b128 v[202:205], v169 offset:34816
	ds_read_b128 v[206:209], v169 offset:35840
	ds_read_b128 v[212:215], v169 offset:36864
	ds_read_b128 v[216:219], v169 offset:37888
	ds_read_b128 v[220:223], v169 offset:38912
	ds_read_b128 v[224:227], v169 offset:39936
	global_load_lds_dwordx4 v[232:233], off
	v_lshl_add_u64 v[232:233], s[54:55], 0, v[148:149]
	s_mov_b32 m0, s11
	s_nop 0
	global_load_lds_dwordx4 v[232:233], off
	s_waitcnt vmcnt(8)
	s_waitcnt lgkmcnt(0)
	s_barrier
	s_setprio 1
	s_waitcnt lgkmcnt(0)
	v_mfma_i32_16x16x64_i8 v[142:145], v[118:121], v[194:197], v[142:145]
	v_mfma_i32_16x16x64_i8 v[142:145], v[126:129], v[198:201], v[142:145]
	v_mfma_i32_16x16x64_i8 v[138:141], v[134:137], v[198:201], v[138:141]
	v_mfma_i32_16x16x64_i8 v[138:141], v[130:133], v[194:197], v[138:141]
	v_mfma_i32_16x16x64_i8 v[106:109], v[130:133], v[202:205], v[106:109]
	v_mfma_i32_16x16x64_i8 v[106:109], v[134:137], v[206:209], v[106:109]
	v_mfma_i32_16x16x64_i8 v[110:113], v[126:129], v[206:209], v[110:113]
	v_mfma_i32_16x16x64_i8 v[110:113], v[118:121], v[202:205], v[110:113]
	v_mfma_i32_16x16x64_i8 v[94:97], v[118:121], v[212:215], v[94:97]
	v_mfma_i32_16x16x64_i8 v[94:97], v[126:129], v[216:219], v[94:97]
	v_mfma_i32_16x16x64_i8 v[90:93], v[134:137], v[216:219], v[90:93]
	v_mfma_i32_16x16x64_i8 v[90:93], v[130:133], v[212:215], v[90:93]
	v_mfma_i32_16x16x64_i8 v[74:77], v[130:133], v[220:223], v[74:77]
	v_mfma_i32_16x16x64_i8 v[74:77], v[134:137], v[224:227], v[74:77]
	v_mfma_i32_16x16x64_i8 v[78:81], v[126:129], v[224:227], v[78:81]
	v_mfma_i32_16x16x64_i8 v[78:81], v[118:121], v[220:223], v[78:81]
	s_setprio 0
	s_setprio 1
	v_mfma_i32_16x16x64_i8 v[122:125], v[172:175], v[194:197], v[122:125]
	v_mfma_i32_16x16x64_i8 v[122:125], v[182:185], v[198:201], v[122:125]
	v_mfma_i32_16x16x64_i8 v[114:117], v[190:193], v[198:201], v[114:117]
	v_mfma_i32_16x16x64_i8 v[114:117], v[186:189], v[194:197], v[114:117]
	v_mfma_i32_16x16x64_i8 v[98:101], v[186:189], v[202:205], v[98:101]
	v_mfma_i32_16x16x64_i8 v[98:101], v[190:193], v[206:209], v[98:101]
	v_mfma_i32_16x16x64_i8 v[102:105], v[182:185], v[206:209], v[102:105]
	v_mfma_i32_16x16x64_i8 v[102:105], v[172:175], v[202:205], v[102:105]
	v_mfma_i32_16x16x64_i8 v[86:89], v[172:175], v[212:215], v[86:89]
	v_mfma_i32_16x16x64_i8 v[86:89], v[182:185], v[216:219], v[86:89]
	v_mfma_i32_16x16x64_i8 v[82:85], v[190:193], v[216:219], v[82:85]
	v_mfma_i32_16x16x64_i8 v[82:85], v[186:189], v[212:215], v[82:85]
	v_mfma_i32_16x16x64_i8 v[66:69], v[186:189], v[220:223], v[66:69]
	v_mfma_i32_16x16x64_i8 v[66:69], v[190:193], v[224:227], v[66:69]
	v_mfma_i32_16x16x64_i8 v[70:73], v[182:185], v[224:227], v[70:73]
	v_mfma_i32_16x16x64_i8 v[70:73], v[172:175], v[220:223], v[70:73]
	s_setprio 0
	s_barrier
	s_mov_b32 m0, s65
	v_lshl_add_u64 v[162:163], v[162:163], 0, s[22:23]
	s_add_u32 s52, s52, 0x158080
	ds_read_b128 v[194:197], v169 offset:49152
	ds_read_b128 v[198:201], v169 offset:50176
	ds_read_b128 v[202:205], v169 offset:51200
	ds_read_b128 v[206:209], v169 offset:52224
	ds_read_b128 v[212:215], v169 offset:53248
	ds_read_b128 v[216:219], v169 offset:54272
	ds_read_b128 v[220:223], v169 offset:55296
	ds_read_b128 v[224:227], v169 offset:56320
	global_load_lds_dwordx4 v[162:163], off
	v_lshl_add_u64 v[162:163], v[176:177], 0, s[22:23]
	s_mov_b32 m0, s66
	s_addc_u32 s53, s53, 0
	global_load_lds_dwordx4 v[162:163], off
	v_lshl_add_u64 v[162:163], s[52:53], 0, v[150:151]
	s_mov_b32 m0, s67
	s_nop 0
	global_load_lds_dwordx4 v[162:163], off
	v_lshl_add_u64 v[162:163], s[52:53], 0, v[146:147]
	s_mov_b32 m0, s68
	s_nop 0
	global_load_lds_dwordx4 v[162:163], off
	v_lshl_add_u64 v[162:163], v[228:229], 0, s[22:23]
	s_mov_b32 m0, s26
	s_nop 0
	global_load_lds_dwordx4 v[162:163], off
	v_lshl_add_u64 v[162:163], v[230:231], 0, s[22:23]
	s_mov_b32 m0, s27
	s_nop 0
	global_load_lds_dwordx4 v[162:163], off
	s_waitcnt vmcnt(8)
	s_waitcnt lgkmcnt(0)
	s_barrier
	s_setprio 1
	s_waitcnt lgkmcnt(0)
	v_mfma_i32_16x16x64_i8 v[62:65], v[118:121], v[194:197], v[62:65]
	v_mfma_i32_16x16x64_i8 v[62:65], v[126:129], v[198:201], v[62:65]
	v_mfma_i32_16x16x64_i8 v[58:61], v[134:137], v[198:201], v[58:61]
	v_mfma_i32_16x16x64_i8 v[58:61], v[130:133], v[194:197], v[58:61]
	v_mfma_i32_16x16x64_i8 v[42:45], v[130:133], v[202:205], v[42:45]
	v_mfma_i32_16x16x64_i8 v[42:45], v[134:137], v[206:209], v[42:45]
	v_mfma_i32_16x16x64_i8 v[46:49], v[126:129], v[206:209], v[46:49]
	v_mfma_i32_16x16x64_i8 v[46:49], v[118:121], v[202:205], v[46:49]
	v_mfma_i32_16x16x64_i8 v[30:33], v[118:121], v[212:215], v[30:33]
	v_mfma_i32_16x16x64_i8 v[30:33], v[126:129], v[216:219], v[30:33]
	v_mfma_i32_16x16x64_i8 v[26:29], v[134:137], v[216:219], v[26:29]
	v_mfma_i32_16x16x64_i8 v[26:29], v[130:133], v[212:215], v[26:29]
	v_mfma_i32_16x16x64_i8 v[10:13], v[130:133], v[220:223], v[10:13]
	v_mfma_i32_16x16x64_i8 v[10:13], v[134:137], v[224:227], v[10:13]
	v_mfma_i32_16x16x64_i8 v[14:17], v[126:129], v[224:227], v[14:17]
	v_mfma_i32_16x16x64_i8 v[14:17], v[118:121], v[220:223], v[14:17]
	s_setprio 0
	s_setprio 1
	v_mfma_i32_16x16x64_i8 v[54:57], v[172:175], v[194:197], v[54:57]
	v_mfma_i32_16x16x64_i8 v[54:57], v[182:185], v[198:201], v[54:57]
	v_mfma_i32_16x16x64_i8 v[50:53], v[190:193], v[198:201], v[50:53]
	v_mfma_i32_16x16x64_i8 v[50:53], v[186:189], v[194:197], v[50:53]
	v_mfma_i32_16x16x64_i8 v[34:37], v[186:189], v[202:205], v[34:37]
	v_mfma_i32_16x16x64_i8 v[34:37], v[190:193], v[206:209], v[34:37]
	v_mfma_i32_16x16x64_i8 v[38:41], v[182:185], v[206:209], v[38:41]
	v_mfma_i32_16x16x64_i8 v[38:41], v[172:175], v[202:205], v[38:41]
	v_mfma_i32_16x16x64_i8 v[22:25], v[172:175], v[212:215], v[22:25]
	v_mfma_i32_16x16x64_i8 v[22:25], v[182:185], v[216:219], v[22:25]
	v_mfma_i32_16x16x64_i8 v[18:21], v[190:193], v[216:219], v[18:21]
	v_mfma_i32_16x16x64_i8 v[18:21], v[186:189], v[212:215], v[18:21]
	v_mfma_i32_16x16x64_i8 v[2:5], v[186:189], v[220:223], v[2:5]
	v_mfma_i32_16x16x64_i8 v[2:5], v[190:193], v[224:227], v[2:5]
	v_mfma_i32_16x16x64_i8 v[6:9], v[182:185], v[224:227], v[6:9]
	v_mfma_i32_16x16x64_i8 v[6:9], v[172:175], v[220:223], v[6:9]
	s_setprio 0
	s_barrier
	s_add_i32 s71, s71, 2
	s_add_u32 s50, s50, 0x100
	s_addc_u32 s51, s51, 0
	s_add_u32 s45, s45, 0x100
	s_addc_u32 s70, s70, 0
